# bulk stores of the hand-written passes and GEMM epilogues made write-through (sc1) so the barrier's L2 write-back has less dirty data
# baseline (speedup 1.0000x reference)
.Ln1_top:
	s_waitcnt vmcnt(16)
	v_mul_f32_e32 v7, v32, v32
	v_fmac_f32_e32 v7, v33, v33
	v_fmac_f32_e32 v7, v34, v34
	v_fmac_f32_e32 v7, v35, v35
	v_fmac_f32_e32 v7, v36, v36
	v_fmac_f32_e32 v7, v37, v37
	v_fmac_f32_e32 v7, v38, v38
	v_fmac_f32_e32 v7, v39, v39
	v_fmac_f32_e32 v7, v40, v40
	v_fmac_f32_e32 v7, v41, v41
	v_fmac_f32_e32 v7, v42, v42
	v_fmac_f32_e32 v7, v43, v43
	v_fmac_f32_e32 v7, v44, v44
	v_fmac_f32_e32 v7, v45, v45
	v_fmac_f32_e32 v7, v46, v46
	v_fmac_f32_e32 v7, v47, v47
	s_nop 1
	v_add_f32_dpp v7, v7, v7 quad_perm:[1,0,3,2] row_mask:0xf bank_mask:0xf
	s_nop 1
	v_add_f32_dpp v7, v7, v7 quad_perm:[2,3,0,1] row_mask:0xf bank_mask:0xf
	s_nop 1
	v_add_f32_dpp v7, v7, v7 row_half_mirror row_mask:0xf bank_mask:0xf
	s_nop 1
	v_add_f32_dpp v7, v7, v7 row_mirror row_mask:0xf bank_mask:0xf
	s_nop 1
	ds_bpermute_b32 v8, v5, v7
	s_waitcnt lgkmcnt(0)
	v_add_f32_e32 v7, v7, v8
	ds_bpermute_b32 v8, v6, v7
	s_waitcnt lgkmcnt(0)
	v_add_f32_e32 v7, v7, v8
	v_mov_b32_e32 v8, 0x358637bd
	v_fmac_f32_e32 v8, 0x3a800000, v7
	v_rsq_f32_e32 v8, v8
	s_nop 0
	v_mul_f32_e32 v32, v32, v8
	v_mul_f32_e32 v33, v33, v8
	v_mul_f32_e32 v34, v34, v8
	v_mul_f32_e32 v35, v35, v8
	v_mul_f32_e32 v36, v36, v8
	v_mul_f32_e32 v37, v37, v8
	v_mul_f32_e32 v38, v38, v8
	v_mul_f32_e32 v39, v39, v8
	v_mul_f32_e32 v40, v40, v8
	v_mul_f32_e32 v41, v41, v8
	v_mul_f32_e32 v42, v42, v8
	v_mul_f32_e32 v43, v43, v8
	v_mul_f32_e32 v44, v44, v8
	v_mul_f32_e32 v45, v45, v8
	v_mul_f32_e32 v46, v46, v8
	v_mul_f32_e32 v47, v47, v8
	v_mul_f32_e32 v32, v32, v16
	v_mul_f32_e32 v33, v33, v17
	v_mul_f32_e32 v34, v34, v18
	v_mul_f32_e32 v35, v35, v19
	v_mul_f32_e32 v36, v36, v20
	v_mul_f32_e32 v37, v37, v21
	v_mul_f32_e32 v38, v38, v22
	v_mul_f32_e32 v39, v39, v23
	v_mul_f32_e32 v40, v40, v24
	v_mul_f32_e32 v41, v41, v25
	v_mul_f32_e32 v42, v42, v26
	v_mul_f32_e32 v43, v43, v27
	v_mul_f32_e32 v44, v44, v28
	v_mul_f32_e32 v45, v45, v29
	v_mul_f32_e32 v46, v46, v30
	v_mul_f32_e32 v47, v47, v31
	v_add_f32_e32 v80, 1.0, v80
	v_add_f32_e32 v81, 1.0, v81
	v_add_f32_e32 v82, 1.0, v82
	v_add_f32_e32 v83, 1.0, v83
	v_add_f32_e32 v84, 1.0, v84
	v_add_f32_e32 v85, 1.0, v85
	v_add_f32_e32 v86, 1.0, v86
	v_add_f32_e32 v87, 1.0, v87
	v_add_f32_e32 v88, 1.0, v88
	v_add_f32_e32 v89, 1.0, v89
	v_add_f32_e32 v90, 1.0, v90
	v_add_f32_e32 v91, 1.0, v91
	v_add_f32_e32 v92, 1.0, v92
	v_add_f32_e32 v93, 1.0, v93
	v_add_f32_e32 v94, 1.0, v94
	v_add_f32_e32 v95, 1.0, v95
	v_fma_f32 v32, v32, v80, v64
	v_fma_f32 v33, v33, v81, v65
	v_fma_f32 v34, v34, v82, v66
	v_fma_f32 v35, v35, v83, v67
	v_fma_f32 v36, v36, v84, v68
	v_fma_f32 v37, v37, v85, v69
	v_fma_f32 v38, v38, v86, v70
	v_fma_f32 v39, v39, v87, v71
	v_fma_f32 v40, v40, v88, v72
	v_fma_f32 v41, v41, v89, v73
	v_fma_f32 v42, v42, v90, v74
	v_fma_f32 v43, v43, v91, v75
	v_fma_f32 v44, v44, v92, v76
	v_fma_f32 v45, v45, v93, v77
	v_fma_f32 v46, v46, v94, v78
	v_fma_f32 v47, v47, v95, v79
	v_cvt_pk_bf16_f32 v32, v32, v33
	v_cvt_pk_bf16_f32 v33, v34, v35
	v_cvt_pk_bf16_f32 v34, v36, v37
	v_cvt_pk_bf16_f32 v35, v38, v39
	v_cvt_pk_bf16_f32 v36, v40, v41
	v_cvt_pk_bf16_f32 v37, v42, v43
	v_cvt_pk_bf16_f32 v38, v44, v45
	v_cvt_pk_bf16_f32 v39, v46, v47
	s_nop 0
	global_store_dwordx2 v9, v[32:33], s[50:51] sc1
	global_store_dwordx2 v9, v[34:35], s[50:51] offset:512 sc1
	global_store_dwordx2 v9, v[36:37], s[50:51] offset:1024 sc1
	global_store_dwordx2 v9, v[38:39], s[50:51] offset:1536 sc1
	s_add_i32 s28, s27, 2
	s_cmp_lt_u32 s28, s26
	s_cselect_b32 s28, s28, 0
	s_cmp_ge_u32 s28, s23
	s_addc_u32 s44, s28, 0
	s_cmp_ge_u32 s44, s25
	s_addc_u32 s44, s44, 0
	s_lshl_b32 s44, s44, 11
	s_add_i32 s44, s44, s19
	s_mul_hi_u32 s46, s44, 0x38e38e39
	s_lshr_b32 s46, s46, 9
	s_mul_i32 s16, s46, 0x900
	s_sub_u32 s16, s44, s16
	s_cmp_lt_u32 s16, 0x100
	s_cbranch_scc1 .Ln1_3_ctx
	s_lshl_b32 s17, s46, 11
	s_add_i32 s17, s17, s16
	s_add_i32 s17, s17, 0xffffff00
	s_lshl_b32 s17, s17, 12
	s_add_u32 s30, s66, s17
	s_addc_u32 s31, s67, 0
	s_add_i32 s46, s46, s65
	s_branch .Ln1_3_ptr

.Ln1_3_ptr:
	s_mul_i32 s46, s46, 0x6000
	s_add_u32 s36, s96, 0x1be04000
	s_addc_u32 s37, s97, 0
	s_add_u32 s36, s36, s46
	s_addc_u32 s37, s37, 0
	s_add_u32 s38, s36, 0x1000
	s_addc_u32 s39, s37, 0
	s_lshl_b32 s17, s44, 11
	s_add_u32 s50, s6, s17
	s_addc_u32 s51, s7, 0
	global_load_dwordx4 v[32:35], v4, s[30:31]
	global_load_dwordx4 v[36:39], v4, s[30:31] offset:1024
	global_load_dwordx4 v[40:43], v4, s[30:31] offset:2048
	global_load_dwordx4 v[44:47], v4, s[30:31] offset:3072
	global_load_dwordx4 v[64:67], v4, s[36:37]
	global_load_dwordx4 v[68:71], v4, s[36:37] offset:1024
	global_load_dwordx4 v[72:75], v4, s[36:37] offset:2048
	global_load_dwordx4 v[76:79], v4, s[36:37] offset:3072
	global_load_dwordx4 v[80:83], v4, s[38:39]
	global_load_dwordx4 v[84:87], v4, s[38:39] offset:1024
	global_load_dwordx4 v[88:91], v4, s[38:39] offset:2048
	global_load_dwordx4 v[92:95], v4, s[38:39] offset:3072
	s_waitcnt vmcnt(16)
	v_mul_f32_e32 v7, v48, v48
	v_fmac_f32_e32 v7, v49, v49
	v_fmac_f32_e32 v7, v50, v50
	v_fmac_f32_e32 v7, v51, v51
	v_fmac_f32_e32 v7, v52, v52
	v_fmac_f32_e32 v7, v53, v53
	v_fmac_f32_e32 v7, v54, v54
	v_fmac_f32_e32 v7, v55, v55
	v_fmac_f32_e32 v7, v56, v56
	v_fmac_f32_e32 v7, v57, v57
	v_fmac_f32_e32 v7, v58, v58
	v_fmac_f32_e32 v7, v59, v59
	v_fmac_f32_e32 v7, v60, v60
	v_fmac_f32_e32 v7, v61, v61
	v_fmac_f32_e32 v7, v62, v62
	v_fmac_f32_e32 v7, v63, v63
	s_nop 1
	v_add_f32_dpp v7, v7, v7 quad_perm:[1,0,3,2] row_mask:0xf bank_mask:0xf
	s_nop 1
	v_add_f32_dpp v7, v7, v7 quad_perm:[2,3,0,1] row_mask:0xf bank_mask:0xf
	s_nop 1
	v_add_f32_dpp v7, v7, v7 row_half_mirror row_mask:0xf bank_mask:0xf
	s_nop 1
	v_add_f32_dpp v7, v7, v7 row_mirror row_mask:0xf bank_mask:0xf
	s_nop 1
	ds_bpermute_b32 v8, v5, v7
	s_waitcnt lgkmcnt(0)
	v_add_f32_e32 v7, v7, v8
	ds_bpermute_b32 v8, v6, v7
	s_waitcnt lgkmcnt(0)
	v_add_f32_e32 v7, v7, v8
	v_mov_b32_e32 v8, 0x358637bd
	v_fmac_f32_e32 v8, 0x3a800000, v7
	v_rsq_f32_e32 v8, v8
	s_nop 0
	v_mul_f32_e32 v48, v48, v8
	v_mul_f32_e32 v49, v49, v8
	v_mul_f32_e32 v50, v50, v8
	v_mul_f32_e32 v51, v51, v8
	v_mul_f32_e32 v52, v52, v8
	v_mul_f32_e32 v53, v53, v8
	v_mul_f32_e32 v54, v54, v8
	v_mul_f32_e32 v55, v55, v8
	v_mul_f32_e32 v56, v56, v8
	v_mul_f32_e32 v57, v57, v8
	v_mul_f32_e32 v58, v58, v8
	v_mul_f32_e32 v59, v59, v8
	v_mul_f32_e32 v60, v60, v8
	v_mul_f32_e32 v61, v61, v8
	v_mul_f32_e32 v62, v62, v8
	v_mul_f32_e32 v63, v63, v8
	v_mul_f32_e32 v48, v48, v16
	v_mul_f32_e32 v49, v49, v17
	v_mul_f32_e32 v50, v50, v18
	v_mul_f32_e32 v51, v51, v19
	v_mul_f32_e32 v52, v52, v20
	v_mul_f32_e32 v53, v53, v21
	v_mul_f32_e32 v54, v54, v22
	v_mul_f32_e32 v55, v55, v23
	v_mul_f32_e32 v56, v56, v24
	v_mul_f32_e32 v57, v57, v25
	v_mul_f32_e32 v58, v58, v26
	v_mul_f32_e32 v59, v59, v27
	v_mul_f32_e32 v60, v60, v28
	v_mul_f32_e32 v61, v61, v29
	v_mul_f32_e32 v62, v62, v30
	v_mul_f32_e32 v63, v63, v31
	v_add_f32_e32 v112, 1.0, v112
	v_add_f32_e32 v113, 1.0, v113
	v_add_f32_e32 v114, 1.0, v114
	v_add_f32_e32 v115, 1.0, v115
	v_add_f32_e32 v116, 1.0, v116
	v_add_f32_e32 v117, 1.0, v117
	v_add_f32_e32 v118, 1.0, v118
	v_add_f32_e32 v119, 1.0, v119
	v_add_f32_e32 v120, 1.0, v120
	v_add_f32_e32 v121, 1.0, v121
	v_add_f32_e32 v122, 1.0, v122
	v_add_f32_e32 v123, 1.0, v123
	v_add_f32_e32 v124, 1.0, v124
	v_add_f32_e32 v125, 1.0, v125
	v_add_f32_e32 v126, 1.0, v126
	v_add_f32_e32 v127, 1.0, v127
	v_fma_f32 v48, v48, v112, v96
	v_fma_f32 v49, v49, v113, v97
	v_fma_f32 v50, v50, v114, v98
	v_fma_f32 v51, v51, v115, v99
	v_fma_f32 v52, v52, v116, v100
	v_fma_f32 v53, v53, v117, v101
	v_fma_f32 v54, v54, v118, v102
	v_fma_f32 v55, v55, v119, v103
	v_fma_f32 v56, v56, v120, v104
	v_fma_f32 v57, v57, v121, v105
	v_fma_f32 v58, v58, v122, v106
	v_fma_f32 v59, v59, v123, v107
	v_fma_f32 v60, v60, v124, v108
	v_fma_f32 v61, v61, v125, v109
	v_fma_f32 v62, v62, v126, v110
	v_fma_f32 v63, v63, v127, v111
	v_cvt_pk_bf16_f32 v48, v48, v49
	v_cvt_pk_bf16_f32 v49, v50, v51
	v_cvt_pk_bf16_f32 v50, v52, v53
	v_cvt_pk_bf16_f32 v51, v54, v55
	v_cvt_pk_bf16_f32 v52, v56, v57
	v_cvt_pk_bf16_f32 v53, v58, v59
	v_cvt_pk_bf16_f32 v54, v60, v61
	v_cvt_pk_bf16_f32 v55, v62, v63
	s_nop 0
	global_store_dwordx2 v9, v[48:49], s[56:57] sc1
	global_store_dwordx2 v9, v[50:51], s[56:57] offset:512 sc1
	global_store_dwordx2 v9, v[52:53], s[56:57] offset:1024 sc1
	global_store_dwordx2 v9, v[54:55], s[56:57] offset:1536 sc1
	s_add_i32 s28, s27, 3
	s_cmp_lt_u32 s28, s26
	s_cselect_b32 s28, s28, 0
	s_cmp_ge_u32 s28, s23
	s_addc_u32 s44, s28, 0
	s_cmp_ge_u32 s44, s25
	s_addc_u32 s44, s44, 0
	s_lshl_b32 s44, s44, 11
	s_add_i32 s44, s44, s19
	s_mul_hi_u32 s46, s44, 0x38e38e39
	s_lshr_b32 s46, s46, 9
	s_mul_i32 s16, s46, 0x900
	s_sub_u32 s16, s44, s16
	s_cmp_lt_u32 s16, 0x100
	s_cbranch_scc1 .Ln1_4_ctx
	s_lshl_b32 s17, s46, 11
	s_add_i32 s17, s17, s16
	s_add_i32 s17, s17, 0xffffff00
	s_lshl_b32 s17, s17, 12
	s_add_u32 s30, s66, s17
	s_addc_u32 s31, s67, 0
	s_add_i32 s46, s46, s65
	s_branch .Ln1_4_ptr

.Left_go:
	s_add_u32 s16, s96, s16
	s_addc_u32 s17, s97, 0
	v_lshrrev_b32_e32 v129, 4, v218
	v_and_b32_e32 v130, 15, v218
	v_mul_u32_u24_e32 v131, 272, v129
	v_mul_lo_u32 v132, v129, s38
	v_lshl_add_u32 v131, v130, 4, v131
	v_lshl_add_u32 v132, v130, 4, v132
	s_waitcnt lgkmcnt(0)
	s_barrier
	ds_read_b128 v[0:3], v131 offset:0
	ds_read_b128 v[4:7], v131 offset:4352
	ds_read_b128 v[8:11], v131 offset:8704
	ds_read_b128 v[12:15], v131 offset:13056
	ds_read_b128 v[16:19], v131 offset:17408
	ds_read_b128 v[20:23], v131 offset:21760
	ds_read_b128 v[24:27], v131 offset:26112
	ds_read_b128 v[28:31], v131 offset:30464
	ds_read_b128 v[32:35], v131 offset:34816
	ds_read_b128 v[36:39], v131 offset:39168
	ds_read_b128 v[40:43], v131 offset:43520
	ds_read_b128 v[44:47], v131 offset:47872
	ds_read_b128 v[48:51], v131 offset:52224
	ds_read_b128 v[52:55], v131 offset:56576
	ds_read_b128 v[56:59], v131 offset:60928
	ds_read_b128 v[60:63], v131 offset:65280
	s_waitcnt lgkmcnt(15)
	global_store_dwordx4 v132, v[0:3], s[16:17] sc1
	s_add_u32 s16, s16, s39
	s_addc_u32 s17, s17, 0
	s_waitcnt lgkmcnt(14)
	global_store_dwordx4 v132, v[4:7], s[16:17] sc1
	s_add_u32 s16, s16, s39
	s_addc_u32 s17, s17, 0
	s_waitcnt lgkmcnt(13)
	global_store_dwordx4 v132, v[8:11], s[16:17] sc1
	s_add_u32 s16, s16, s39
	s_addc_u32 s17, s17, 0
	s_waitcnt lgkmcnt(12)
	global_store_dwordx4 v132, v[12:15], s[16:17] sc1
	s_add_u32 s16, s16, s39
	s_addc_u32 s17, s17, 0
	s_waitcnt lgkmcnt(11)
	global_store_dwordx4 v132, v[16:19], s[16:17] sc1
	s_add_u32 s16, s16, s39
	s_addc_u32 s17, s17, 0
	s_waitcnt lgkmcnt(10)
	global_store_dwordx4 v132, v[20:23], s[16:17] sc1
	s_add_u32 s16, s16, s39
	s_addc_u32 s17, s17, 0
	s_waitcnt lgkmcnt(9)
	global_store_dwordx4 v132, v[24:27], s[16:17] sc1
	s_add_u32 s16, s16, s39
	s_addc_u32 s17, s17, 0
	s_waitcnt lgkmcnt(8)
	global_store_dwordx4 v132, v[28:31], s[16:17] sc1
	s_add_u32 s16, s16, s39
	s_addc_u32 s17, s17, 0
	s_waitcnt lgkmcnt(7)
	global_store_dwordx4 v132, v[32:35], s[16:17] sc1
	s_add_u32 s16, s16, s39
	s_addc_u32 s17, s17, 0
	s_waitcnt lgkmcnt(6)
	global_store_dwordx4 v132, v[36:39], s[16:17] sc1
	s_add_u32 s16, s16, s39
	s_addc_u32 s17, s17, 0
	s_waitcnt lgkmcnt(5)
	global_store_dwordx4 v132, v[40:43], s[16:17] sc1
	s_add_u32 s16, s16, s39
	s_addc_u32 s17, s17, 0
	s_waitcnt lgkmcnt(4)
	global_store_dwordx4 v132, v[44:47], s[16:17] sc1
	s_add_u32 s16, s16, s39
	s_addc_u32 s17, s17, 0
	s_waitcnt lgkmcnt(3)
	global_store_dwordx4 v132, v[48:51], s[16:17] sc1
	s_add_u32 s16, s16, s39
	s_addc_u32 s17, s17, 0
	s_waitcnt lgkmcnt(2)
	global_store_dwordx4 v132, v[52:55], s[16:17] sc1
	s_add_u32 s16, s16, s39
	s_addc_u32 s17, s17, 0
	s_waitcnt lgkmcnt(1)
	global_store_dwordx4 v132, v[56:59], s[16:17] sc1
	s_add_u32 s16, s16, s39
	s_addc_u32 s17, s17, 0
	s_waitcnt lgkmcnt(0)
	global_store_dwordx4 v132, v[60:63], s[16:17] sc1
	s_barrier
	s_branch .LBB0_416

.Lgemm_ipn_loop:
	ds_read_b128 v[232:235], v207 offset:40992
	ds_read_b128 v[236:239], v207 offset:43552
	ds_read_b128 v[220:223], v206 offset:32
	ds_read_b128 v[240:243], v206 offset:2592
	ds_read_b128 v[244:247], v206 offset:5152
	ds_read_b128 v[248:251], v206 offset:7712
	s_waitcnt lgkmcnt(9)
	v_mfma_f32_32x32x16_bf16 v[112:127], v[180:183], v[196:199], v[112:127]
	v_mfma_f32_32x32x16_bf16 v[96:111], v[180:183], v[228:231], v[96:111]
	s_waitcnt lgkmcnt(8)
	v_mfma_f32_32x32x16_bf16 v[80:95], v[184:187], v[196:199], v[80:95]
	v_mfma_f32_32x32x16_bf16 v[64:79], v[184:187], v[228:231], v[64:79]
	ds_write_b128 v202, v[152:155] offset:20480
	ds_write_b128 v202, v[156:159] offset:25600
	ds_write_b128 v202, v[160:163] offset:30720
	ds_write_b128 v202, v[164:167] offset:35840
	ds_write_b128 v202, v[168:171] offset:51200
	ds_write_b128 v202, v[176:179] offset:56320
	v_add_u32_e32 v201, s64, v200
	global_load_dwordx4 v[128:131], v201, s[26:27]
	global_load_dwordx4 v[152:155], v201, s[26:27] offset:64
	global_load_dwordx4 v[132:135], v201, s[28:29]
	global_load_dwordx4 v[156:159], v201, s[28:29] offset:64
	global_load_dwordx4 v[136:139], v201, s[30:31]
	global_load_dwordx4 v[160:163], v201, s[30:31] offset:64
	global_load_dwordx4 v[140:143], v201, s[36:37]
	global_load_dwordx4 v[164:167], v201, s[36:37] offset:64
	global_load_dwordx4 v[144:147], v201, s[42:43]
	global_load_dwordx4 v[168:171], v201, s[42:43] offset:64
	global_load_dwordx4 v[148:151], v201, s[48:49]
	global_load_dwordx4 v[176:179], v201, s[48:49] offset:64
	s_add_i32 s64, s64, 0x80
	s_min_u32 s64, s64, 0x780
	s_waitcnt lgkmcnt(13)
	v_mfma_f32_32x32x16_bf16 v[48:63], v[188:191], v[196:199], v[48:63]
	v_mfma_f32_32x32x16_bf16 v[32:47], v[188:191], v[228:231], v[32:47]
	s_waitcnt lgkmcnt(12)
	v_mfma_f32_32x32x16_bf16 v[16:31], v[192:195], v[196:199], v[16:31]
	v_mfma_f32_32x32x16_bf16 v[0:15], v[192:195], v[228:231], v[0:15]
	s_waitcnt lgkmcnt(0)
	s_barrier
	ds_read_b128 v[196:199], v207 offset:51200
	ds_read_b128 v[228:231], v207 offset:53760
	ds_read_b128 v[180:183], v206 offset:20480
	ds_read_b128 v[184:187], v206 offset:23040
	ds_read_b128 v[188:191], v206 offset:25600
	ds_read_b128 v[192:195], v206 offset:28160
	v_mfma_f32_32x32x16_bf16 v[112:127], v[220:223], v[232:235], v[112:127]
	v_mfma_f32_32x32x16_bf16 v[96:111], v[220:223], v[236:239], v[96:111]
	v_mfma_f32_32x32x16_bf16 v[80:95], v[240:243], v[232:235], v[80:95]
	v_mfma_f32_32x32x16_bf16 v[64:79], v[240:243], v[236:239], v[64:79]
	v_mfma_f32_32x32x16_bf16 v[48:63], v[244:247], v[232:235], v[48:63]
	v_mfma_f32_32x32x16_bf16 v[32:47], v[244:247], v[236:239], v[32:47]
	v_mfma_f32_32x32x16_bf16 v[16:31], v[248:251], v[232:235], v[16:31]
	v_mfma_f32_32x32x16_bf16 v[0:15], v[248:251], v[236:239], v[0:15]
	ds_read_b128 v[232:235], v207 offset:51232
	ds_read_b128 v[236:239], v207 offset:53792
	ds_read_b128 v[220:223], v206 offset:20512
	ds_read_b128 v[240:243], v206 offset:23072
	ds_read_b128 v[244:247], v206 offset:25632
	ds_read_b128 v[248:251], v206 offset:28192
	s_waitcnt lgkmcnt(9)
	v_mfma_f32_32x32x16_bf16 v[112:127], v[180:183], v[196:199], v[112:127]
	v_mfma_f32_32x32x16_bf16 v[96:111], v[180:183], v[228:231], v[96:111]
	s_waitcnt lgkmcnt(8)
	v_mfma_f32_32x32x16_bf16 v[80:95], v[184:187], v[196:199], v[80:95]
	v_mfma_f32_32x32x16_bf16 v[64:79], v[184:187], v[228:231], v[64:79]
	s_waitcnt vmcnt(0)
	ds_write_b128 v202, v[128:131] offset:0
	ds_write_b128 v202, v[132:135] offset:5120
	ds_write_b128 v202, v[136:139] offset:10240
	ds_write_b128 v202, v[140:143] offset:15360
	ds_write_b128 v202, v[144:147] offset:40960
	ds_write_b128 v202, v[148:151] offset:46080
	s_waitcnt lgkmcnt(13)
	v_mfma_f32_32x32x16_bf16 v[48:63], v[188:191], v[196:199], v[48:63]
	v_mfma_f32_32x32x16_bf16 v[32:47], v[188:191], v[228:231], v[32:47]
	s_waitcnt lgkmcnt(12)
	v_mfma_f32_32x32x16_bf16 v[16:31], v[192:195], v[196:199], v[16:31]
	v_mfma_f32_32x32x16_bf16 v[0:15], v[192:195], v[228:231], v[0:15]
	s_waitcnt lgkmcnt(0)
	s_barrier
	ds_read_b128 v[196:199], v207 offset:40960
	ds_read_b128 v[228:231], v207 offset:43520
	ds_read_b128 v[180:183], v206 offset:0
	ds_read_b128 v[184:187], v206 offset:2560
	ds_read_b128 v[188:191], v206 offset:5120
	ds_read_b128 v[192:195], v206 offset:7680
	v_mfma_f32_32x32x16_bf16 v[112:127], v[220:223], v[232:235], v[112:127]
	v_mfma_f32_32x32x16_bf16 v[96:111], v[220:223], v[236:239], v[96:111]
	v_mfma_f32_32x32x16_bf16 v[80:95], v[240:243], v[232:235], v[80:95]
	v_mfma_f32_32x32x16_bf16 v[64:79], v[240:243], v[236:239], v[64:79]
	v_mfma_f32_32x32x16_bf16 v[48:63], v[244:247], v[232:235], v[48:63]
	v_mfma_f32_32x32x16_bf16 v[32:47], v[244:247], v[236:239], v[32:47]
	v_mfma_f32_32x32x16_bf16 v[16:31], v[248:251], v[232:235], v[16:31]
	v_mfma_f32_32x32x16_bf16 v[0:15], v[248:251], v[236:239], v[0:15]
	s_add_i32 s65, s65, -1
	s_cmp_lg_u32 s65, 0
	s_cbranch_scc1 .Lgemm_ipn_loop
	s_waitcnt lgkmcnt(0)
	s_waitcnt vmcnt(0)
	v_and_b32_e32 v128, 31, v218
	v_lshrrev_b32_e32 v129, 7, v218
	v_bfe_u32 v130, v218, 5, 1
	v_bfe_u32 v131, v218, 6, 1
	v_lshl_add_u32 v128, v131, 6, v128
	v_mul_u32_u24_e32 v128, 528, v128
	v_lshlrev_b32_e32 v129, 8, v129
	v_lshl_add_u32 v129, v130, 3, v129
	v_add_u32_e32 v128, v128, v129
	s_nop 7
	v_cvt_pk_bf16_f32 v112, v112, v113
	v_cvt_pk_bf16_f32 v113, v114, v115
	v_cvt_pk_bf16_f32 v116, v116, v117
	v_cvt_pk_bf16_f32 v117, v118, v119
	v_cvt_pk_bf16_f32 v120, v120, v121
	v_cvt_pk_bf16_f32 v121, v122, v123
	v_cvt_pk_bf16_f32 v124, v124, v125
	v_cvt_pk_bf16_f32 v125, v126, v127
	ds_write_b64 v128, v[112:113] offset:0
	ds_write_b64 v128, v[116:117] offset:16
	ds_write_b64 v128, v[120:121] offset:32
	ds_write_b64 v128, v[124:125] offset:48
	v_cvt_pk_bf16_f32 v96, v96, v97
	v_cvt_pk_bf16_f32 v97, v98, v99
	v_cvt_pk_bf16_f32 v100, v100, v101
	v_cvt_pk_bf16_f32 v101, v102, v103
	v_cvt_pk_bf16_f32 v104, v104, v105
	v_cvt_pk_bf16_f32 v105, v106, v107
	v_cvt_pk_bf16_f32 v108, v108, v109
	v_cvt_pk_bf16_f32 v109, v110, v111
	ds_write_b64 v128, v[96:97] offset:16896
	ds_write_b64 v128, v[100:101] offset:16912
	ds_write_b64 v128, v[104:105] offset:16928
	ds_write_b64 v128, v[108:109] offset:16944
	v_cvt_pk_bf16_f32 v80, v80, v81
	v_cvt_pk_bf16_f32 v81, v82, v83
	v_cvt_pk_bf16_f32 v84, v84, v85
	v_cvt_pk_bf16_f32 v85, v86, v87
	v_cvt_pk_bf16_f32 v88, v88, v89
	v_cvt_pk_bf16_f32 v89, v90, v91
	v_cvt_pk_bf16_f32 v92, v92, v93
	v_cvt_pk_bf16_f32 v93, v94, v95
	ds_write_b64 v128, v[80:81] offset:64
	ds_write_b64 v128, v[84:85] offset:80
	ds_write_b64 v128, v[88:89] offset:96
	ds_write_b64 v128, v[92:93] offset:112
	v_cvt_pk_bf16_f32 v64, v64, v65
	v_cvt_pk_bf16_f32 v65, v66, v67
	v_cvt_pk_bf16_f32 v68, v68, v69
	v_cvt_pk_bf16_f32 v69, v70, v71
	v_cvt_pk_bf16_f32 v72, v72, v73
	v_cvt_pk_bf16_f32 v73, v74, v75
	v_cvt_pk_bf16_f32 v76, v76, v77
	v_cvt_pk_bf16_f32 v77, v78, v79
	ds_write_b64 v128, v[64:65] offset:16960
	ds_write_b64 v128, v[68:69] offset:16976
	ds_write_b64 v128, v[72:73] offset:16992
	ds_write_b64 v128, v[76:77] offset:17008
	v_cvt_pk_bf16_f32 v48, v48, v49
	v_cvt_pk_bf16_f32 v49, v50, v51
	v_cvt_pk_bf16_f32 v52, v52, v53
	v_cvt_pk_bf16_f32 v53, v54, v55
	v_cvt_pk_bf16_f32 v56, v56, v57
	v_cvt_pk_bf16_f32 v57, v58, v59
	v_cvt_pk_bf16_f32 v60, v60, v61
	v_cvt_pk_bf16_f32 v61, v62, v63
	ds_write_b64 v128, v[48:49] offset:128
	ds_write_b64 v128, v[52:53] offset:144
	ds_write_b64 v128, v[56:57] offset:160
	ds_write_b64 v128, v[60:61] offset:176
	v_cvt_pk_bf16_f32 v32, v32, v33
	v_cvt_pk_bf16_f32 v33, v34, v35
	v_cvt_pk_bf16_f32 v36, v36, v37
	v_cvt_pk_bf16_f32 v37, v38, v39
	v_cvt_pk_bf16_f32 v40, v40, v41
	v_cvt_pk_bf16_f32 v41, v42, v43
	v_cvt_pk_bf16_f32 v44, v44, v45
	v_cvt_pk_bf16_f32 v45, v46, v47
	ds_write_b64 v128, v[32:33] offset:17024
	ds_write_b64 v128, v[36:37] offset:17040
	ds_write_b64 v128, v[40:41] offset:17056
	ds_write_b64 v128, v[44:45] offset:17072
	v_cvt_pk_bf16_f32 v16, v16, v17
	v_cvt_pk_bf16_f32 v17, v18, v19
	v_cvt_pk_bf16_f32 v20, v20, v21
	v_cvt_pk_bf16_f32 v21, v22, v23
	v_cvt_pk_bf16_f32 v24, v24, v25
	v_cvt_pk_bf16_f32 v25, v26, v27
	v_cvt_pk_bf16_f32 v28, v28, v29
	v_cvt_pk_bf16_f32 v29, v30, v31
	ds_write_b64 v128, v[16:17] offset:192
	ds_write_b64 v128, v[20:21] offset:208
	ds_write_b64 v128, v[24:25] offset:224
	ds_write_b64 v128, v[28:29] offset:240
	v_cvt_pk_bf16_f32 v0, v0, v1
	v_cvt_pk_bf16_f32 v1, v2, v3
	v_cvt_pk_bf16_f32 v4, v4, v5
	v_cvt_pk_bf16_f32 v5, v6, v7
	v_cvt_pk_bf16_f32 v8, v8, v9
	v_cvt_pk_bf16_f32 v9, v10, v11
	v_cvt_pk_bf16_f32 v12, v12, v13
	v_cvt_pk_bf16_f32 v13, v14, v15
	ds_write_b64 v128, v[0:1] offset:17088
	ds_write_b64 v128, v[4:5] offset:17104
	ds_write_b64 v128, v[8:9] offset:17120
	ds_write_b64 v128, v[12:13] offset:17136
	s_mul_hi_u32 s36, s73, 0x38e38e39
	s_lshr_b32 s36, s36, 9
	s_mul_i32 s37, s36, 0x900
	s_sub_u32 s37, s73, s37
	s_lshl_b32 s36, s36, 9
	s_add_i32 s36, s36, s72
	s_add_i32 s36, s36, 0xfffff700
	s_mul_i32 s36, s36, 0x900
	s_add_i32 s36, s36, s37
	s_lshl_b32 s16, s36, 1
	s_add_u32 s16, s16, 0x13200000
	s_add_u32 s16, s96, s16
	s_addc_u32 s17, s97, 0
	s_movk_i32 s38, 0x1200
	s_mov_b32 s39, 0x9000
	v_lshrrev_b32_e32 v129, 5, v218
	v_and_b32_e32 v130, 31, v218
	v_mul_u32_u24_e32 v131, 528, v129
	v_mul_lo_u32 v132, v129, s38
	v_lshl_add_u32 v131, v130, 4, v131
	v_lshl_add_u32 v132, v130, 4, v132
	s_waitcnt lgkmcnt(0)
	s_barrier
	ds_read_b128 v[0:3], v131 offset:0
	ds_read_b128 v[4:7], v131 offset:4224
	ds_read_b128 v[8:11], v131 offset:8448
	ds_read_b128 v[12:15], v131 offset:12672
	ds_read_b128 v[16:19], v131 offset:16896
	ds_read_b128 v[20:23], v131 offset:21120
	ds_read_b128 v[24:27], v131 offset:25344
	ds_read_b128 v[28:31], v131 offset:29568
	ds_read_b128 v[32:35], v131 offset:33792
	ds_read_b128 v[36:39], v131 offset:38016
	ds_read_b128 v[40:43], v131 offset:42240
	ds_read_b128 v[44:47], v131 offset:46464
	ds_read_b128 v[48:51], v131 offset:50688
	ds_read_b128 v[52:55], v131 offset:54912
	ds_read_b128 v[56:59], v131 offset:59136
	ds_read_b128 v[60:63], v131 offset:63360
	s_waitcnt lgkmcnt(15)
	global_store_dwordx4 v132, v[0:3], s[16:17] sc1
	s_add_u32 s16, s16, s39
	s_addc_u32 s17, s17, 0
	s_waitcnt lgkmcnt(14)
	global_store_dwordx4 v132, v[4:7], s[16:17] sc1
	s_add_u32 s16, s16, s39
	s_addc_u32 s17, s17, 0
	s_waitcnt lgkmcnt(13)
	global_store_dwordx4 v132, v[8:11], s[16:17] sc1
	s_add_u32 s16, s16, s39
	s_addc_u32 s17, s17, 0
	s_waitcnt lgkmcnt(12)
	global_store_dwordx4 v132, v[12:15], s[16:17] sc1
	s_add_u32 s16, s16, s39
	s_addc_u32 s17, s17, 0
	s_waitcnt lgkmcnt(11)
	global_store_dwordx4 v132, v[16:19], s[16:17] sc1
	s_add_u32 s16, s16, s39
	s_addc_u32 s17, s17, 0
	s_waitcnt lgkmcnt(10)
	global_store_dwordx4 v132, v[20:23], s[16:17] sc1
	s_add_u32 s16, s16, s39
	s_addc_u32 s17, s17, 0
	s_waitcnt lgkmcnt(9)
	global_store_dwordx4 v132, v[24:27], s[16:17] sc1
	s_add_u32 s16, s16, s39
	s_addc_u32 s17, s17, 0
	s_waitcnt lgkmcnt(8)
	global_store_dwordx4 v132, v[28:31], s[16:17] sc1
	s_add_u32 s16, s16, s39
	s_addc_u32 s17, s17, 0
	s_waitcnt lgkmcnt(7)
	global_store_dwordx4 v132, v[32:35], s[16:17] sc1
	s_add_u32 s16, s16, s39
	s_addc_u32 s17, s17, 0
	s_waitcnt lgkmcnt(6)
	global_store_dwordx4 v132, v[36:39], s[16:17] sc1
	s_add_u32 s16, s16, s39
	s_addc_u32 s17, s17, 0
	s_waitcnt lgkmcnt(5)
	global_store_dwordx4 v132, v[40:43], s[16:17] sc1
	s_add_u32 s16, s16, s39
	s_addc_u32 s17, s17, 0
	s_waitcnt lgkmcnt(4)
	global_store_dwordx4 v132, v[44:47], s[16:17] sc1
	s_add_u32 s16, s16, s39
	s_addc_u32 s17, s17, 0
	s_waitcnt lgkmcnt(3)
	global_store_dwordx4 v132, v[48:51], s[16:17] sc1
	s_add_u32 s16, s16, s39
	s_addc_u32 s17, s17, 0
	s_waitcnt lgkmcnt(2)
	global_store_dwordx4 v132, v[52:55], s[16:17] sc1
	s_add_u32 s16, s16, s39
	s_addc_u32 s17, s17, 0
	s_waitcnt lgkmcnt(1)
	global_store_dwordx4 v132, v[56:59], s[16:17] sc1
	s_add_u32 s16, s16, s39
	s_addc_u32 s17, s17, 0
	s_waitcnt lgkmcnt(0)
	global_store_dwordx4 v132, v[60:63], s[16:17] sc1
	s_barrier
	s_branch .LBB0_416

; DI void hyena_item_lat(const Params& p, int l, int it) {
;     ...
; #pragma unroll
;   for (int i = 2; i < 8; ++i) HY_LOADA(a[i], nb - 16 * i)
; #pragma unroll 1
;   for (int sb = 0; sb < L; sb += 128) {
; #pragma unroll
;     for (int u = 0; u < 4; ++u) {
;       const int s0 = sb + 32 * u;
;       HY_LOADA(a[(0 - 2 * u) & 7], nb + s0)
;       HY_LOADA(a[(1 - 2 * u) & 7], nb - 16 + s0)
;       const bf16x8 bfrag = *(const bf16x8*)(ub + s0);
; #pragma unroll
;       for (int i = 0; i < 8; ++i) acc[i] = __builtin_amdgcn_mfma_f32_16x16x32_bf16(a[(i - 2 * u) & 7].v, bfrag, acc[i], 0, 0, 0);
;     }
;   }
;     ...
;   float ssq = 0.f;
;   for (int t = 0; t < 32; ++t) ssq += WSP(const float, OFF_PART)[(size_t)(f * 32 + t) * 256 + c];
;   const float scale = rsqrtf(ssq + EPSF);
;   const float bias = p.in[I_HYBIAS][l * 256 + c];
;   const u16* X1C = WSP(const u16, OFF_X1C);
;   u16* YM = WSP(u16, OFF_ACT);
.LBB0_1139:
	s_waitcnt vmcnt(0)
	v_mov_b64_e32 v[66:67], v[82:83]
	v_mov_b64_e32 v[68:69], v[84:85]
	v_mov_b64_e32 v[70:71], v[86:87]
	v_mov_b64_e32 v[72:73], v[88:89]
	global_load_dwordx4 v[82:85], v[60:61], off offset:64
	global_load_dwordx4 v[86:89], v[60:61], off offset:128
	s_mov_b64 s[38:39], 0x100
	s_nop 1
	v_mfma_f32_16x16x32_bf16 v[4:7], v[48:51], v[66:69], v[4:7]
	v_add_u32_e32 v49, s13, v58
	v_add_u32_e32 v48, 0x880, v49
	v_add_u32_e32 v50, 0x870, v49
	v_mfma_f32_16x16x32_bf16 v[0:3], v[52:55], v[66:69], v[0:3]
	v_ashrrev_i32_e32 v49, 31, v48
	v_ashrrev_i32_e32 v51, 31, v50
	v_lshl_add_u64 v[78:79], v[48:49], 1, v[56:57]
	v_lshl_add_u64 v[80:81], v[50:51], 1, v[56:57]
	v_mfma_f32_16x16x32_bf16 v[12:15], v[32:35], v[66:69], v[12:15]
	global_load_dwordx4 v[48:51], v[78:79], off offset:64
	global_load_dwordx4 v[52:55], v[80:81], off offset:64
	s_addk_i32 s13, 0x80
	v_mfma_f32_16x16x32_bf16 v[8:11], v[36:39], v[66:69], v[8:11]
	s_cmpk_lt_u32 s13, 0x780
	global_load_dwordx4 v[74:77], v[60:61], off
	v_mfma_f32_16x16x32_bf16 v[4:7], v[32:35], v[70:73], v[4:7]
	global_load_dwordx4 v[32:35], v[78:79], off
	v_mfma_f32_16x16x32_bf16 v[0:3], v[36:39], v[70:73], v[0:3]
	global_load_dwordx4 v[36:39], v[80:81], off
	v_mfma_f32_16x16x32_bf16 v[20:23], v[40:43], v[66:69], v[20:23]
	v_mfma_f32_16x16x32_bf16 v[16:19], v[44:47], v[66:69], v[16:19]
	s_waitcnt vmcnt(1)
	v_mfma_f32_16x16x32_bf16 v[28:31], v[32:35], v[66:69], v[28:31]
	s_waitcnt vmcnt(0)
	v_mfma_f32_16x16x32_bf16 v[24:27], v[36:39], v[66:69], v[24:27]
	global_load_dwordx4 v[66:69], v[60:61], off offset:-64
	v_lshl_add_u64 v[60:61], v[60:61], 0, s[38:39]
	v_mfma_f32_16x16x32_bf16 v[12:15], v[40:43], v[70:73], v[12:15]
	v_mfma_f32_16x16x32_bf16 v[8:11], v[44:47], v[70:73], v[8:11]
	v_mfma_f32_16x16x32_bf16 v[20:23], v[32:35], v[70:73], v[20:23]
	v_mfma_f32_16x16x32_bf16 v[16:19], v[36:39], v[70:73], v[16:19]
	v_mfma_f32_16x16x32_bf16 v[28:31], v[48:51], v[70:73], v[28:31]
	v_mfma_f32_16x16x32_bf16 v[24:27], v[52:55], v[70:73], v[24:27]
	s_waitcnt vmcnt(0)
	v_mfma_f32_16x16x32_bf16 v[4:7], v[40:43], v[66:69], v[4:7]
	global_load_dwordx4 v[40:43], v[78:79], off offset:192
	v_mfma_f32_16x16x32_bf16 v[0:3], v[44:47], v[66:69], v[0:3]
	global_load_dwordx4 v[44:47], v[80:81], off offset:192
	v_mfma_f32_16x16x32_bf16 v[12:15], v[32:35], v[66:69], v[12:15]
	v_mfma_f32_16x16x32_bf16 v[8:11], v[36:39], v[66:69], v[8:11]
	v_mfma_f32_16x16x32_bf16 v[4:7], v[32:35], v[74:77], v[4:7]
	global_load_dwordx4 v[32:35], v[78:79], off offset:128
	v_mfma_f32_16x16x32_bf16 v[0:3], v[36:39], v[74:77], v[0:3]
	global_load_dwordx4 v[36:39], v[80:81], off offset:128
	v_mfma_f32_16x16x32_bf16 v[20:23], v[48:51], v[66:69], v[20:23]
	v_mfma_f32_16x16x32_bf16 v[16:19], v[52:55], v[66:69], v[16:19]
	v_mfma_f32_16x16x32_bf16 v[12:15], v[48:51], v[74:77], v[12:15]
	v_mfma_f32_16x16x32_bf16 v[8:11], v[52:55], v[74:77], v[8:11]
	s_waitcnt vmcnt(1)
	v_mfma_f32_16x16x32_bf16 v[28:31], v[32:35], v[66:69], v[28:31]
	s_waitcnt vmcnt(0)
	v_mfma_f32_16x16x32_bf16 v[24:27], v[36:39], v[66:69], v[24:27]
	v_mfma_f32_16x16x32_bf16 v[20:23], v[32:35], v[74:77], v[20:23]
	v_mfma_f32_16x16x32_bf16 v[16:19], v[36:39], v[74:77], v[16:19]
	v_mfma_f32_16x16x32_bf16 v[28:31], v[40:43], v[74:77], v[28:31]
	v_mfma_f32_16x16x32_bf16 v[24:27], v[44:47], v[74:77], v[24:27]
	s_cbranch_scc1 .LBB0_1139
	s_waitcnt vmcnt(0)
	v_mov_b64_e32 v[32:33], s[96:97]
	v_mad_i64_i32 v[32:33], s[38:39], v59, s9, v[32:33]
	s_mov_b64 s[38:39], 0x15600200
	s_ashr_i32 s35, s34, 31
	v_lshl_add_u64 v[32:33], v[32:33], 0, s[38:39]
	s_lshl_b64 s[38:39], s[34:35], 2
	s_add_u32 s38, s43, s38
	s_addc_u32 s39, s44, s39
	global_load_dword v38, v173, s[38:39]
	global_load_dword v39, v173, s[38:39] offset:1024
	global_load_dword v40, v173, s[38:39] offset:2048
	global_load_dword v41, v173, s[38:39] offset:3072
	v_mov_b32_e32 v92, 0x1000
	global_load_dword v42, v92, s[38:39]
	global_load_dword v43, v92, s[38:39] offset:1024
	global_load_dword v44, v92, s[38:39] offset:2048
	global_load_dword v45, v92, s[38:39] offset:3072
	v_mov_b32_e32 v92, 0x2000
	global_load_dword v46, v92, s[38:39]
	global_load_dword v47, v92, s[38:39] offset:1024
	global_load_dword v48, v92, s[38:39] offset:2048
	global_load_dword v49, v92, s[38:39] offset:3072
	v_mov_b32_e32 v92, 0x3000
	global_load_dword v50, v92, s[38:39]
	global_load_dword v51, v92, s[38:39] offset:1024
	global_load_dword v52, v92, s[38:39] offset:2048
	global_load_dword v53, v92, s[38:39] offset:3072
	v_mov_b32_e32 v92, 0x4000
	global_load_dword v54, v92, s[38:39]
	global_load_dword v55, v92, s[38:39] offset:1024
	global_load_dword v56, v92, s[38:39] offset:2048
	global_load_dword v57, v92, s[38:39] offset:3072
	v_mov_b32_e32 v92, 0x5000
	global_load_dword v58, v92, s[38:39]
	global_load_dword v65, v92, s[38:39] offset:1024
	global_load_dword v66, v92, s[38:39] offset:2048
	global_load_dword v67, v92, s[38:39] offset:3072
	v_mov_b32_e32 v92, 0x6000
	global_load_dword v68, v92, s[38:39]
	global_load_dword v69, v92, s[38:39] offset:1024
	global_load_dword v70, v92, s[38:39] offset:2048
	global_load_dword v71, v92, s[38:39] offset:3072
	v_mov_b32_e32 v92, 0x7000
	global_load_dword v72, v92, s[38:39]
	global_load_dword v73, v92, s[38:39] offset:1024
	global_load_dword v74, v92, s[38:39] offset:2048
	global_load_dword v75, v92, s[38:39] offset:3072
	v_readlane_b32 s16, v254, 29
	s_lshl_b64 s[36:37], s[36:37], 2
	v_readlane_b32 s18, v254, 31
	v_readlane_b32 s19, v254, 32
	s_add_u32 s36, s18, s36
	s_addc_u32 s37, s19, s37
	global_load_dword v37, v173, s[36:37]
	s_movk_i32 s13, 0x900
	v_lshl_or_b32 v34, v64, 2, v63
	v_mov_b32_e32 v35, 0x100
	v_mad_u32_u24 v172, v62, s13, v35
	v_mov_b32_e32 v35, 0
	v_lshl_add_u64 v[94:95], v[34:35], 1, v[32:33]
	global_load_dwordx2 v[76:77], v[94:95], off
	global_load_dwordx2 v[78:79], v[94:95], off offset:32
	global_load_dwordx2 v[80:81], v[94:95], off offset:64
	global_load_dwordx2 v[82:83], v[94:95], off offset:96
	global_load_dwordx2 v[84:85], v[94:95], off offset:128
	global_load_dwordx2 v[86:87], v[94:95], off offset:160
	global_load_dwordx2 v[88:89], v[94:95], off offset:192
	global_load_dwordx2 v[90:91], v[94:95], off offset:224
	v_readlane_b32 s17, v254, 30
	s_lshl_b64 s[34:35], s[34:35], 1
	v_readlane_b32 s16, v255, 42
	v_readlane_b32 s17, v255, 43
	v_readlane_b32 s20, v254, 33
	v_readlane_b32 s21, v254, 34
	v_readlane_b32 s24, v254, 37
	v_readlane_b32 s18, v254, 10
	s_mov_b64 s[20:21], s[46:47]
	s_mov_b32 s24, s64
	v_readlane_b32 s22, v254, 35
	v_readlane_b32 s23, v254, 36
	v_readlane_b32 s25, v254, 38
	v_readlane_b32 s26, v254, 39
	v_readlane_b32 s27, v254, 40
	v_readlane_b32 s28, v254, 41
	v_readlane_b32 s29, v254, 42
	v_readlane_b32 s30, v254, 43
	v_readlane_b32 s31, v254, 44
	v_readlane_b32 s19, v254, 11
	s_add_u32 s38, s16, s34
	s_addc_u32 s39, s17, s35
	s_add_u32 s36, s6, s34
	s_addc_u32 s37, s7, s35
	v_lshlrev_b32_e32 v142, 13, v62
	v_lshl_add_u32 v142, v34, 2, v142
	s_waitcnt vmcnt(0)
; DI u16 f2bf(float x) { u32 u = __float_as_uint(x); u += 0x7fffu + ((u >> 16) & 1u); return (u16)(u >> 16); }
; DI float bf2f(u16 v) { return __uint_as_float(((u32)v) << 16); }
; DI void hyena_item_lat(const Params& p, int l, int it) {
;     ...
;   float ssq = 0.f;
;   for (int t = 0; t < 32; ++t) ssq += WSP(const float, OFF_PART)[(size_t)(f * 32 + t) * 256 + c];
;   const float scale = rsqrtf(ssq + EPSF);
;   const float bias = p.in[I_HYBIAS][l * 256 + c];
;   const u16* X1C = WSP(const u16, OFF_X1C);
;   u16* YM = WSP(u16, OFF_ACT);
;   const int b = l16;
; #pragma unroll
;   for (int i = 0; i < 8; ++i)
; #pragma unroll
;     for (int r = 0; r < 4; ++r) {
;       const int t = tt0 + 16 * i + kg * 4 + r;
;       const size_t row = (size_t)b * TPB + posoff + t;
;       const float uu = bf2f(UT[((size_t)(c * 16 + b)) * TPB + posoff + t]);
;       const float x1 = bf2f(X1C[row * 256 + c]);
;       YM[row * 1024 + c] = f2bf(x1 * (scale * acc[i][r] + bias * uu));
	v_add_f32_e32 v36, 0, v38
	v_add_f32_e32 v36, v36, v39
	v_add_f32_e32 v36, v36, v40
	v_add_f32_e32 v36, v36, v41
	v_add_f32_e32 v36, v36, v42
	v_add_f32_e32 v36, v36, v43
	v_add_f32_e32 v36, v36, v44
	v_add_f32_e32 v36, v36, v45
	v_add_f32_e32 v36, v36, v46
	v_add_f32_e32 v36, v36, v47
	v_add_f32_e32 v36, v36, v48
	v_add_f32_e32 v36, v36, v49
	v_add_f32_e32 v36, v36, v50
	v_add_f32_e32 v36, v36, v51
	v_add_f32_e32 v36, v36, v52
	v_add_f32_e32 v36, v36, v53
	v_add_f32_e32 v36, v36, v54
	v_add_f32_e32 v36, v36, v55
	v_add_f32_e32 v36, v36, v56
	v_add_f32_e32 v36, v36, v57
	v_add_f32_e32 v36, v36, v58
	v_add_f32_e32 v36, v36, v65
	v_add_f32_e32 v36, v36, v66
	v_add_f32_e32 v36, v36, v67
	v_add_f32_e32 v36, v36, v68
	v_add_f32_e32 v36, v36, v69
	v_add_f32_e32 v36, v36, v70
	v_add_f32_e32 v36, v36, v71
	v_add_f32_e32 v36, v36, v72
	v_add_f32_e32 v36, v36, v73
	v_add_f32_e32 v36, v36, v74
	v_add_f32_e32 v36, v36, v75
	s_mov_b32 s13, 0x800000
	v_add_f32_e32 v36, 0x358637bd, v36
	v_cmp_gt_f32_e32 vcc, s13, v36
	v_mul_f32_e32 v35, 0x4b800000, v36
	s_movk_i32 s13, 0x900
	s_nop 0
	v_cndmask_b32_e32 v36, v36, v35, vcc
	v_rsq_f32_e32 v36, v36
	s_nop 0
	v_mul_f32_e32 v35, 0x45800000, v36
	v_cndmask_b32_e32 v36, v36, v35, vcc
	v_lshlrev_b32_e32 v92, 16, v76
	v_mul_f32_e32 v92, v37, v92
	v_fmac_f32_e32 v92, v28, v36
	v_mov_b32_e32 v28, v92
	v_and_b32_e32 v92, 0xffff0000, v76
	v_mul_f32_e32 v92, v37, v92
	v_fmac_f32_e32 v92, v29, v36
	v_mov_b32_e32 v29, v92
	v_lshlrev_b32_e32 v92, 16, v77
	v_mul_f32_e32 v92, v37, v92
	v_fmac_f32_e32 v92, v30, v36
	v_mov_b32_e32 v30, v92
	v_and_b32_e32 v92, 0xffff0000, v77
	v_mul_f32_e32 v92, v37, v92
	v_fmac_f32_e32 v92, v31, v36
	v_mov_b32_e32 v31, v92
	v_lshlrev_b32_e32 v92, 16, v78
	v_mul_f32_e32 v92, v37, v92
	v_fmac_f32_e32 v92, v24, v36
	v_mov_b32_e32 v24, v92
	v_and_b32_e32 v92, 0xffff0000, v78
	v_mul_f32_e32 v92, v37, v92
	v_fmac_f32_e32 v92, v25, v36
	v_mov_b32_e32 v25, v92
	v_lshlrev_b32_e32 v92, 16, v79
	v_mul_f32_e32 v92, v37, v92
	v_fmac_f32_e32 v92, v26, v36
	v_mov_b32_e32 v26, v92
	v_and_b32_e32 v92, 0xffff0000, v79
	v_mul_f32_e32 v92, v37, v92
	v_fmac_f32_e32 v92, v27, v36
	v_mov_b32_e32 v27, v92
	v_lshlrev_b32_e32 v92, 16, v80
	v_mul_f32_e32 v92, v37, v92
	v_fmac_f32_e32 v92, v20, v36
	v_mov_b32_e32 v20, v92
	v_and_b32_e32 v92, 0xffff0000, v80
	v_mul_f32_e32 v92, v37, v92
	v_fmac_f32_e32 v92, v21, v36
	v_mov_b32_e32 v21, v92
	v_lshlrev_b32_e32 v92, 16, v81
	v_mul_f32_e32 v92, v37, v92
	v_fmac_f32_e32 v92, v22, v36
	v_mov_b32_e32 v22, v92
	v_and_b32_e32 v92, 0xffff0000, v81
	v_mul_f32_e32 v92, v37, v92
	v_fmac_f32_e32 v92, v23, v36
	v_mov_b32_e32 v23, v92
	v_lshlrev_b32_e32 v92, 16, v82
	v_mul_f32_e32 v92, v37, v92
	v_fmac_f32_e32 v92, v16, v36
	v_mov_b32_e32 v16, v92
	v_and_b32_e32 v92, 0xffff0000, v82
	v_mul_f32_e32 v92, v37, v92
	v_fmac_f32_e32 v92, v17, v36
	v_mov_b32_e32 v17, v92
	v_lshlrev_b32_e32 v92, 16, v83
	v_mul_f32_e32 v92, v37, v92
	v_fmac_f32_e32 v92, v18, v36
	v_mov_b32_e32 v18, v92
	v_and_b32_e32 v92, 0xffff0000, v83
	v_mul_f32_e32 v92, v37, v92
	v_fmac_f32_e32 v92, v19, v36
	v_mov_b32_e32 v19, v92
	v_lshlrev_b32_e32 v92, 16, v84
	v_mul_f32_e32 v92, v37, v92
	v_fmac_f32_e32 v92, v12, v36
	v_mov_b32_e32 v12, v92
	v_and_b32_e32 v92, 0xffff0000, v84
	v_mul_f32_e32 v92, v37, v92
	v_fmac_f32_e32 v92, v13, v36
	v_mov_b32_e32 v13, v92
	v_lshlrev_b32_e32 v92, 16, v85
	v_mul_f32_e32 v92, v37, v92
	v_fmac_f32_e32 v92, v14, v36
	v_mov_b32_e32 v14, v92
	v_and_b32_e32 v92, 0xffff0000, v85
	v_mul_f32_e32 v92, v37, v92
	v_fmac_f32_e32 v92, v15, v36
	v_mov_b32_e32 v15, v92
	v_lshlrev_b32_e32 v92, 16, v86
	v_mul_f32_e32 v92, v37, v92
	v_fmac_f32_e32 v92, v8, v36
	v_mov_b32_e32 v8, v92
	v_and_b32_e32 v92, 0xffff0000, v86
	v_mul_f32_e32 v92, v37, v92
	v_fmac_f32_e32 v92, v9, v36
	v_mov_b32_e32 v9, v92
	v_lshlrev_b32_e32 v92, 16, v87
	v_mul_f32_e32 v92, v37, v92
	v_fmac_f32_e32 v92, v10, v36
	v_mov_b32_e32 v10, v92
	v_and_b32_e32 v92, 0xffff0000, v87
	v_mul_f32_e32 v92, v37, v92
	v_fmac_f32_e32 v92, v11, v36
	v_mov_b32_e32 v11, v92
	v_lshlrev_b32_e32 v92, 16, v88
	v_mul_f32_e32 v92, v37, v92
	v_fmac_f32_e32 v92, v4, v36
	v_mov_b32_e32 v4, v92
	v_and_b32_e32 v92, 0xffff0000, v88
	v_mul_f32_e32 v92, v37, v92
	v_fmac_f32_e32 v92, v5, v36
	v_mov_b32_e32 v5, v92
	v_lshlrev_b32_e32 v92, 16, v89
	v_mul_f32_e32 v92, v37, v92
	v_fmac_f32_e32 v92, v6, v36
	v_mov_b32_e32 v6, v92
	v_and_b32_e32 v92, 0xffff0000, v89
	v_mul_f32_e32 v92, v37, v92
	v_fmac_f32_e32 v92, v7, v36
	v_mov_b32_e32 v7, v92
	v_lshlrev_b32_e32 v92, 16, v90
	v_mul_f32_e32 v92, v37, v92
	v_fmac_f32_e32 v92, v0, v36
	v_mov_b32_e32 v0, v92
	v_and_b32_e32 v92, 0xffff0000, v90
	v_mul_f32_e32 v92, v37, v92
	v_fmac_f32_e32 v92, v1, v36
	v_mov_b32_e32 v1, v92
	v_lshlrev_b32_e32 v92, 16, v91
	v_mul_f32_e32 v92, v37, v92
	v_fmac_f32_e32 v92, v2, v36
	v_mov_b32_e32 v2, v92
	v_and_b32_e32 v92, 0xffff0000, v91
	v_mul_f32_e32 v92, v37, v92
	v_fmac_f32_e32 v92, v3, v36
	v_mov_b32_e32 v3, v92
	s_lshl_b32 s38, s34, 16
	s_add_u32 s38, s96, s38
	s_addc_u32 s39, s97, 0
	global_store_dwordx4 v142, v[28:31], s[38:39] sc1
	global_store_dwordx4 v142, v[24:27], s[38:39] offset:64 sc1
	global_store_dwordx4 v142, v[20:23], s[38:39] offset:128 sc1
	global_store_dwordx4 v142, v[16:19], s[38:39] offset:192 sc1
	global_store_dwordx4 v142, v[12:15], s[38:39] offset:256 sc1
	global_store_dwordx4 v142, v[8:11], s[38:39] offset:320 sc1
	global_store_dwordx4 v142, v[4:7], s[38:39] offset:384 sc1
	global_store_dwordx4 v142, v[0:3], s[38:39] offset:448 sc1

; DI u32 pack2(float a, float b) { return (u32)f2bf(a) | ((u32)f2bf(b) << 16); }
; DI float bflo(u32 v) { return __uint_as_float(v << 16); }
; DI float bfhi(u32 v) { return __uint_as_float(v & 0xffff0000u); }
; DI float silu_f(float x) { return x / (1.f + __expf(-x)); }
; DI void phase_ssd_combine(const Params& p, int l, int bid, int nblk) {
;     ...
;   for (int row = bid * 4 + w; row < ROWS; row += nblk * 4) {
;     const int pos = row % TPB;
;     if (l == 1 && pos < CTXL) continue;
;     const uint4 vf = *(const uint4*)(YF + (size_t)row * 512 + c0);
;     const uint4 vb = *(const uint4*)(YB + (size_t)row * 512 + c0);
;     const uint4 vx = *(const uint4*)(XBCA + (size_t)row * 1024 + c0);
;     const uint4 vz = *(const uint4*)(PZ + (size_t)row * 512 + c0);
;     const u32 af_[4] = {vf.x, vf.y, vf.z, vf.w}, ab_[4] = {vb.x, vb.y, vb.z, vb.w};
;     const u32 ax_[4] = {vx.x, vx.y, vx.z, vx.w}, az_[4] = {vz.x, vz.y, vz.z, vz.w};
;     float y[8];
;     float ss = 0.f;
; #pragma unroll
;     for (int i = 0; i < 4; ++i) {
;       const float y0 = bflo(af_[i]) + bflo(ab_[i]) + dsk * bflo(ax_[i]);
;       const float y1 = bfhi(af_[i]) + bfhi(ab_[i]) + dsk * bfhi(ax_[i]);
;       y[2 * i] = y0 * silu_f(bflo(az_[i]));
;       y[2 * i + 1] = y1 * silu_f(bfhi(az_[i]));
;       ss += y[2 * i] * y[2 * i] + y[2 * i + 1] * y[2 * i + 1];
;     }
; #pragma unroll
;     for (int o = 16; o >= 1; o >>= 1) ss += __shfl_xor(ss, o);
;     const float rs = rsqrtf(ss * (1.f / 256.f) + EPSF);
;     float o8[8];
; #pragma unroll
;     for (int i = 0; i < 8; ++i) o8[i] = y[i] * rs * ng[c0 + i];
;     uint4 o = {pack2(o8[0], o8[1]), pack2(o8[2], o8[3]), pack2(o8[4], o8[5]), pack2(o8[6], o8[7])};
;     *(uint4*)&YM[(size_t)row * 1024 + 256 + c0] = o;
;   }
.Lcmb_top:
	s_waitcnt vmcnt(5)
	v_lshlrev_b32_e32 v64, 16, v32
	v_and_b32_e32 v65, 0xffff0000, v32
	v_lshlrev_b32_e32 v66, 16, v33
	v_and_b32_e32 v67, 0xffff0000, v33
	v_lshlrev_b32_e32 v68, 16, v34
	v_and_b32_e32 v69, 0xffff0000, v34
	v_lshlrev_b32_e32 v70, 16, v35
	v_and_b32_e32 v71, 0xffff0000, v35
	v_lshlrev_b32_e32 v80, 16, v36
	v_and_b32_e32 v81, 0xffff0000, v36
	v_lshlrev_b32_e32 v82, 16, v37
	v_and_b32_e32 v83, 0xffff0000, v37
	v_lshlrev_b32_e32 v84, 16, v38
	v_and_b32_e32 v85, 0xffff0000, v38
	v_lshlrev_b32_e32 v86, 16, v39
	v_and_b32_e32 v87, 0xffff0000, v39
	v_add_f32_e32 v64, v64, v80
	v_add_f32_e32 v65, v65, v81
	v_add_f32_e32 v66, v66, v82
	v_add_f32_e32 v67, v67, v83
	v_add_f32_e32 v68, v68, v84
	v_add_f32_e32 v69, v69, v85
	v_add_f32_e32 v70, v70, v86
	v_add_f32_e32 v71, v71, v87
	v_lshlrev_b32_e32 v80, 16, v40
	v_and_b32_e32 v81, 0xffff0000, v40
	v_lshlrev_b32_e32 v82, 16, v41
	v_and_b32_e32 v83, 0xffff0000, v41
	v_lshlrev_b32_e32 v84, 16, v42
	v_and_b32_e32 v85, 0xffff0000, v42
	v_lshlrev_b32_e32 v86, 16, v43
	v_and_b32_e32 v87, 0xffff0000, v43
	v_fmac_f32_e32 v64, v24, v80
	v_fmac_f32_e32 v65, v24, v81
	v_fmac_f32_e32 v66, v24, v82
	v_fmac_f32_e32 v67, v24, v83
	v_fmac_f32_e32 v68, v24, v84
	v_fmac_f32_e32 v69, v24, v85
	v_fmac_f32_e32 v70, v24, v86
	v_fmac_f32_e32 v71, v24, v87
	v_lshlrev_b32_e32 v72, 16, v44
	v_and_b32_e32 v73, 0xffff0000, v44
	v_lshlrev_b32_e32 v74, 16, v45
	v_and_b32_e32 v75, 0xffff0000, v45
	v_lshlrev_b32_e32 v76, 16, v46
	v_and_b32_e32 v77, 0xffff0000, v46
	v_lshlrev_b32_e32 v78, 16, v47
	v_and_b32_e32 v79, 0xffff0000, v47
	v_mul_f32_e32 v80, 0xbfb8aa3b, v72
	v_mul_f32_e32 v81, 0xbfb8aa3b, v73
	v_mul_f32_e32 v82, 0xbfb8aa3b, v74
	v_mul_f32_e32 v83, 0xbfb8aa3b, v75
	v_mul_f32_e32 v84, 0xbfb8aa3b, v76
	v_mul_f32_e32 v85, 0xbfb8aa3b, v77
	v_mul_f32_e32 v86, 0xbfb8aa3b, v78
	v_mul_f32_e32 v87, 0xbfb8aa3b, v79
	v_exp_f32_e32 v80, v80
	v_exp_f32_e32 v81, v81
	v_exp_f32_e32 v82, v82
	v_exp_f32_e32 v83, v83
	v_exp_f32_e32 v84, v84
	v_exp_f32_e32 v85, v85
	v_exp_f32_e32 v86, v86
	v_exp_f32_e32 v87, v87
	v_add_f32_e32 v80, 1.0, v80
	v_add_f32_e32 v81, 1.0, v81
	v_add_f32_e32 v82, 1.0, v82
	v_add_f32_e32 v83, 1.0, v83
	v_add_f32_e32 v84, 1.0, v84
	v_add_f32_e32 v85, 1.0, v85
	v_add_f32_e32 v86, 1.0, v86
	v_add_f32_e32 v87, 1.0, v87
	v_rcp_f32_e32 v80, v80
	v_rcp_f32_e32 v81, v81
	v_rcp_f32_e32 v82, v82
	v_rcp_f32_e32 v83, v83
	v_rcp_f32_e32 v84, v84
	v_rcp_f32_e32 v85, v85
	v_rcp_f32_e32 v86, v86
	v_rcp_f32_e32 v87, v87
	v_mul_f32_e32 v72, v72, v80
	v_mul_f32_e32 v73, v73, v81
	v_mul_f32_e32 v74, v74, v82
	v_mul_f32_e32 v75, v75, v83
	v_mul_f32_e32 v76, v76, v84
	v_mul_f32_e32 v77, v77, v85
	v_mul_f32_e32 v78, v78, v86
	v_mul_f32_e32 v79, v79, v87
	v_mul_f32_e32 v64, v64, v72
	v_mul_f32_e32 v65, v65, v73
	v_mul_f32_e32 v66, v66, v74
	v_mul_f32_e32 v67, v67, v75
	v_mul_f32_e32 v68, v68, v76
	v_mul_f32_e32 v69, v69, v77
	v_mul_f32_e32 v70, v70, v78
	v_mul_f32_e32 v71, v71, v79
	v_mul_f32_e32 v7, v64, v64
	v_fmac_f32_e32 v7, v65, v65
	v_fmac_f32_e32 v7, v66, v66
	v_fmac_f32_e32 v7, v67, v67
	v_fmac_f32_e32 v7, v68, v68
	v_fmac_f32_e32 v7, v69, v69
	v_fmac_f32_e32 v7, v70, v70
	v_fmac_f32_e32 v7, v71, v71
	s_nop 1
	v_add_f32_dpp v7, v7, v7 quad_perm:[1,0,3,2] row_mask:0xf bank_mask:0xf
	s_nop 1
	v_add_f32_dpp v7, v7, v7 quad_perm:[2,3,0,1] row_mask:0xf bank_mask:0xf
	s_nop 1
	v_add_f32_dpp v7, v7, v7 row_half_mirror row_mask:0xf bank_mask:0xf
	s_nop 1
	v_add_f32_dpp v7, v7, v7 row_mirror row_mask:0xf bank_mask:0xf
	s_nop 1
	ds_bpermute_b32 v8, v5, v7
	s_waitcnt lgkmcnt(0)
	v_add_f32_e32 v7, v7, v8
	v_mov_b32_e32 v8, 0x358637bd
	v_fmac_f32_e32 v8, 0x3b800000, v7
	v_rsq_f32_e32 v8, v8
	s_nop 0
	v_mul_f32_e32 v64, v64, v8
	v_mul_f32_e32 v65, v65, v8
	v_mul_f32_e32 v66, v66, v8
	v_mul_f32_e32 v67, v67, v8
	v_mul_f32_e32 v68, v68, v8
	v_mul_f32_e32 v69, v69, v8
	v_mul_f32_e32 v70, v70, v8
	v_mul_f32_e32 v71, v71, v8
	v_mul_f32_e32 v64, v64, v16
	v_mul_f32_e32 v65, v65, v17
	v_mul_f32_e32 v66, v66, v18
	v_mul_f32_e32 v67, v67, v19
	v_mul_f32_e32 v68, v68, v20
	v_mul_f32_e32 v69, v69, v21
	v_mul_f32_e32 v70, v70, v22
	v_mul_f32_e32 v71, v71, v23
	v_cvt_pk_bf16_f32 v88, v64, v65
	v_cvt_pk_bf16_f32 v89, v66, v67
	v_cvt_pk_bf16_f32 v90, v68, v69
	v_cvt_pk_bf16_f32 v91, v70, v71
	s_nop 0
	global_store_dwordx4 v4, v[88:91], s[80:81] offset:512 sc1
	s_add_i32 s28, s27, 2
	s_cmp_lt_u32 s28, s26
	s_cselect_b32 s28, s28, 0
	s_cmp_ge_u32 s28, s23
	s_addc_u32 s44, s28, 0
	s_cmp_ge_u32 s44, s25
	s_addc_u32 s44, s44, 0
	s_lshl_b32 s44, s44, 11
	s_add_i32 s44, s44, s19
	s_lshl_b32 s16, s44, 10
	s_lshl_b32 s17, s44, 11
	s_add_u32 s30, s96, s16
	s_addc_u32 s31, s97, 0
	s_add_u32 s48, s30, 0x3600000
	s_addc_u32 s49, s31, 0
	s_add_u32 s30, s30, 0x5a00000
	s_addc_u32 s31, s31, 0
	s_add_u32 s38, s30, 0x2400000
	s_addc_u32 s39, s31, 0
	s_add_u32 s66, s96, s17
	s_addc_u32 s67, s97, 0
	s_add_u32 s66, s66, 0xea00000
	s_addc_u32 s67, s67, 0
	s_add_u32 s80, s6, s17
	s_addc_u32 s81, s7, 0
	global_load_dwordx4 v[32:35], v4, s[30:31]
	global_load_dwordx4 v[36:39], v4, s[38:39]
	global_load_dwordx4 v[40:43], v4, s[66:67]
	global_load_dwordx4 v[44:47], v4, s[48:49]
	s_waitcnt vmcnt(5)
; DI u32 pack2(float a, float b) { return (u32)f2bf(a) | ((u32)f2bf(b) << 16); }
; DI float bflo(u32 v) { return __uint_as_float(v << 16); }
; DI float bfhi(u32 v) { return __uint_as_float(v & 0xffff0000u); }
; DI float silu_f(float x) { return x / (1.f + __expf(-x)); }
; DI void phase_ssd_combine(const Params& p, int l, int bid, int nblk) {
;     ...
;   for (int row = bid * 4 + w; row < ROWS; row += nblk * 4) {
;     const int pos = row % TPB;
;     if (l == 1 && pos < CTXL) continue;
;     const uint4 vf = *(const uint4*)(YF + (size_t)row * 512 + c0);
;     const uint4 vb = *(const uint4*)(YB + (size_t)row * 512 + c0);
;     const uint4 vx = *(const uint4*)(XBCA + (size_t)row * 1024 + c0);
;     const uint4 vz = *(const uint4*)(PZ + (size_t)row * 512 + c0);
;     const u32 af_[4] = {vf.x, vf.y, vf.z, vf.w}, ab_[4] = {vb.x, vb.y, vb.z, vb.w};
;     const u32 ax_[4] = {vx.x, vx.y, vx.z, vx.w}, az_[4] = {vz.x, vz.y, vz.z, vz.w};
;     float y[8];
;     float ss = 0.f;
; #pragma unroll
;     for (int i = 0; i < 4; ++i) {
;       const float y0 = bflo(af_[i]) + bflo(ab_[i]) + dsk * bflo(ax_[i]);
;       const float y1 = bfhi(af_[i]) + bfhi(ab_[i]) + dsk * bfhi(ax_[i]);
;       y[2 * i] = y0 * silu_f(bflo(az_[i]));
;       y[2 * i + 1] = y1 * silu_f(bfhi(az_[i]));
;       ss += y[2 * i] * y[2 * i] + y[2 * i + 1] * y[2 * i + 1];
;     }
; #pragma unroll
;     for (int o = 16; o >= 1; o >>= 1) ss += __shfl_xor(ss, o);
;     const float rs = rsqrtf(ss * (1.f / 256.f) + EPSF);
;     float o8[8];
; #pragma unroll
;     for (int i = 0; i < 8; ++i) o8[i] = y[i] * rs * ng[c0 + i];
;     uint4 o = {pack2(o8[0], o8[1]), pack2(o8[2], o8[3]), pack2(o8[4], o8[5]), pack2(o8[6], o8[7])};
;     *(uint4*)&YM[(size_t)row * 1024 + 256 + c0] = o;
;   }
	v_lshlrev_b32_e32 v64, 16, v48
	v_and_b32_e32 v65, 0xffff0000, v48
	v_lshlrev_b32_e32 v66, 16, v49
	v_and_b32_e32 v67, 0xffff0000, v49
	v_lshlrev_b32_e32 v68, 16, v50
	v_and_b32_e32 v69, 0xffff0000, v50
	v_lshlrev_b32_e32 v70, 16, v51
	v_and_b32_e32 v71, 0xffff0000, v51
	v_lshlrev_b32_e32 v80, 16, v52
	v_and_b32_e32 v81, 0xffff0000, v52
	v_lshlrev_b32_e32 v82, 16, v53
	v_and_b32_e32 v83, 0xffff0000, v53
	v_lshlrev_b32_e32 v84, 16, v54
	v_and_b32_e32 v85, 0xffff0000, v54
	v_lshlrev_b32_e32 v86, 16, v55
	v_and_b32_e32 v87, 0xffff0000, v55
	v_add_f32_e32 v64, v64, v80
	v_add_f32_e32 v65, v65, v81
	v_add_f32_e32 v66, v66, v82
	v_add_f32_e32 v67, v67, v83
	v_add_f32_e32 v68, v68, v84
	v_add_f32_e32 v69, v69, v85
	v_add_f32_e32 v70, v70, v86
	v_add_f32_e32 v71, v71, v87
	v_lshlrev_b32_e32 v80, 16, v56
	v_and_b32_e32 v81, 0xffff0000, v56
	v_lshlrev_b32_e32 v82, 16, v57
	v_and_b32_e32 v83, 0xffff0000, v57
	v_lshlrev_b32_e32 v84, 16, v58
	v_and_b32_e32 v85, 0xffff0000, v58
	v_lshlrev_b32_e32 v86, 16, v59
	v_and_b32_e32 v87, 0xffff0000, v59
	v_fmac_f32_e32 v64, v24, v80
	v_fmac_f32_e32 v65, v24, v81
	v_fmac_f32_e32 v66, v24, v82
	v_fmac_f32_e32 v67, v24, v83
	v_fmac_f32_e32 v68, v24, v84
	v_fmac_f32_e32 v69, v24, v85
	v_fmac_f32_e32 v70, v24, v86
	v_fmac_f32_e32 v71, v24, v87
	v_lshlrev_b32_e32 v72, 16, v60
	v_and_b32_e32 v73, 0xffff0000, v60
	v_lshlrev_b32_e32 v74, 16, v61
	v_and_b32_e32 v75, 0xffff0000, v61
	v_lshlrev_b32_e32 v76, 16, v62
	v_and_b32_e32 v77, 0xffff0000, v62
	v_lshlrev_b32_e32 v78, 16, v63
	v_and_b32_e32 v79, 0xffff0000, v63
	v_mul_f32_e32 v80, 0xbfb8aa3b, v72
	v_mul_f32_e32 v81, 0xbfb8aa3b, v73
	v_mul_f32_e32 v82, 0xbfb8aa3b, v74
	v_mul_f32_e32 v83, 0xbfb8aa3b, v75
	v_mul_f32_e32 v84, 0xbfb8aa3b, v76
	v_mul_f32_e32 v85, 0xbfb8aa3b, v77
	v_mul_f32_e32 v86, 0xbfb8aa3b, v78
	v_mul_f32_e32 v87, 0xbfb8aa3b, v79
	v_exp_f32_e32 v80, v80
	v_exp_f32_e32 v81, v81
	v_exp_f32_e32 v82, v82
	v_exp_f32_e32 v83, v83
	v_exp_f32_e32 v84, v84
	v_exp_f32_e32 v85, v85
	v_exp_f32_e32 v86, v86
	v_exp_f32_e32 v87, v87
	v_add_f32_e32 v80, 1.0, v80
	v_add_f32_e32 v81, 1.0, v81
	v_add_f32_e32 v82, 1.0, v82
	v_add_f32_e32 v83, 1.0, v83
	v_add_f32_e32 v84, 1.0, v84
	v_add_f32_e32 v85, 1.0, v85
	v_add_f32_e32 v86, 1.0, v86
	v_add_f32_e32 v87, 1.0, v87
	v_rcp_f32_e32 v80, v80
	v_rcp_f32_e32 v81, v81
	v_rcp_f32_e32 v82, v82
	v_rcp_f32_e32 v83, v83
	v_rcp_f32_e32 v84, v84
	v_rcp_f32_e32 v85, v85
	v_rcp_f32_e32 v86, v86
	v_rcp_f32_e32 v87, v87
	v_mul_f32_e32 v72, v72, v80
	v_mul_f32_e32 v73, v73, v81
	v_mul_f32_e32 v74, v74, v82
	v_mul_f32_e32 v75, v75, v83
	v_mul_f32_e32 v76, v76, v84
	v_mul_f32_e32 v77, v77, v85
	v_mul_f32_e32 v78, v78, v86
	v_mul_f32_e32 v79, v79, v87
	v_mul_f32_e32 v64, v64, v72
	v_mul_f32_e32 v65, v65, v73
	v_mul_f32_e32 v66, v66, v74
	v_mul_f32_e32 v67, v67, v75
	v_mul_f32_e32 v68, v68, v76
	v_mul_f32_e32 v69, v69, v77
	v_mul_f32_e32 v70, v70, v78
	v_mul_f32_e32 v71, v71, v79
	v_mul_f32_e32 v7, v64, v64
	v_fmac_f32_e32 v7, v65, v65
	v_fmac_f32_e32 v7, v66, v66
	v_fmac_f32_e32 v7, v67, v67
	v_fmac_f32_e32 v7, v68, v68
	v_fmac_f32_e32 v7, v69, v69
	v_fmac_f32_e32 v7, v70, v70
	v_fmac_f32_e32 v7, v71, v71
	s_nop 1
	v_add_f32_dpp v7, v7, v7 quad_perm:[1,0,3,2] row_mask:0xf bank_mask:0xf
	s_nop 1
	v_add_f32_dpp v7, v7, v7 quad_perm:[2,3,0,1] row_mask:0xf bank_mask:0xf
	s_nop 1
	v_add_f32_dpp v7, v7, v7 row_half_mirror row_mask:0xf bank_mask:0xf
	s_nop 1
	v_add_f32_dpp v7, v7, v7 row_mirror row_mask:0xf bank_mask:0xf
	s_nop 1
	ds_bpermute_b32 v8, v5, v7
	s_waitcnt lgkmcnt(0)
	v_add_f32_e32 v7, v7, v8
	v_mov_b32_e32 v8, 0x358637bd
	v_fmac_f32_e32 v8, 0x3b800000, v7
	v_rsq_f32_e32 v8, v8
	s_nop 0
	v_mul_f32_e32 v64, v64, v8
	v_mul_f32_e32 v65, v65, v8
	v_mul_f32_e32 v66, v66, v8
	v_mul_f32_e32 v67, v67, v8
	v_mul_f32_e32 v68, v68, v8
	v_mul_f32_e32 v69, v69, v8
	v_mul_f32_e32 v70, v70, v8
	v_mul_f32_e32 v71, v71, v8
	v_mul_f32_e32 v64, v64, v16
	v_mul_f32_e32 v65, v65, v17
	v_mul_f32_e32 v66, v66, v18
	v_mul_f32_e32 v67, v67, v19
	v_mul_f32_e32 v68, v68, v20
	v_mul_f32_e32 v69, v69, v21
	v_mul_f32_e32 v70, v70, v22
	v_mul_f32_e32 v71, v71, v23
	v_cvt_pk_bf16_f32 v88, v64, v65
	v_cvt_pk_bf16_f32 v89, v66, v67
	v_cvt_pk_bf16_f32 v90, v68, v69
	v_cvt_pk_bf16_f32 v91, v70, v71
	s_nop 0
	global_store_dwordx4 v4, v[88:91], s[82:83] offset:512 sc1
	s_add_i32 s28, s27, 3
	s_cmp_lt_u32 s28, s26
	s_cselect_b32 s28, s28, 0
	s_cmp_ge_u32 s28, s23
	s_addc_u32 s44, s28, 0
	s_cmp_ge_u32 s44, s25
	s_addc_u32 s44, s44, 0
	s_lshl_b32 s44, s44, 11
	s_add_i32 s44, s44, s19
	s_lshl_b32 s16, s44, 10
	s_lshl_b32 s17, s44, 11
	s_add_u32 s30, s96, s16
	s_addc_u32 s31, s97, 0
	s_add_u32 s48, s30, 0x3600000
	s_addc_u32 s49, s31, 0
	s_add_u32 s30, s30, 0x5a00000
	s_addc_u32 s31, s31, 0
	s_add_u32 s38, s30, 0x2400000
	s_addc_u32 s39, s31, 0
	s_add_u32 s66, s96, s17
	s_addc_u32 s67, s97, 0
	s_add_u32 s66, s66, 0xea00000
	s_addc_u32 s67, s67, 0
	s_add_u32 s82, s6, s17
	s_addc_u32 s83, s7, 0
	global_load_dwordx4 v[48:51], v4, s[30:31]
	global_load_dwordx4 v[52:55], v4, s[38:39]
	global_load_dwordx4 v[56:59], v4, s[66:67]
	global_load_dwordx4 v[60:63], v4, s[48:49]
	s_add_i32 s27, s27, 2
	s_cmp_lt_u32 s27, s26
	s_cbranch_scc1 .Lcmb_top
	s_waitcnt vmcnt(0)
	v_readlane_b32 s19, v253, 0
	v_lshrrev_b32_e32 v4, 2, v218
	v_and_b32_e32 v5, 3, v218
	v_lshlrev_b32_e32 v6, 17, v4
	v_lshl_add_u32 v6, v5, 6, v6
	v_mul_u32_u24_e32 v7, 4352, v5
	v_lshl_add_u32 v7, v4, 2, v7
	v_mul_u32_u24_e32 v8, 272, v4
	v_lshl_add_u32 v8, v5, 6, v8
	v_lshlrev_b32_e32 v9, 9, v4
	v_lshl_add_u32 v9, v5, 5, v9
	v_lshlrev_b32_e32 v10, 11, v4
	v_lshl_add_u32 v10, v5, 5, v10
	s_mov_b32 s38, 0
; DI u16 f2bf(float x) { u32 u = __float_as_uint(x); u += 0x7fffu + ((u >> 16) & 1u); return (u16)(u >> 16); }
; DI float bf2f(u16 v) { return __uint_as_float(((u32)v) << 16); }
; DI void hyena_item_lat(const Params& p, int l, int it) {
;     ...
;   const int b = l16;
; #pragma unroll
;   for (int i = 0; i < 8; ++i)
; #pragma unroll
;     for (int r = 0; r < 4; ++r) {
;       const int t = tt0 + 16 * i + kg * 4 + r;
;       const size_t row = (size_t)b * TPB + posoff + t;
;       const float uu = bf2f(UT[((size_t)(c * 16 + b)) * TPB + posoff + t]);
;       const float x1 = bf2f(X1C[row * 256 + c]);
;       YM[row * 1024 + c] = f2bf(x1 * (scale * acc[i][r] + bias * uu));
;     }
.Lhyt_top:
	s_lshl_b32 s16, s38, 9
	s_add_i32 s16, s16, s19
	s_and_b32 s22, s16, 3
	s_bfe_u32 s23, s16, 0x50002
	s_lshr_b32 s25, s16, 7
	s_lshl_b32 s17, s22, 23
	s_lshl_b32 s16, s25, 13
	s_add_i32 s17, s17, s16
	s_lshl_b32 s16, s23, 8
	s_add_i32 s17, s17, s16
	s_add_u32 s26, s96, s17
	s_addc_u32 s27, s97, 0
	s_mul_i32 s17, s25, 0x900
	s_lshl_b32 s16, s23, 6
	s_add_i32 s17, s17, s16
	s_addk_i32 s17, 0x100
	s_lshl_b32 s16, s17, 9
	s_lshl_b32 s39, s22, 7
	s_add_i32 s16, s16, s39
	s_add_u32 s28, s96, 0x16800000
	s_addc_u32 s29, s97, 0
	s_add_u32 s28, s28, s16
	s_addc_u32 s29, s29, 0
	s_lshl_b32 s16, s17, 11
	s_add_i32 s16, s16, s39
	s_add_u32 s30, s6, s16
	s_addc_u32 s31, s7, 0
	global_load_dwordx4 v[16:19], v6, s[26:27]
	global_load_dwordx4 v[20:23], v6, s[26:27] offset:16
	global_load_dwordx4 v[24:27], v6, s[26:27] offset:32
	global_load_dwordx4 v[28:31], v6, s[26:27] offset:48
	global_load_dwordx4 v[32:35], v9, s[28:29]
	global_load_dwordx4 v[36:39], v9, s[28:29] offset:16
	s_waitcnt vmcnt(2)
	ds_write_b32 v7, v16
	ds_write_b32 v7, v17 offset:272
	ds_write_b32 v7, v18 offset:544
	ds_write_b32 v7, v19 offset:816
	ds_write_b32 v7, v20 offset:1088
	ds_write_b32 v7, v21 offset:1360
	ds_write_b32 v7, v22 offset:1632
	ds_write_b32 v7, v23 offset:1904
	ds_write_b32 v7, v24 offset:2176
	ds_write_b32 v7, v25 offset:2448
	ds_write_b32 v7, v26 offset:2720
	ds_write_b32 v7, v27 offset:2992
	ds_write_b32 v7, v28 offset:3264
	ds_write_b32 v7, v29 offset:3536
	ds_write_b32 v7, v30 offset:3808
	ds_write_b32 v7, v31 offset:4080
	s_waitcnt lgkmcnt(0)
	s_barrier
	ds_read_b128 v[16:19], v8
	ds_read_b128 v[20:23], v8 offset:16
	ds_read_b128 v[24:27], v8 offset:32
	ds_read_b128 v[28:31], v8 offset:48
	s_waitcnt vmcnt(0) lgkmcnt(0)
	v_lshlrev_b32_e32 v11, 16, v32
	v_mul_f32_e32 v16, v16, v11
	v_and_b32_e32 v11, 0xffff0000, v32
	v_mul_f32_e32 v17, v17, v11
	v_lshlrev_b32_e32 v11, 16, v33
	v_mul_f32_e32 v18, v18, v11
	v_and_b32_e32 v11, 0xffff0000, v33
	v_mul_f32_e32 v19, v19, v11
	v_lshlrev_b32_e32 v11, 16, v34
	v_mul_f32_e32 v20, v20, v11
	v_and_b32_e32 v11, 0xffff0000, v34
	v_mul_f32_e32 v21, v21, v11
	v_lshlrev_b32_e32 v11, 16, v35
	v_mul_f32_e32 v22, v22, v11
	v_and_b32_e32 v11, 0xffff0000, v35
	v_mul_f32_e32 v23, v23, v11
	v_lshlrev_b32_e32 v11, 16, v36
	v_mul_f32_e32 v24, v24, v11
	v_and_b32_e32 v11, 0xffff0000, v36
	v_mul_f32_e32 v25, v25, v11
	v_lshlrev_b32_e32 v11, 16, v37
	v_mul_f32_e32 v26, v26, v11
	v_and_b32_e32 v11, 0xffff0000, v37
	v_mul_f32_e32 v27, v27, v11
	v_lshlrev_b32_e32 v11, 16, v38
	v_mul_f32_e32 v28, v28, v11
	v_and_b32_e32 v11, 0xffff0000, v38
	v_mul_f32_e32 v29, v29, v11
	v_lshlrev_b32_e32 v11, 16, v39
	v_mul_f32_e32 v30, v30, v11
	v_and_b32_e32 v11, 0xffff0000, v39
	v_mul_f32_e32 v31, v31, v11
	v_cvt_pk_bf16_f32 v32, v16, v17
	v_cvt_pk_bf16_f32 v33, v18, v19
	v_cvt_pk_bf16_f32 v34, v20, v21
	v_cvt_pk_bf16_f32 v35, v22, v23
	v_cvt_pk_bf16_f32 v36, v24, v25
	v_cvt_pk_bf16_f32 v37, v26, v27
	v_cvt_pk_bf16_f32 v38, v28, v29
	v_cvt_pk_bf16_f32 v39, v30, v31
	s_nop 0
	global_store_dwordx4 v10, v[32:35], s[30:31] sc1
	global_store_dwordx4 v10, v[36:39], s[30:31] offset:16 sc1
	s_barrier
	s_add_i32 s38, s38, 1
	s_cmp_lt_u32 s38, 4
	s_cbranch_scc1 .Lhyt_top
	s_waitcnt vmcnt(0)

; DI void phase_outproj(const Params& p, int l, int bid, int nblk, char* smem) {
;     ...
;   auto ef = [=](int m, int n, float v0, float v1, float v2, float v3) {
;     const int b = m / TPB, pos = m % TPB;
;     const float4 ga = *(const float4*)&MOD[(size_t)(l * 17 + (pos < CTXL ? 16 : b)) * 6144 + 2048 + n];
;     const float4 xo = *(const float4*)(xrow_ptr(pp, l == 0, b, pos) + n);
;     const float4 o = {xo.x + ga.x * v0, xo.y + ga.y * v1, xo.z + ga.z * v2, xo.w + ga.w * v3};
;     *(float4*)(xrow_wptr(pp, b, pos) + n) = o;
;   };
;   const int ntile = (l == 1 ? NB * 16 : ROWS / 128) * 8;
;   const int vb = (nblk % 8 == 0) ? (bid & 7) * (nblk >> 3) + (bid >> 3) : bid;
;   for (int t = vb; t < ntile; t += nblk) {
;     const int mi = t >> 3, nt = t & 7;
;     const int mt = (l == 1) ? (mi >> 4) * 18 + 2 + (mi & 15) : mi;
;     gemm_tile<true, 2>(af, bfn, ef, mt * 128, nt * 128, 1024, smem);
.Lop_go:
	s_lshl_b32 s18, s35, 2
	s_add_u32 s48, s48, s18
	s_addc_u32 s49, s49, 0
	s_add_u32 s50, s50, s18
	s_addc_u32 s51, s51, 0
	s_mul_i32 s19, s19, 0x6000
	v_readlane_b32 s20, v253, 19
	v_readlane_b32 s21, v253, 20
	s_add_u32 s20, s20, s19
	s_addc_u32 s21, s21, 0
	s_add_u32 s20, s20, s18
	s_addc_u32 s21, s21, 0
	s_add_u32 s20, s20, 0x2000
	s_addc_u32 s21, s21, 0
	v_and_b32_e32 v128, 31, v218
	v_lshrrev_b32_e32 v129, 7, v218
	v_bfe_u32 v130, v218, 5, 1
	v_bfe_u32 v131, v218, 6, 1
	v_lshl_add_u32 v128, v129, 6, v128
	v_mul_u32_u24_e32 v128, 528, v128
	v_lshlrev_b32_e32 v131, 8, v131
	v_lshl_add_u32 v131, v130, 4, v131
	v_add_u32_e32 v128, v128, v131
	v_lshrrev_b32_e32 v129, 5, v218
	v_and_b32_e32 v130, 31, v218
	v_lshlrev_b32_e32 v132, 12, v129
	v_lshlrev_b32_e32 v133, 4, v130
	v_lshl_add_u32 v132, v130, 4, v132
	global_load_dwordx4 v[136:139], v133, s[20:21]
	global_load_dwordx4 v[64:67], v132, s[48:49]
	s_add_u32 s48, s48, 0x8000
	s_addc_u32 s49, s49, 0
	global_load_dwordx4 v[68:71], v132, s[48:49]
	s_add_u32 s48, s48, 0x8000
	s_addc_u32 s49, s49, 0
	global_load_dwordx4 v[72:75], v132, s[48:49]
	s_add_u32 s48, s48, 0x8000
	s_addc_u32 s49, s49, 0
	global_load_dwordx4 v[76:79], v132, s[48:49]
	s_add_u32 s48, s48, 0x8000
	s_addc_u32 s49, s49, 0
	global_load_dwordx4 v[80:83], v132, s[48:49]
	s_add_u32 s48, s48, 0x8000
	s_addc_u32 s49, s49, 0
	global_load_dwordx4 v[84:87], v132, s[48:49]
	s_add_u32 s48, s48, 0x8000
	s_addc_u32 s49, s49, 0
	global_load_dwordx4 v[88:91], v132, s[48:49]
	s_add_u32 s48, s48, 0x8000
	s_addc_u32 s49, s49, 0
	global_load_dwordx4 v[92:95], v132, s[48:49]
	s_add_u32 s48, s48, 0x8000
	s_addc_u32 s49, s49, 0
	global_load_dwordx4 v[96:99], v132, s[48:49]
	s_add_u32 s48, s48, 0x8000
	s_addc_u32 s49, s49, 0
	global_load_dwordx4 v[100:103], v132, s[48:49]
	s_add_u32 s48, s48, 0x8000
	s_addc_u32 s49, s49, 0
	global_load_dwordx4 v[104:107], v132, s[48:49]
	s_add_u32 s48, s48, 0x8000
	s_addc_u32 s49, s49, 0
	global_load_dwordx4 v[108:111], v132, s[48:49]
	s_add_u32 s48, s48, 0x8000
	s_addc_u32 s49, s49, 0
	global_load_dwordx4 v[112:115], v132, s[48:49]
	s_add_u32 s48, s48, 0x8000
	s_addc_u32 s49, s49, 0
	global_load_dwordx4 v[116:119], v132, s[48:49]
	s_add_u32 s48, s48, 0x8000
	s_addc_u32 s49, s49, 0
	global_load_dwordx4 v[120:123], v132, s[48:49]
	s_add_u32 s48, s48, 0x8000
	s_addc_u32 s49, s49, 0
	global_load_dwordx4 v[124:127], v132, s[48:49]
	ds_write_b128 v128, v[48:51] offset:0
	ds_write_b128 v128, v[52:55] offset:32
	ds_write_b128 v128, v[56:59] offset:64
	ds_write_b128 v128, v[60:63] offset:96
	ds_write_b128 v128, v[32:35] offset:128
	ds_write_b128 v128, v[36:39] offset:160
	ds_write_b128 v128, v[40:43] offset:192
	ds_write_b128 v128, v[44:47] offset:224
	ds_write_b128 v128, v[16:19] offset:16896
	ds_write_b128 v128, v[20:23] offset:16928
	ds_write_b128 v128, v[24:27] offset:16960
	ds_write_b128 v128, v[28:31] offset:16992
	ds_write_b128 v128, v[0:3] offset:17024
	ds_write_b128 v128, v[4:7] offset:17056
	ds_write_b128 v128, v[8:11] offset:17088
	ds_write_b128 v128, v[12:15] offset:17120
	v_mul_u32_u24_e32 v131, 528, v129
	v_lshl_add_u32 v131, v130, 4, v131
	s_waitcnt lgkmcnt(0)
	s_barrier
; DI void phase_outproj(const Params& p, int l, int bid, int nblk, char* smem) {
;     ...
;   auto ef = [=](int m, int n, float v0, float v1, float v2, float v3) {
;     const int b = m / TPB, pos = m % TPB;
;     const float4 ga = *(const float4*)&MOD[(size_t)(l * 17 + (pos < CTXL ? 16 : b)) * 6144 + 2048 + n];
;     const float4 xo = *(const float4*)(xrow_ptr(pp, l == 0, b, pos) + n);
;     const float4 o = {xo.x + ga.x * v0, xo.y + ga.y * v1, xo.z + ga.z * v2, xo.w + ga.w * v3};
;     *(float4*)(xrow_wptr(pp, b, pos) + n) = o;
;   };
	ds_read_b128 v[0:3], v131 offset:0
	ds_read_b128 v[4:7], v131 offset:4224
	ds_read_b128 v[8:11], v131 offset:8448
	ds_read_b128 v[12:15], v131 offset:12672
	ds_read_b128 v[16:19], v131 offset:16896
	ds_read_b128 v[20:23], v131 offset:21120
	ds_read_b128 v[24:27], v131 offset:25344
	ds_read_b128 v[28:31], v131 offset:29568
	ds_read_b128 v[32:35], v131 offset:33792
	ds_read_b128 v[36:39], v131 offset:38016
	ds_read_b128 v[40:43], v131 offset:42240
	ds_read_b128 v[44:47], v131 offset:46464
	ds_read_b128 v[48:51], v131 offset:50688
	ds_read_b128 v[52:55], v131 offset:54912
	ds_read_b128 v[56:59], v131 offset:59136
	ds_read_b128 v[60:63], v131 offset:63360
	s_waitcnt vmcnt(15) lgkmcnt(15)
	v_pk_fma_f32 v[0:1], v[136:137], v[0:1], v[64:65]
	v_pk_fma_f32 v[2:3], v[138:139], v[2:3], v[66:67]
	s_nop 0
	global_store_dwordx4 v132, v[0:3], s[50:51] sc1
	s_add_u32 s50, s50, 0x8000
	s_addc_u32 s51, s51, 0
	s_waitcnt vmcnt(15) lgkmcnt(14)
	v_pk_fma_f32 v[4:5], v[136:137], v[4:5], v[68:69]
	v_pk_fma_f32 v[6:7], v[138:139], v[6:7], v[70:71]
	s_nop 0
	global_store_dwordx4 v132, v[4:7], s[50:51] sc1
	s_add_u32 s50, s50, 0x8000
	s_addc_u32 s51, s51, 0
	s_waitcnt vmcnt(15) lgkmcnt(13)
	v_pk_fma_f32 v[8:9], v[136:137], v[8:9], v[72:73]
	v_pk_fma_f32 v[10:11], v[138:139], v[10:11], v[74:75]
	s_nop 0
	global_store_dwordx4 v132, v[8:11], s[50:51] sc1
	s_add_u32 s50, s50, 0x8000
	s_addc_u32 s51, s51, 0
	s_waitcnt vmcnt(15) lgkmcnt(12)
	v_pk_fma_f32 v[12:13], v[136:137], v[12:13], v[76:77]
	v_pk_fma_f32 v[14:15], v[138:139], v[14:15], v[78:79]
	s_nop 0
	global_store_dwordx4 v132, v[12:15], s[50:51] sc1
	s_add_u32 s50, s50, 0x8000
	s_addc_u32 s51, s51, 0
	s_waitcnt vmcnt(15) lgkmcnt(11)
	v_pk_fma_f32 v[16:17], v[136:137], v[16:17], v[80:81]
	v_pk_fma_f32 v[18:19], v[138:139], v[18:19], v[82:83]
	s_nop 0
	global_store_dwordx4 v132, v[16:19], s[50:51] sc1
	s_add_u32 s50, s50, 0x8000
	s_addc_u32 s51, s51, 0
	s_waitcnt vmcnt(15) lgkmcnt(10)
	v_pk_fma_f32 v[20:21], v[136:137], v[20:21], v[84:85]
	v_pk_fma_f32 v[22:23], v[138:139], v[22:23], v[86:87]
	s_nop 0
	global_store_dwordx4 v132, v[20:23], s[50:51] sc1
	s_add_u32 s50, s50, 0x8000
	s_addc_u32 s51, s51, 0
	s_waitcnt vmcnt(15) lgkmcnt(9)
	v_pk_fma_f32 v[24:25], v[136:137], v[24:25], v[88:89]
	v_pk_fma_f32 v[26:27], v[138:139], v[26:27], v[90:91]
	s_nop 0
	global_store_dwordx4 v132, v[24:27], s[50:51] sc1
	s_add_u32 s50, s50, 0x8000
	s_addc_u32 s51, s51, 0
	s_waitcnt vmcnt(15) lgkmcnt(8)
	v_pk_fma_f32 v[28:29], v[136:137], v[28:29], v[92:93]
	v_pk_fma_f32 v[30:31], v[138:139], v[30:31], v[94:95]
	s_nop 0
	global_store_dwordx4 v132, v[28:31], s[50:51] sc1
	s_add_u32 s50, s50, 0x8000
	s_addc_u32 s51, s51, 0
	s_waitcnt vmcnt(15) lgkmcnt(7)
	v_pk_fma_f32 v[32:33], v[136:137], v[32:33], v[96:97]
	v_pk_fma_f32 v[34:35], v[138:139], v[34:35], v[98:99]
	s_nop 0
	global_store_dwordx4 v132, v[32:35], s[50:51] sc1
	s_add_u32 s50, s50, 0x8000
	s_addc_u32 s51, s51, 0
	s_waitcnt vmcnt(15) lgkmcnt(6)
	v_pk_fma_f32 v[36:37], v[136:137], v[36:37], v[100:101]
	v_pk_fma_f32 v[38:39], v[138:139], v[38:39], v[102:103]
	s_nop 0
	global_store_dwordx4 v132, v[36:39], s[50:51] sc1
	s_add_u32 s50, s50, 0x8000
	s_addc_u32 s51, s51, 0
	s_waitcnt vmcnt(15) lgkmcnt(5)
	v_pk_fma_f32 v[40:41], v[136:137], v[40:41], v[104:105]
	v_pk_fma_f32 v[42:43], v[138:139], v[42:43], v[106:107]
	s_nop 0
	global_store_dwordx4 v132, v[40:43], s[50:51] sc1
	s_add_u32 s50, s50, 0x8000
	s_addc_u32 s51, s51, 0
	s_waitcnt vmcnt(15) lgkmcnt(4)
	v_pk_fma_f32 v[44:45], v[136:137], v[44:45], v[108:109]
	v_pk_fma_f32 v[46:47], v[138:139], v[46:47], v[110:111]
	s_nop 0
	global_store_dwordx4 v132, v[44:47], s[50:51] sc1
	s_add_u32 s50, s50, 0x8000
	s_addc_u32 s51, s51, 0
	s_waitcnt vmcnt(15) lgkmcnt(3)
	v_pk_fma_f32 v[48:49], v[136:137], v[48:49], v[112:113]
	v_pk_fma_f32 v[50:51], v[138:139], v[50:51], v[114:115]
	s_nop 0
	global_store_dwordx4 v132, v[48:51], s[50:51] sc1
	s_add_u32 s50, s50, 0x8000
	s_addc_u32 s51, s51, 0
	s_waitcnt vmcnt(15) lgkmcnt(2)
	v_pk_fma_f32 v[52:53], v[136:137], v[52:53], v[116:117]
	v_pk_fma_f32 v[54:55], v[138:139], v[54:55], v[118:119]
	s_nop 0
	global_store_dwordx4 v132, v[52:55], s[50:51] sc1
	s_add_u32 s50, s50, 0x8000
	s_addc_u32 s51, s51, 0
	s_waitcnt vmcnt(15) lgkmcnt(1)
	v_pk_fma_f32 v[56:57], v[136:137], v[56:57], v[120:121]
	v_pk_fma_f32 v[58:59], v[138:139], v[58:59], v[122:123]
	s_nop 0
	global_store_dwordx4 v132, v[56:59], s[50:51] sc1
	s_add_u32 s50, s50, 0x8000
	s_addc_u32 s51, s51, 0
	s_waitcnt vmcnt(15) lgkmcnt(0)
	v_pk_fma_f32 v[60:61], v[136:137], v[60:61], v[124:125]
	v_pk_fma_f32 v[62:63], v[138:139], v[62:63], v[126:127]
	s_nop 0
	global_store_dwordx4 v132, v[60:63], s[50:51] sc1
	s_barrier
	s_add_i32 s34, s34, s54
	s_cmp_ge_i32 s34, s13
	s_cbranch_scc0 .LBB0_1262
	v_readlane_b32 s18, v254, 10
	s_mov_b64 s[20:21], s[46:47]
	s_mov_b32 s24, s64
	v_readlane_b32 s19, v254, 11

; DI u32 pack2(float a, float b) { return (u32)f2bf(a) | ((u32)f2bf(b) << 16); }
; DI void phase_norm(const Params& p, int l, int which, int bid, int nblk) {
;     ...
;     float ss = 0.f;
; #pragma unroll
;     for (int i = 0; i < 16; ++i) ss += x[i] * x[i];
;     ss = wave_sum(ss);
;     const float rs = rsqrtf(ss * (1.f / 1024.f) + EPSF);
; #pragma unroll
;     for (int hh = 0; hh < 2; ++hh) {
;       const int c0 = hh * 512 + lane * 8;
;       float y[8];
; #pragma unroll
;       for (int i = 0; i < 8; ++i) {
;         const float yn = x[hh * 8 + i] * rs * g[c0 + i];
;         y[i] = yn * (1.f + mod[1024 + c0 + i]) + mod[c0 + i];
;       }
;       uint4 o = {pack2(y[0], y[1]), pack2(y[2], y[3]), pack2(y[4], y[5]), pack2(y[6], y[7])};
;       *(uint4*)&WSP(u16, OFF_ACT)[(size_t)row * 1024 + c0] = o;
;     }
.Ln2_top:
	s_waitcnt vmcnt(16)
	v_mul_f32_e32 v7, v32, v32
	v_fmac_f32_e32 v7, v33, v33
	v_fmac_f32_e32 v7, v34, v34
	v_fmac_f32_e32 v7, v35, v35
	v_fmac_f32_e32 v7, v36, v36
	v_fmac_f32_e32 v7, v37, v37
	v_fmac_f32_e32 v7, v38, v38
	v_fmac_f32_e32 v7, v39, v39
	v_fmac_f32_e32 v7, v40, v40
	v_fmac_f32_e32 v7, v41, v41
	v_fmac_f32_e32 v7, v42, v42
	v_fmac_f32_e32 v7, v43, v43
	v_fmac_f32_e32 v7, v44, v44
	v_fmac_f32_e32 v7, v45, v45
	v_fmac_f32_e32 v7, v46, v46
	v_fmac_f32_e32 v7, v47, v47
	s_nop 1
	v_add_f32_dpp v7, v7, v7 quad_perm:[1,0,3,2] row_mask:0xf bank_mask:0xf
	s_nop 1
	v_add_f32_dpp v7, v7, v7 quad_perm:[2,3,0,1] row_mask:0xf bank_mask:0xf
	s_nop 1
	v_add_f32_dpp v7, v7, v7 row_half_mirror row_mask:0xf bank_mask:0xf
	s_nop 1
	v_add_f32_dpp v7, v7, v7 row_mirror row_mask:0xf bank_mask:0xf
	s_nop 1
	ds_bpermute_b32 v8, v5, v7
	s_waitcnt lgkmcnt(0)
	v_add_f32_e32 v7, v7, v8
	ds_bpermute_b32 v8, v6, v7
	s_waitcnt lgkmcnt(0)
	v_add_f32_e32 v7, v7, v8
	v_mov_b32_e32 v8, 0x358637bd
	v_fmac_f32_e32 v8, 0x3a800000, v7
	v_rsq_f32_e32 v8, v8
	s_nop 0
	v_mul_f32_e32 v32, v32, v8
	v_mul_f32_e32 v33, v33, v8
	v_mul_f32_e32 v34, v34, v8
	v_mul_f32_e32 v35, v35, v8
	v_mul_f32_e32 v36, v36, v8
	v_mul_f32_e32 v37, v37, v8
	v_mul_f32_e32 v38, v38, v8
	v_mul_f32_e32 v39, v39, v8
	v_mul_f32_e32 v40, v40, v8
	v_mul_f32_e32 v41, v41, v8
	v_mul_f32_e32 v42, v42, v8
	v_mul_f32_e32 v43, v43, v8
	v_mul_f32_e32 v44, v44, v8
	v_mul_f32_e32 v45, v45, v8
	v_mul_f32_e32 v46, v46, v8
	v_mul_f32_e32 v47, v47, v8
	v_mul_f32_e32 v32, v32, v16
	v_mul_f32_e32 v33, v33, v17
	v_mul_f32_e32 v34, v34, v18
	v_mul_f32_e32 v35, v35, v19
	v_mul_f32_e32 v36, v36, v20
	v_mul_f32_e32 v37, v37, v21
	v_mul_f32_e32 v38, v38, v22
	v_mul_f32_e32 v39, v39, v23
	v_mul_f32_e32 v40, v40, v24
	v_mul_f32_e32 v41, v41, v25
	v_mul_f32_e32 v42, v42, v26
	v_mul_f32_e32 v43, v43, v27
	v_mul_f32_e32 v44, v44, v28
	v_mul_f32_e32 v45, v45, v29
	v_mul_f32_e32 v46, v46, v30
	v_mul_f32_e32 v47, v47, v31
	v_add_f32_e32 v80, 1.0, v80
	v_add_f32_e32 v81, 1.0, v81
	v_add_f32_e32 v82, 1.0, v82
	v_add_f32_e32 v83, 1.0, v83
	v_add_f32_e32 v84, 1.0, v84
	v_add_f32_e32 v85, 1.0, v85
	v_add_f32_e32 v86, 1.0, v86
	v_add_f32_e32 v87, 1.0, v87
	v_add_f32_e32 v88, 1.0, v88
	v_add_f32_e32 v89, 1.0, v89
	v_add_f32_e32 v90, 1.0, v90
	v_add_f32_e32 v91, 1.0, v91
	v_add_f32_e32 v92, 1.0, v92
	v_add_f32_e32 v93, 1.0, v93
	v_add_f32_e32 v94, 1.0, v94
	v_add_f32_e32 v95, 1.0, v95
	v_fma_f32 v32, v32, v80, v64
	v_fma_f32 v33, v33, v81, v65
	v_fma_f32 v34, v34, v82, v66
	v_fma_f32 v35, v35, v83, v67
	v_fma_f32 v36, v36, v84, v68
	v_fma_f32 v37, v37, v85, v69
	v_fma_f32 v38, v38, v86, v70
	v_fma_f32 v39, v39, v87, v71
	v_fma_f32 v40, v40, v88, v72
	v_fma_f32 v41, v41, v89, v73
	v_fma_f32 v42, v42, v90, v74
	v_fma_f32 v43, v43, v91, v75
	v_fma_f32 v44, v44, v92, v76
	v_fma_f32 v45, v45, v93, v77
	v_fma_f32 v46, v46, v94, v78
	v_fma_f32 v47, v47, v95, v79
	v_cvt_pk_bf16_f32 v32, v32, v33
	v_cvt_pk_bf16_f32 v33, v34, v35
	v_cvt_pk_bf16_f32 v34, v36, v37
	v_cvt_pk_bf16_f32 v35, v38, v39
	v_cvt_pk_bf16_f32 v36, v40, v41
	v_cvt_pk_bf16_f32 v37, v42, v43
	v_cvt_pk_bf16_f32 v38, v44, v45
	v_cvt_pk_bf16_f32 v39, v46, v47
	s_nop 0
	global_store_dwordx2 v9, v[32:33], s[50:51] sc1
	global_store_dwordx2 v9, v[34:35], s[50:51] offset:512 sc1
	global_store_dwordx2 v9, v[36:37], s[50:51] offset:1024 sc1
	global_store_dwordx2 v9, v[38:39], s[50:51] offset:1536 sc1
	s_add_i32 s28, s27, 2
	s_cmp_lt_u32 s28, s26
	s_cselect_b32 s28, s28, 0
	s_cmp_ge_u32 s28, s23
	s_addc_u32 s44, s28, 0
	s_cmp_ge_u32 s44, s25
	s_addc_u32 s44, s44, 0
	s_lshl_b32 s44, s44, 11
	s_add_i32 s44, s44, s19
	s_mul_hi_u32 s46, s44, 0x38e38e39
	s_lshr_b32 s46, s46, 9
	s_mul_i32 s16, s46, 0x900
	s_sub_u32 s16, s44, s16
	s_cmp_lt_u32 s16, 0x100
	s_cbranch_scc1 .Ln2_3_ctx
	s_lshl_b32 s17, s46, 11
	s_add_i32 s17, s17, s16
	s_add_i32 s17, s17, 0xffffff00
	s_lshl_b32 s17, s17, 12
	s_add_u32 s30, s94, s17
	s_addc_u32 s31, s95, 0
	s_add_i32 s46, s46, s65
	s_branch .Ln2_3_ptr

; DI u32 pack2(float a, float b) { return (u32)f2bf(a) | ((u32)f2bf(b) << 16); }
; DI void phase_norm(const Params& p, int l, int which, int bid, int nblk) {
;     ...
;   for (int row = bid * 4 + w; row < ROWS; row += nblk * 4) {
;     const int b = row / TPB, pos = row % TPB;
;     if (which == 1 && l == 1 && pos < CTXL) continue;
;     const float* xr = xrow_ptr(p, from_input, b, pos);
;     const float* mod = WSP(const float, OFF_MOD) + (size_t)(l * 17 + (pos < CTXL ? 16 : b)) * 6144 + which * 3072;
;     float x[16];
; #pragma unroll
;     for (int hh = 0; hh < 2; ++hh) {
;       const float4 a = *(const float4*)(xr + hh * 512 + lane * 8);
;       const float4 c = *(const float4*)(xr + hh * 512 + lane * 8 + 4);
;       x[hh * 8 + 0] = a.x; x[hh * 8 + 1] = a.y; x[hh * 8 + 2] = a.z; x[hh * 8 + 3] = a.w;
;       x[hh * 8 + 4] = c.x; x[hh * 8 + 5] = c.y; x[hh * 8 + 6] = c.z; x[hh * 8 + 7] = c.w;
;     }
;     float ss = 0.f;
; #pragma unroll
;     for (int i = 0; i < 16; ++i) ss += x[i] * x[i];
;     ss = wave_sum(ss);
;     const float rs = rsqrtf(ss * (1.f / 1024.f) + EPSF);
; #pragma unroll
;     for (int hh = 0; hh < 2; ++hh) {
;       const int c0 = hh * 512 + lane * 8;
;       float y[8];
; #pragma unroll
;       for (int i = 0; i < 8; ++i) {
;         const float yn = x[hh * 8 + i] * rs * g[c0 + i];
;         y[i] = yn * (1.f + mod[1024 + c0 + i]) + mod[c0 + i];
;       }
;       uint4 o = {pack2(y[0], y[1]), pack2(y[2], y[3]), pack2(y[4], y[5]), pack2(y[6], y[7])};
;       *(uint4*)&WSP(u16, OFF_ACT)[(size_t)row * 1024 + c0] = o;
;     }
.Ln2_3_ptr:
	s_mul_i32 s46, s46, 0x6000
	s_add_u32 s36, s96, 0x1be07000
	s_addc_u32 s37, s97, 0
	s_add_u32 s36, s36, s46
	s_addc_u32 s37, s37, 0
	s_add_u32 s38, s36, 0x1000
	s_addc_u32 s39, s37, 0
	s_lshl_b32 s17, s44, 11
	s_add_u32 s50, s6, s17
	s_addc_u32 s51, s7, 0
	global_load_dwordx4 v[32:35], v4, s[30:31]
	global_load_dwordx4 v[36:39], v4, s[30:31] offset:1024
	global_load_dwordx4 v[40:43], v4, s[30:31] offset:2048
	global_load_dwordx4 v[44:47], v4, s[30:31] offset:3072
	global_load_dwordx4 v[64:67], v4, s[36:37]
	global_load_dwordx4 v[68:71], v4, s[36:37] offset:1024
	global_load_dwordx4 v[72:75], v4, s[36:37] offset:2048
	global_load_dwordx4 v[76:79], v4, s[36:37] offset:3072
	global_load_dwordx4 v[80:83], v4, s[38:39]
	global_load_dwordx4 v[84:87], v4, s[38:39] offset:1024
	global_load_dwordx4 v[88:91], v4, s[38:39] offset:2048
	global_load_dwordx4 v[92:95], v4, s[38:39] offset:3072
	s_waitcnt vmcnt(16)
	v_mul_f32_e32 v7, v48, v48
	v_fmac_f32_e32 v7, v49, v49
	v_fmac_f32_e32 v7, v50, v50
	v_fmac_f32_e32 v7, v51, v51
	v_fmac_f32_e32 v7, v52, v52
	v_fmac_f32_e32 v7, v53, v53
	v_fmac_f32_e32 v7, v54, v54
	v_fmac_f32_e32 v7, v55, v55
	v_fmac_f32_e32 v7, v56, v56
	v_fmac_f32_e32 v7, v57, v57
	v_fmac_f32_e32 v7, v58, v58
	v_fmac_f32_e32 v7, v59, v59
	v_fmac_f32_e32 v7, v60, v60
	v_fmac_f32_e32 v7, v61, v61
	v_fmac_f32_e32 v7, v62, v62
	v_fmac_f32_e32 v7, v63, v63
	s_nop 1
	v_add_f32_dpp v7, v7, v7 quad_perm:[1,0,3,2] row_mask:0xf bank_mask:0xf
	s_nop 1
	v_add_f32_dpp v7, v7, v7 quad_perm:[2,3,0,1] row_mask:0xf bank_mask:0xf
	s_nop 1
	v_add_f32_dpp v7, v7, v7 row_half_mirror row_mask:0xf bank_mask:0xf
	s_nop 1
	v_add_f32_dpp v7, v7, v7 row_mirror row_mask:0xf bank_mask:0xf
	s_nop 1
	ds_bpermute_b32 v8, v5, v7
	s_waitcnt lgkmcnt(0)
	v_add_f32_e32 v7, v7, v8
	ds_bpermute_b32 v8, v6, v7
	s_waitcnt lgkmcnt(0)
	v_add_f32_e32 v7, v7, v8
	v_mov_b32_e32 v8, 0x358637bd
	v_fmac_f32_e32 v8, 0x3a800000, v7
	v_rsq_f32_e32 v8, v8
	s_nop 0
	v_mul_f32_e32 v48, v48, v8
	v_mul_f32_e32 v49, v49, v8
	v_mul_f32_e32 v50, v50, v8
	v_mul_f32_e32 v51, v51, v8
	v_mul_f32_e32 v52, v52, v8
	v_mul_f32_e32 v53, v53, v8
	v_mul_f32_e32 v54, v54, v8
	v_mul_f32_e32 v55, v55, v8
	v_mul_f32_e32 v56, v56, v8
	v_mul_f32_e32 v57, v57, v8
	v_mul_f32_e32 v58, v58, v8
	v_mul_f32_e32 v59, v59, v8
	v_mul_f32_e32 v60, v60, v8
	v_mul_f32_e32 v61, v61, v8
	v_mul_f32_e32 v62, v62, v8
	v_mul_f32_e32 v63, v63, v8
	v_mul_f32_e32 v48, v48, v16
	v_mul_f32_e32 v49, v49, v17
	v_mul_f32_e32 v50, v50, v18
	v_mul_f32_e32 v51, v51, v19
	v_mul_f32_e32 v52, v52, v20
	v_mul_f32_e32 v53, v53, v21
	v_mul_f32_e32 v54, v54, v22
	v_mul_f32_e32 v55, v55, v23
	v_mul_f32_e32 v56, v56, v24
	v_mul_f32_e32 v57, v57, v25
	v_mul_f32_e32 v58, v58, v26
	v_mul_f32_e32 v59, v59, v27
	v_mul_f32_e32 v60, v60, v28
	v_mul_f32_e32 v61, v61, v29
	v_mul_f32_e32 v62, v62, v30
	v_mul_f32_e32 v63, v63, v31
	v_add_f32_e32 v112, 1.0, v112
	v_add_f32_e32 v113, 1.0, v113
	v_add_f32_e32 v114, 1.0, v114
	v_add_f32_e32 v115, 1.0, v115
	v_add_f32_e32 v116, 1.0, v116
	v_add_f32_e32 v117, 1.0, v117
	v_add_f32_e32 v118, 1.0, v118
	v_add_f32_e32 v119, 1.0, v119
	v_add_f32_e32 v120, 1.0, v120
	v_add_f32_e32 v121, 1.0, v121
	v_add_f32_e32 v122, 1.0, v122
	v_add_f32_e32 v123, 1.0, v123
	v_add_f32_e32 v124, 1.0, v124
	v_add_f32_e32 v125, 1.0, v125
	v_add_f32_e32 v126, 1.0, v126
	v_add_f32_e32 v127, 1.0, v127
	v_fma_f32 v48, v48, v112, v96
	v_fma_f32 v49, v49, v113, v97
	v_fma_f32 v50, v50, v114, v98
	v_fma_f32 v51, v51, v115, v99
	v_fma_f32 v52, v52, v116, v100
	v_fma_f32 v53, v53, v117, v101
	v_fma_f32 v54, v54, v118, v102
	v_fma_f32 v55, v55, v119, v103
	v_fma_f32 v56, v56, v120, v104
	v_fma_f32 v57, v57, v121, v105
	v_fma_f32 v58, v58, v122, v106
	v_fma_f32 v59, v59, v123, v107
	v_fma_f32 v60, v60, v124, v108
	v_fma_f32 v61, v61, v125, v109
	v_fma_f32 v62, v62, v126, v110
	v_fma_f32 v63, v63, v127, v111
	v_cvt_pk_bf16_f32 v48, v48, v49
	v_cvt_pk_bf16_f32 v49, v50, v51
	v_cvt_pk_bf16_f32 v50, v52, v53
	v_cvt_pk_bf16_f32 v51, v54, v55
	v_cvt_pk_bf16_f32 v52, v56, v57
	v_cvt_pk_bf16_f32 v53, v58, v59
	v_cvt_pk_bf16_f32 v54, v60, v61
	v_cvt_pk_bf16_f32 v55, v62, v63
	s_nop 0
	global_store_dwordx2 v9, v[48:49], s[56:57] sc1
	global_store_dwordx2 v9, v[50:51], s[56:57] offset:512 sc1
	global_store_dwordx2 v9, v[52:53], s[56:57] offset:1024 sc1
	global_store_dwordx2 v9, v[54:55], s[56:57] offset:1536 sc1
	s_add_i32 s28, s27, 3
	s_cmp_lt_u32 s28, s26
	s_cselect_b32 s28, s28, 0
	s_cmp_ge_u32 s28, s23
	s_addc_u32 s44, s28, 0
	s_cmp_ge_u32 s44, s25
	s_addc_u32 s44, s44, 0
	s_lshl_b32 s44, s44, 11
	s_add_i32 s44, s44, s19
	s_mul_hi_u32 s46, s44, 0x38e38e39
	s_lshr_b32 s46, s46, 9
	s_mul_i32 s16, s46, 0x900
	s_sub_u32 s16, s44, s16
	s_cmp_lt_u32 s16, 0x100
	s_cbranch_scc1 .Ln2_4_ctx
	s_lshl_b32 s17, s46, 11
	s_add_i32 s17, s17, s16
	s_add_i32 s17, s17, 0xffffff00
	s_lshl_b32 s17, s17, 12
	s_add_u32 s30, s94, s17
	s_addc_u32 s31, s95, 0
	s_add_i32 s46, s46, s65
	s_branch .Ln2_4_ptr

; DI void phase_tables(const Params& p, int l, int bid, int nblk) {
;     ...
;   for (int e = gtid; e < 2 * 16384 * 64; e += gn) {
;     const int which = e / (16384 * 64), r = e % (16384 * 64);
;     const float sc = which ? V_SCALE : U_SCALE;
;     const float* src = (which ? p.in[I_PV] : p.in[I_PU]) + (size_t)l * 16384 * 1024 + (size_t)r * 16;
;     u32 o[4];
; #pragma unroll
;     for (int q = 0; q < 4; ++q) {
;       const float4 a = *(const float4*)(src + q * 4);
;       int v = __builtin_amdgcn_cvt_pk_fp8_f32(a.x * sc, a.y * sc, 0, false);
;       v = __builtin_amdgcn_cvt_pk_fp8_f32(a.z * sc, a.w * sc, v, true);
;       o[q] = (u32)v;
;     }
;     uint4 ov = {o[0], o[1], o[2], o[3]};
;     *(uint4*)&dst[(size_t)e * 16] = ov;
;   }
.LBB0_1330:
	s_or_b64 exec, exec, s[34:35]
	v_readlane_b32 s19, v255, 54
	v_readlane_b32 s16, v255, 40
	v_readlane_b32 s17, v255, 41
	s_lshl_b32 s86, s24, 26
	v_add_u32_e32 v0, s19, v218
	v_lshlrev_b32_e32 v4, 6, v0
	v_bfe_u32 v1, v0, 3, 3
	v_lshlrev_b32_e32 v1, 21, v1
	v_bfe_u32 v2, v0, 6, 11
	v_lshl_or_b32 v1, v2, 7, v1
	v_and_b32_e32 v2, 7, v0
	v_lshl_or_b32 v5, v2, 4, v1
	s_add_u32 s22, s88, s86
	s_addc_u32 s23, s89, 0
	global_load_dwordx4 v[8:11], v4, s[22:23]
	global_load_dwordx4 v[12:15], v4, s[22:23] offset:16
	global_load_dwordx4 v[16:19], v4, s[22:23] offset:32
	global_load_dwordx4 v[20:23], v4, s[22:23] offset:48
	s_add_u32 s36, s22, 0x800000
	s_addc_u32 s37, s23, 0
	global_load_dwordx4 v[24:27], v4, s[36:37]
	global_load_dwordx4 v[28:31], v4, s[36:37] offset:16
	global_load_dwordx4 v[32:35], v4, s[36:37] offset:32
	global_load_dwordx4 v[36:39], v4, s[36:37] offset:48
	s_add_u32 s36, s22, 0x1000000
	s_addc_u32 s37, s23, 0
	global_load_dwordx4 v[40:43], v4, s[36:37]
	global_load_dwordx4 v[44:47], v4, s[36:37] offset:16
	global_load_dwordx4 v[48:51], v4, s[36:37] offset:32
	global_load_dwordx4 v[52:55], v4, s[36:37] offset:48
	s_add_u32 s36, s22, 0x1800000
	s_addc_u32 s37, s23, 0
	global_load_dwordx4 v[56:59], v4, s[36:37]
	global_load_dwordx4 v[60:63], v4, s[36:37] offset:16
	global_load_dwordx4 v[64:67], v4, s[36:37] offset:32
	global_load_dwordx4 v[68:71], v4, s[36:37] offset:48
	s_add_u32 s36, s22, 0x2000000
	s_addc_u32 s37, s23, 0
	global_load_dwordx4 v[72:75], v4, s[36:37]
	global_load_dwordx4 v[76:79], v4, s[36:37] offset:16
	global_load_dwordx4 v[80:83], v4, s[36:37] offset:32
	global_load_dwordx4 v[84:87], v4, s[36:37] offset:48
	s_add_u32 s36, s22, 0x2800000
	s_addc_u32 s37, s23, 0
	global_load_dwordx4 v[88:91], v4, s[36:37]
	global_load_dwordx4 v[92:95], v4, s[36:37] offset:16
	global_load_dwordx4 v[96:99], v4, s[36:37] offset:32
	global_load_dwordx4 v[100:103], v4, s[36:37] offset:48
	s_add_u32 s36, s22, 0x3000000
	s_addc_u32 s37, s23, 0
	global_load_dwordx4 v[104:107], v4, s[36:37]
	global_load_dwordx4 v[108:111], v4, s[36:37] offset:16
	global_load_dwordx4 v[112:115], v4, s[36:37] offset:32
	global_load_dwordx4 v[116:119], v4, s[36:37] offset:48
	s_add_u32 s36, s22, 0x3800000
	s_addc_u32 s37, s23, 0
	global_load_dwordx4 v[120:123], v4, s[36:37]
	global_load_dwordx4 v[124:127], v4, s[36:37] offset:16
	global_load_dwordx4 v[128:131], v4, s[36:37] offset:32
	global_load_dwordx4 v[132:135], v4, s[36:37] offset:48
	s_waitcnt vmcnt(16)
	v_mov_b32_e32 v6, 0x42800000
	v_mov_b32_e32 v7, v6
	v_pk_mul_f32 v[8:9], v[8:9], v[6:7]
	v_pk_mul_f32 v[10:11], v[10:11], v[6:7]
	v_cvt_pk_fp8_f32 v148, v8, v9
	v_cvt_pk_fp8_f32 v148, v10, v11 op_sel:[0,0,1]
	v_pk_mul_f32 v[12:13], v[12:13], v[6:7]
	v_pk_mul_f32 v[14:15], v[14:15], v[6:7]
	v_cvt_pk_fp8_f32 v149, v12, v13
	v_cvt_pk_fp8_f32 v149, v14, v15 op_sel:[0,0,1]
	v_pk_mul_f32 v[16:17], v[16:17], v[6:7]
	v_pk_mul_f32 v[18:19], v[18:19], v[6:7]
	v_cvt_pk_fp8_f32 v150, v16, v17
	v_cvt_pk_fp8_f32 v150, v18, v19 op_sel:[0,0,1]
	v_pk_mul_f32 v[20:21], v[20:21], v[6:7]
	v_pk_mul_f32 v[22:23], v[22:23], v[6:7]
	v_cvt_pk_fp8_f32 v151, v20, v21
	v_cvt_pk_fp8_f32 v151, v22, v23 op_sel:[0,0,1]
	s_add_u32 s38, s16, 0x0
	s_addc_u32 s39, s17, 0
	global_store_dwordx4 v5, v[148:151], s[38:39] sc1
	v_pk_mul_f32 v[24:25], v[24:25], v[6:7]
	v_pk_mul_f32 v[26:27], v[26:27], v[6:7]
	v_cvt_pk_fp8_f32 v152, v24, v25
	v_cvt_pk_fp8_f32 v152, v26, v27 op_sel:[0,0,1]
	v_pk_mul_f32 v[28:29], v[28:29], v[6:7]
	v_pk_mul_f32 v[30:31], v[30:31], v[6:7]
	v_cvt_pk_fp8_f32 v153, v28, v29
	v_cvt_pk_fp8_f32 v153, v30, v31 op_sel:[0,0,1]
	v_pk_mul_f32 v[32:33], v[32:33], v[6:7]
	v_pk_mul_f32 v[34:35], v[34:35], v[6:7]
	v_cvt_pk_fp8_f32 v154, v32, v33
	v_cvt_pk_fp8_f32 v154, v34, v35 op_sel:[0,0,1]
	v_pk_mul_f32 v[36:37], v[36:37], v[6:7]
	v_pk_mul_f32 v[38:39], v[38:39], v[6:7]
	v_cvt_pk_fp8_f32 v155, v36, v37
	v_cvt_pk_fp8_f32 v155, v38, v39 op_sel:[0,0,1]
	s_add_u32 s38, s16, 0x40000
	s_addc_u32 s39, s17, 0
	global_store_dwordx4 v5, v[152:155], s[38:39] sc1
	v_pk_mul_f32 v[40:41], v[40:41], v[6:7]
	v_pk_mul_f32 v[42:43], v[42:43], v[6:7]
	v_cvt_pk_fp8_f32 v156, v40, v41
	v_cvt_pk_fp8_f32 v156, v42, v43 op_sel:[0,0,1]
	v_pk_mul_f32 v[44:45], v[44:45], v[6:7]
	v_pk_mul_f32 v[46:47], v[46:47], v[6:7]
	v_cvt_pk_fp8_f32 v157, v44, v45
	v_cvt_pk_fp8_f32 v157, v46, v47 op_sel:[0,0,1]
	v_pk_mul_f32 v[48:49], v[48:49], v[6:7]
	v_pk_mul_f32 v[50:51], v[50:51], v[6:7]
	v_cvt_pk_fp8_f32 v158, v48, v49
	v_cvt_pk_fp8_f32 v158, v50, v51 op_sel:[0,0,1]
	v_pk_mul_f32 v[52:53], v[52:53], v[6:7]
	v_pk_mul_f32 v[54:55], v[54:55], v[6:7]
	v_cvt_pk_fp8_f32 v159, v52, v53
	v_cvt_pk_fp8_f32 v159, v54, v55 op_sel:[0,0,1]
	s_add_u32 s38, s16, 0x80000
	s_addc_u32 s39, s17, 0
	global_store_dwordx4 v5, v[156:159], s[38:39] sc1
	v_pk_mul_f32 v[56:57], v[56:57], v[6:7]
	v_pk_mul_f32 v[58:59], v[58:59], v[6:7]
	v_cvt_pk_fp8_f32 v160, v56, v57
	v_cvt_pk_fp8_f32 v160, v58, v59 op_sel:[0,0,1]
	v_pk_mul_f32 v[60:61], v[60:61], v[6:7]
	v_pk_mul_f32 v[62:63], v[62:63], v[6:7]
	v_cvt_pk_fp8_f32 v161, v60, v61
	v_cvt_pk_fp8_f32 v161, v62, v63 op_sel:[0,0,1]
	v_pk_mul_f32 v[64:65], v[64:65], v[6:7]
	v_pk_mul_f32 v[66:67], v[66:67], v[6:7]
	v_cvt_pk_fp8_f32 v162, v64, v65
	v_cvt_pk_fp8_f32 v162, v66, v67 op_sel:[0,0,1]
	v_pk_mul_f32 v[68:69], v[68:69], v[6:7]
	v_pk_mul_f32 v[70:71], v[70:71], v[6:7]
	v_cvt_pk_fp8_f32 v163, v68, v69
	v_cvt_pk_fp8_f32 v163, v70, v71 op_sel:[0,0,1]
	s_add_u32 s38, s16, 0xc0000
	s_addc_u32 s39, s17, 0
	global_store_dwordx4 v5, v[160:163], s[38:39] sc1
	s_add_u32 s22, s90, s86
	s_addc_u32 s23, s91, 0
	global_load_dwordx4 v[8:11], v4, s[22:23]
	global_load_dwordx4 v[12:15], v4, s[22:23] offset:16
	global_load_dwordx4 v[16:19], v4, s[22:23] offset:32
	global_load_dwordx4 v[20:23], v4, s[22:23] offset:48
	s_add_u32 s36, s22, 0x800000
	s_addc_u32 s37, s23, 0
	global_load_dwordx4 v[24:27], v4, s[36:37]
	global_load_dwordx4 v[28:31], v4, s[36:37] offset:16
	global_load_dwordx4 v[32:35], v4, s[36:37] offset:32
	global_load_dwordx4 v[36:39], v4, s[36:37] offset:48
	s_add_u32 s36, s22, 0x1000000
	s_addc_u32 s37, s23, 0
	global_load_dwordx4 v[40:43], v4, s[36:37]
	global_load_dwordx4 v[44:47], v4, s[36:37] offset:16
	global_load_dwordx4 v[48:51], v4, s[36:37] offset:32
	global_load_dwordx4 v[52:55], v4, s[36:37] offset:48
	s_add_u32 s36, s22, 0x1800000
	s_addc_u32 s37, s23, 0
	global_load_dwordx4 v[56:59], v4, s[36:37]
	global_load_dwordx4 v[60:63], v4, s[36:37] offset:16
	global_load_dwordx4 v[64:67], v4, s[36:37] offset:32
	global_load_dwordx4 v[68:71], v4, s[36:37] offset:48
	s_waitcnt vmcnt(20)
; DI void phase_tables(const Params& p, int l, int bid, int nblk) {
;     ...
;   for (int e = gtid; e < 2 * 16384 * 64; e += gn) {
;     const int which = e / (16384 * 64), r = e % (16384 * 64);
;     const float sc = which ? V_SCALE : U_SCALE;
;     const float* src = (which ? p.in[I_PV] : p.in[I_PU]) + (size_t)l * 16384 * 1024 + (size_t)r * 16;
;     u32 o[4];
; #pragma unroll
;     for (int q = 0; q < 4; ++q) {
;       const float4 a = *(const float4*)(src + q * 4);
;       int v = __builtin_amdgcn_cvt_pk_fp8_f32(a.x * sc, a.y * sc, 0, false);
;       v = __builtin_amdgcn_cvt_pk_fp8_f32(a.z * sc, a.w * sc, v, true);
;       o[q] = (u32)v;
;     }
;     uint4 ov = {o[0], o[1], o[2], o[3]};
;     *(uint4*)&dst[(size_t)e * 16] = ov;
;   }
	v_mov_b32_e32 v6, 0x42800000
	v_mov_b32_e32 v7, v6
	v_pk_mul_f32 v[72:73], v[72:73], v[6:7]
	v_pk_mul_f32 v[74:75], v[74:75], v[6:7]
	v_cvt_pk_fp8_f32 v176, v72, v73
	v_cvt_pk_fp8_f32 v176, v74, v75 op_sel:[0,0,1]
	v_pk_mul_f32 v[76:77], v[76:77], v[6:7]
	v_pk_mul_f32 v[78:79], v[78:79], v[6:7]
	v_cvt_pk_fp8_f32 v177, v76, v77
	v_cvt_pk_fp8_f32 v177, v78, v79 op_sel:[0,0,1]
	v_pk_mul_f32 v[80:81], v[80:81], v[6:7]
	v_pk_mul_f32 v[82:83], v[82:83], v[6:7]
	v_cvt_pk_fp8_f32 v178, v80, v81
	v_cvt_pk_fp8_f32 v178, v82, v83 op_sel:[0,0,1]
	v_pk_mul_f32 v[84:85], v[84:85], v[6:7]
	v_pk_mul_f32 v[86:87], v[86:87], v[6:7]
	v_cvt_pk_fp8_f32 v179, v84, v85
	v_cvt_pk_fp8_f32 v179, v86, v87 op_sel:[0,0,1]
	s_add_u32 s38, s16, 0x100000
	s_addc_u32 s39, s17, 0
	global_store_dwordx4 v5, v[176:179], s[38:39] sc1
	v_pk_mul_f32 v[88:89], v[88:89], v[6:7]
	v_pk_mul_f32 v[90:91], v[90:91], v[6:7]
	v_cvt_pk_fp8_f32 v180, v88, v89
	v_cvt_pk_fp8_f32 v180, v90, v91 op_sel:[0,0,1]
	v_pk_mul_f32 v[92:93], v[92:93], v[6:7]
	v_pk_mul_f32 v[94:95], v[94:95], v[6:7]
	v_cvt_pk_fp8_f32 v181, v92, v93
	v_cvt_pk_fp8_f32 v181, v94, v95 op_sel:[0,0,1]
	v_pk_mul_f32 v[96:97], v[96:97], v[6:7]
	v_pk_mul_f32 v[98:99], v[98:99], v[6:7]
	v_cvt_pk_fp8_f32 v182, v96, v97
	v_cvt_pk_fp8_f32 v182, v98, v99 op_sel:[0,0,1]
	v_pk_mul_f32 v[100:101], v[100:101], v[6:7]
	v_pk_mul_f32 v[102:103], v[102:103], v[6:7]
	v_cvt_pk_fp8_f32 v183, v100, v101
	v_cvt_pk_fp8_f32 v183, v102, v103 op_sel:[0,0,1]
	s_add_u32 s38, s16, 0x140000
	s_addc_u32 s39, s17, 0
	global_store_dwordx4 v5, v[180:183], s[38:39] sc1
	v_pk_mul_f32 v[104:105], v[104:105], v[6:7]
	v_pk_mul_f32 v[106:107], v[106:107], v[6:7]
	v_cvt_pk_fp8_f32 v184, v104, v105
	v_cvt_pk_fp8_f32 v184, v106, v107 op_sel:[0,0,1]
	v_pk_mul_f32 v[108:109], v[108:109], v[6:7]
	v_pk_mul_f32 v[110:111], v[110:111], v[6:7]
	v_cvt_pk_fp8_f32 v185, v108, v109
	v_cvt_pk_fp8_f32 v185, v110, v111 op_sel:[0,0,1]
	v_pk_mul_f32 v[112:113], v[112:113], v[6:7]
	v_pk_mul_f32 v[114:115], v[114:115], v[6:7]
	v_cvt_pk_fp8_f32 v186, v112, v113
	v_cvt_pk_fp8_f32 v186, v114, v115 op_sel:[0,0,1]
	v_pk_mul_f32 v[116:117], v[116:117], v[6:7]
	v_pk_mul_f32 v[118:119], v[118:119], v[6:7]
	v_cvt_pk_fp8_f32 v187, v116, v117
	v_cvt_pk_fp8_f32 v187, v118, v119 op_sel:[0,0,1]
	s_add_u32 s38, s16, 0x180000
	s_addc_u32 s39, s17, 0
	global_store_dwordx4 v5, v[184:187], s[38:39] sc1
	v_pk_mul_f32 v[120:121], v[120:121], v[6:7]
	v_pk_mul_f32 v[122:123], v[122:123], v[6:7]
	v_cvt_pk_fp8_f32 v188, v120, v121
	v_cvt_pk_fp8_f32 v188, v122, v123 op_sel:[0,0,1]
	v_pk_mul_f32 v[124:125], v[124:125], v[6:7]
	v_pk_mul_f32 v[126:127], v[126:127], v[6:7]
	v_cvt_pk_fp8_f32 v189, v124, v125
	v_cvt_pk_fp8_f32 v189, v126, v127 op_sel:[0,0,1]
	v_pk_mul_f32 v[128:129], v[128:129], v[6:7]
	v_pk_mul_f32 v[130:131], v[130:131], v[6:7]
	v_cvt_pk_fp8_f32 v190, v128, v129
	v_cvt_pk_fp8_f32 v190, v130, v131 op_sel:[0,0,1]
	v_pk_mul_f32 v[132:133], v[132:133], v[6:7]
	v_pk_mul_f32 v[134:135], v[134:135], v[6:7]
	v_cvt_pk_fp8_f32 v191, v132, v133
	v_cvt_pk_fp8_f32 v191, v134, v135 op_sel:[0,0,1]
	s_add_u32 s38, s16, 0x1c0000
	s_addc_u32 s39, s17, 0
	global_store_dwordx4 v5, v[188:191], s[38:39] sc1
	s_add_u32 s36, s22, 0x2000000
	s_addc_u32 s37, s23, 0
	global_load_dwordx4 v[72:75], v4, s[36:37]
	global_load_dwordx4 v[76:79], v4, s[36:37] offset:16
	global_load_dwordx4 v[80:83], v4, s[36:37] offset:32
	global_load_dwordx4 v[84:87], v4, s[36:37] offset:48
	s_add_u32 s36, s22, 0x2800000
	s_addc_u32 s37, s23, 0
	global_load_dwordx4 v[88:91], v4, s[36:37]
	global_load_dwordx4 v[92:95], v4, s[36:37] offset:16
	global_load_dwordx4 v[96:99], v4, s[36:37] offset:32
	global_load_dwordx4 v[100:103], v4, s[36:37] offset:48
	s_add_u32 s36, s22, 0x3000000
	s_addc_u32 s37, s23, 0
	global_load_dwordx4 v[104:107], v4, s[36:37]
	global_load_dwordx4 v[108:111], v4, s[36:37] offset:16
	global_load_dwordx4 v[112:115], v4, s[36:37] offset:32
	global_load_dwordx4 v[116:119], v4, s[36:37] offset:48
	s_add_u32 s36, s22, 0x3800000
	s_addc_u32 s37, s23, 0
	global_load_dwordx4 v[120:123], v4, s[36:37]
	global_load_dwordx4 v[124:127], v4, s[36:37] offset:16
	global_load_dwordx4 v[128:131], v4, s[36:37] offset:32
	global_load_dwordx4 v[132:135], v4, s[36:37] offset:48
	s_waitcnt vmcnt(20)
; DI void phase_tables(const Params& p, int l, int bid, int nblk) {
;     ...
;   for (int e = gtid; e < 2 * 16384 * 64; e += gn) {
;     const int which = e / (16384 * 64), r = e % (16384 * 64);
;     const float sc = which ? V_SCALE : U_SCALE;
;     const float* src = (which ? p.in[I_PV] : p.in[I_PU]) + (size_t)l * 16384 * 1024 + (size_t)r * 16;
;     u32 o[4];
; #pragma unroll
;     for (int q = 0; q < 4; ++q) {
;       const float4 a = *(const float4*)(src + q * 4);
;       int v = __builtin_amdgcn_cvt_pk_fp8_f32(a.x * sc, a.y * sc, 0, false);
;       v = __builtin_amdgcn_cvt_pk_fp8_f32(a.z * sc, a.w * sc, v, true);
;       o[q] = (u32)v;
;     }
;     uint4 ov = {o[0], o[1], o[2], o[3]};
;     *(uint4*)&dst[(size_t)e * 16] = ov;
;   }
	v_mov_b32_e32 v6, 4.0
	v_mov_b32_e32 v7, v6
	v_pk_mul_f32 v[8:9], v[8:9], v[6:7]
	v_pk_mul_f32 v[10:11], v[10:11], v[6:7]
	v_cvt_pk_fp8_f32 v148, v8, v9
	v_cvt_pk_fp8_f32 v148, v10, v11 op_sel:[0,0,1]
	v_pk_mul_f32 v[12:13], v[12:13], v[6:7]
	v_pk_mul_f32 v[14:15], v[14:15], v[6:7]
	v_cvt_pk_fp8_f32 v149, v12, v13
	v_cvt_pk_fp8_f32 v149, v14, v15 op_sel:[0,0,1]
	v_pk_mul_f32 v[16:17], v[16:17], v[6:7]
	v_pk_mul_f32 v[18:19], v[18:19], v[6:7]
	v_cvt_pk_fp8_f32 v150, v16, v17
	v_cvt_pk_fp8_f32 v150, v18, v19 op_sel:[0,0,1]
	v_pk_mul_f32 v[20:21], v[20:21], v[6:7]
	v_pk_mul_f32 v[22:23], v[22:23], v[6:7]
	v_cvt_pk_fp8_f32 v151, v20, v21
	v_cvt_pk_fp8_f32 v151, v22, v23 op_sel:[0,0,1]
	s_add_u32 s38, s16, 0x1000000
	s_addc_u32 s39, s17, 0
	global_store_dwordx4 v5, v[148:151], s[38:39] sc1
	v_pk_mul_f32 v[24:25], v[24:25], v[6:7]
	v_pk_mul_f32 v[26:27], v[26:27], v[6:7]
	v_cvt_pk_fp8_f32 v152, v24, v25
	v_cvt_pk_fp8_f32 v152, v26, v27 op_sel:[0,0,1]
	v_pk_mul_f32 v[28:29], v[28:29], v[6:7]
	v_pk_mul_f32 v[30:31], v[30:31], v[6:7]
	v_cvt_pk_fp8_f32 v153, v28, v29
	v_cvt_pk_fp8_f32 v153, v30, v31 op_sel:[0,0,1]
	v_pk_mul_f32 v[32:33], v[32:33], v[6:7]
	v_pk_mul_f32 v[34:35], v[34:35], v[6:7]
	v_cvt_pk_fp8_f32 v154, v32, v33
	v_cvt_pk_fp8_f32 v154, v34, v35 op_sel:[0,0,1]
	v_pk_mul_f32 v[36:37], v[36:37], v[6:7]
	v_pk_mul_f32 v[38:39], v[38:39], v[6:7]
	v_cvt_pk_fp8_f32 v155, v36, v37
	v_cvt_pk_fp8_f32 v155, v38, v39 op_sel:[0,0,1]
	s_add_u32 s38, s16, 0x1040000
	s_addc_u32 s39, s17, 0
	global_store_dwordx4 v5, v[152:155], s[38:39] sc1
	v_pk_mul_f32 v[40:41], v[40:41], v[6:7]
	v_pk_mul_f32 v[42:43], v[42:43], v[6:7]
	v_cvt_pk_fp8_f32 v156, v40, v41
	v_cvt_pk_fp8_f32 v156, v42, v43 op_sel:[0,0,1]
	v_pk_mul_f32 v[44:45], v[44:45], v[6:7]
	v_pk_mul_f32 v[46:47], v[46:47], v[6:7]
	v_cvt_pk_fp8_f32 v157, v44, v45
	v_cvt_pk_fp8_f32 v157, v46, v47 op_sel:[0,0,1]
	v_pk_mul_f32 v[48:49], v[48:49], v[6:7]
	v_pk_mul_f32 v[50:51], v[50:51], v[6:7]
	v_cvt_pk_fp8_f32 v158, v48, v49
	v_cvt_pk_fp8_f32 v158, v50, v51 op_sel:[0,0,1]
	v_pk_mul_f32 v[52:53], v[52:53], v[6:7]
	v_pk_mul_f32 v[54:55], v[54:55], v[6:7]
	v_cvt_pk_fp8_f32 v159, v52, v53
	v_cvt_pk_fp8_f32 v159, v54, v55 op_sel:[0,0,1]
	s_add_u32 s38, s16, 0x1080000
	s_addc_u32 s39, s17, 0
	global_store_dwordx4 v5, v[156:159], s[38:39] sc1
	v_pk_mul_f32 v[56:57], v[56:57], v[6:7]
	v_pk_mul_f32 v[58:59], v[58:59], v[6:7]
	v_cvt_pk_fp8_f32 v160, v56, v57
	v_cvt_pk_fp8_f32 v160, v58, v59 op_sel:[0,0,1]
	v_pk_mul_f32 v[60:61], v[60:61], v[6:7]
	v_pk_mul_f32 v[62:63], v[62:63], v[6:7]
	v_cvt_pk_fp8_f32 v161, v60, v61
	v_cvt_pk_fp8_f32 v161, v62, v63 op_sel:[0,0,1]
	v_pk_mul_f32 v[64:65], v[64:65], v[6:7]
	v_pk_mul_f32 v[66:67], v[66:67], v[6:7]
	v_cvt_pk_fp8_f32 v162, v64, v65
	v_cvt_pk_fp8_f32 v162, v66, v67 op_sel:[0,0,1]
	v_pk_mul_f32 v[68:69], v[68:69], v[6:7]
	v_pk_mul_f32 v[70:71], v[70:71], v[6:7]
	v_cvt_pk_fp8_f32 v163, v68, v69
	v_cvt_pk_fp8_f32 v163, v70, v71 op_sel:[0,0,1]
	s_add_u32 s38, s16, 0x10c0000
	s_addc_u32 s39, s17, 0
	global_store_dwordx4 v5, v[160:163], s[38:39] sc1
	s_waitcnt vmcnt(4)
	v_mov_b32_e32 v6, 4.0
	v_mov_b32_e32 v7, v6
	v_pk_mul_f32 v[72:73], v[72:73], v[6:7]
	v_pk_mul_f32 v[74:75], v[74:75], v[6:7]
	v_cvt_pk_fp8_f32 v176, v72, v73
	v_cvt_pk_fp8_f32 v176, v74, v75 op_sel:[0,0,1]
	v_pk_mul_f32 v[76:77], v[76:77], v[6:7]
	v_pk_mul_f32 v[78:79], v[78:79], v[6:7]
	v_cvt_pk_fp8_f32 v177, v76, v77
	v_cvt_pk_fp8_f32 v177, v78, v79 op_sel:[0,0,1]
	v_pk_mul_f32 v[80:81], v[80:81], v[6:7]
	v_pk_mul_f32 v[82:83], v[82:83], v[6:7]
	v_cvt_pk_fp8_f32 v178, v80, v81
	v_cvt_pk_fp8_f32 v178, v82, v83 op_sel:[0,0,1]
	v_pk_mul_f32 v[84:85], v[84:85], v[6:7]
	v_pk_mul_f32 v[86:87], v[86:87], v[6:7]
	v_cvt_pk_fp8_f32 v179, v84, v85
	v_cvt_pk_fp8_f32 v179, v86, v87 op_sel:[0,0,1]
	s_add_u32 s38, s16, 0x1100000
	s_addc_u32 s39, s17, 0
	global_store_dwordx4 v5, v[176:179], s[38:39] sc1
	v_pk_mul_f32 v[88:89], v[88:89], v[6:7]
	v_pk_mul_f32 v[90:91], v[90:91], v[6:7]
	v_cvt_pk_fp8_f32 v180, v88, v89
	v_cvt_pk_fp8_f32 v180, v90, v91 op_sel:[0,0,1]
	v_pk_mul_f32 v[92:93], v[92:93], v[6:7]
	v_pk_mul_f32 v[94:95], v[94:95], v[6:7]
	v_cvt_pk_fp8_f32 v181, v92, v93
	v_cvt_pk_fp8_f32 v181, v94, v95 op_sel:[0,0,1]
	v_pk_mul_f32 v[96:97], v[96:97], v[6:7]
	v_pk_mul_f32 v[98:99], v[98:99], v[6:7]
	v_cvt_pk_fp8_f32 v182, v96, v97
	v_cvt_pk_fp8_f32 v182, v98, v99 op_sel:[0,0,1]
	v_pk_mul_f32 v[100:101], v[100:101], v[6:7]
	v_pk_mul_f32 v[102:103], v[102:103], v[6:7]
	v_cvt_pk_fp8_f32 v183, v100, v101
	v_cvt_pk_fp8_f32 v183, v102, v103 op_sel:[0,0,1]
	s_add_u32 s38, s16, 0x1140000
	s_addc_u32 s39, s17, 0
	global_store_dwordx4 v5, v[180:183], s[38:39] sc1
	v_pk_mul_f32 v[104:105], v[104:105], v[6:7]
	v_pk_mul_f32 v[106:107], v[106:107], v[6:7]
	v_cvt_pk_fp8_f32 v184, v104, v105
	v_cvt_pk_fp8_f32 v184, v106, v107 op_sel:[0,0,1]
	v_pk_mul_f32 v[108:109], v[108:109], v[6:7]
	v_pk_mul_f32 v[110:111], v[110:111], v[6:7]
	v_cvt_pk_fp8_f32 v185, v108, v109
	v_cvt_pk_fp8_f32 v185, v110, v111 op_sel:[0,0,1]
	v_pk_mul_f32 v[112:113], v[112:113], v[6:7]
	v_pk_mul_f32 v[114:115], v[114:115], v[6:7]
	v_cvt_pk_fp8_f32 v186, v112, v113
	v_cvt_pk_fp8_f32 v186, v114, v115 op_sel:[0,0,1]
	v_pk_mul_f32 v[116:117], v[116:117], v[6:7]
	v_pk_mul_f32 v[118:119], v[118:119], v[6:7]
	v_cvt_pk_fp8_f32 v187, v116, v117
	v_cvt_pk_fp8_f32 v187, v118, v119 op_sel:[0,0,1]
	s_add_u32 s38, s16, 0x1180000
	s_addc_u32 s39, s17, 0
	global_store_dwordx4 v5, v[184:187], s[38:39] sc1
	v_pk_mul_f32 v[120:121], v[120:121], v[6:7]
	v_pk_mul_f32 v[122:123], v[122:123], v[6:7]
	v_cvt_pk_fp8_f32 v188, v120, v121
	v_cvt_pk_fp8_f32 v188, v122, v123 op_sel:[0,0,1]
	v_pk_mul_f32 v[124:125], v[124:125], v[6:7]
	v_pk_mul_f32 v[126:127], v[126:127], v[6:7]
	v_cvt_pk_fp8_f32 v189, v124, v125
	v_cvt_pk_fp8_f32 v189, v126, v127 op_sel:[0,0,1]
	v_pk_mul_f32 v[128:129], v[128:129], v[6:7]
	v_pk_mul_f32 v[130:131], v[130:131], v[6:7]
	v_cvt_pk_fp8_f32 v190, v128, v129
	v_cvt_pk_fp8_f32 v190, v130, v131 op_sel:[0,0,1]
	v_pk_mul_f32 v[132:133], v[132:133], v[6:7]
	v_pk_mul_f32 v[134:135], v[134:135], v[6:7]
	v_cvt_pk_fp8_f32 v191, v132, v133
	v_cvt_pk_fp8_f32 v191, v134, v135 op_sel:[0,0,1]
	s_add_u32 s38, s16, 0x11c0000
	s_addc_u32 s39, s17, 0
	global_store_dwordx4 v5, v[188:191], s[38:39] sc1

; template <bool SWAP, int MI, class AF, class BF, class EF>
; DI void gemm_tile(const AF& af, const BF& bfn, const EF& ef, int m0, int n0, int K, char* smem) {
;     ...
;   for (int kt = 0; kt < nk; ++kt) {
;     const int cur = kt & 1;
;     const u16* Ab = As + cur * AROWS * 40;
;     const u16* Bb = Bs + cur * 128 * 40;
; #pragma unroll
;     for (int ks = 0; ks < 2; ++ks) {
;       bf16x8 a[MI], b[2];
; #pragma unroll
;       for (int i = 0; i < MI; ++i) a[i] = *(const bf16x8*)&Ab[(wm * (MI * 32) + i * 32 + l32) * 40 + ks * 16 + h * 8];
; #pragma unroll
;       for (int i = 0; i < 2; ++i) b[i] = *(const bf16x8*)&Bb[(wn * 64 + i * 32 + l32) * 40 + ks * 16 + h * 8];
; #pragma unroll
;       for (int i = 0; i < MI; ++i)
; #pragma unroll
;         for (int j = 0; j < 2; ++j)
;           acc[i][j] = SWAP ? __builtin_amdgcn_mfma_f32_32x32x16_bf16(b[j], a[i], acc[i][j], 0, 0, 0)
;                            : __builtin_amdgcn_mfma_f32_32x32x16_bf16(a[i], b[j], acc[i][j], 0, 0, 0);
;     }
;     {
;       u16* An = As + (cur ^ 1) * AROWS * 40;
;       u16* Bn = Bs + (cur ^ 1) * 128 * 40;
; #pragma unroll
;       for (int i = 0; i < MI; ++i) *(u32x4*)&An[(lrow + 64 * i) * 40 + lk] = ra[i];
; #pragma unroll
;       for (int i = 0; i < 2; ++i) *(u32x4*)&Bn[(lrow + 64 * i) * 40 + lk] = rb[i];
;       const int kn = (kt + 2 < nk) ? kt + 2 : nk - 1;
;       const int k0 = kn * 32 + lk;
; #pragma unroll
;       for (int i = 0; i < MI; ++i) ra[i] = *(const u32x4*)af(m0 + lrow + 64 * i, k0);
; #pragma unroll
;       for (int i = 0; i < 2; ++i) rb[i] = *(const u32x4*)bfn(n0 + lrow + 64 * i, k0);
;     }
;     __syncthreads();
;   }
.Lgemm_q_loop:
	ds_read_b128 v[232:235], v207 offset:40992
	ds_read_b128 v[236:239], v207 offset:43552
	ds_read_b128 v[220:223], v206 offset:32
	ds_read_b128 v[240:243], v206 offset:2592
	ds_read_b128 v[244:247], v206 offset:5152
	ds_read_b128 v[248:251], v206 offset:7712
	s_waitcnt lgkmcnt(9)
	v_mfma_f32_32x32x16_bf16 v[112:127], v[196:199], v[180:183], v[112:127]
	v_mfma_f32_32x32x16_bf16 v[96:111], v[228:231], v[180:183], v[96:111]
	s_waitcnt lgkmcnt(8)
	v_mfma_f32_32x32x16_bf16 v[80:95], v[196:199], v[184:187], v[80:95]
	v_mfma_f32_32x32x16_bf16 v[64:79], v[228:231], v[184:187], v[64:79]
	ds_write_b128 v202, v[152:155] offset:20480
	ds_write_b128 v202, v[156:159] offset:25600
	ds_write_b128 v202, v[160:163] offset:30720
	ds_write_b128 v202, v[164:167] offset:35840
	ds_write_b128 v202, v[168:171] offset:51200
	ds_write_b128 v202, v[176:179] offset:56320
	v_add_u32_e32 v201, s64, v200
	global_load_dwordx4 v[128:131], v201, s[36:37]
	global_load_dwordx4 v[152:155], v201, s[36:37] offset:64
	global_load_dwordx4 v[132:135], v201, s[38:39]
	global_load_dwordx4 v[156:159], v201, s[38:39] offset:64
	global_load_dwordx4 v[136:139], v201, s[42:43]
	global_load_dwordx4 v[160:163], v201, s[42:43] offset:64
	global_load_dwordx4 v[140:143], v201, s[46:47]
	global_load_dwordx4 v[164:167], v201, s[46:47] offset:64
	global_load_dwordx4 v[144:147], v201, s[48:49]
	global_load_dwordx4 v[168:171], v201, s[48:49] offset:64
	global_load_dwordx4 v[148:151], v201, s[50:51]
	global_load_dwordx4 v[176:179], v201, s[50:51] offset:64
	s_add_i32 s64, s64, 0x80
	s_min_u32 s64, s64, 0x780
	s_waitcnt lgkmcnt(13)
	v_mfma_f32_32x32x16_bf16 v[48:63], v[196:199], v[188:191], v[48:63]
	v_mfma_f32_32x32x16_bf16 v[32:47], v[228:231], v[188:191], v[32:47]
	s_waitcnt lgkmcnt(12)
	v_mfma_f32_32x32x16_bf16 v[16:31], v[196:199], v[192:195], v[16:31]
	v_mfma_f32_32x32x16_bf16 v[0:15], v[228:231], v[192:195], v[0:15]
	s_waitcnt lgkmcnt(0)
	s_barrier
	ds_read_b128 v[196:199], v207 offset:51200
	ds_read_b128 v[228:231], v207 offset:53760
	ds_read_b128 v[180:183], v206 offset:20480
	ds_read_b128 v[184:187], v206 offset:23040
	ds_read_b128 v[188:191], v206 offset:25600
	ds_read_b128 v[192:195], v206 offset:28160
	v_mfma_f32_32x32x16_bf16 v[112:127], v[232:235], v[220:223], v[112:127]
	v_mfma_f32_32x32x16_bf16 v[96:111], v[236:239], v[220:223], v[96:111]
	v_mfma_f32_32x32x16_bf16 v[80:95], v[232:235], v[240:243], v[80:95]
	v_mfma_f32_32x32x16_bf16 v[64:79], v[236:239], v[240:243], v[64:79]
	v_mfma_f32_32x32x16_bf16 v[48:63], v[232:235], v[244:247], v[48:63]
	v_mfma_f32_32x32x16_bf16 v[32:47], v[236:239], v[244:247], v[32:47]
	v_mfma_f32_32x32x16_bf16 v[16:31], v[232:235], v[248:251], v[16:31]
	v_mfma_f32_32x32x16_bf16 v[0:15], v[236:239], v[248:251], v[0:15]
	ds_read_b128 v[232:235], v207 offset:51232
	ds_read_b128 v[236:239], v207 offset:53792
	ds_read_b128 v[220:223], v206 offset:20512
	ds_read_b128 v[240:243], v206 offset:23072
	ds_read_b128 v[244:247], v206 offset:25632
	ds_read_b128 v[248:251], v206 offset:28192
	s_waitcnt lgkmcnt(9)
	v_mfma_f32_32x32x16_bf16 v[112:127], v[196:199], v[180:183], v[112:127]
	v_mfma_f32_32x32x16_bf16 v[96:111], v[228:231], v[180:183], v[96:111]
	s_waitcnt lgkmcnt(8)
	v_mfma_f32_32x32x16_bf16 v[80:95], v[196:199], v[184:187], v[80:95]
	v_mfma_f32_32x32x16_bf16 v[64:79], v[228:231], v[184:187], v[64:79]
	s_waitcnt vmcnt(0)
	ds_write_b128 v202, v[128:131] offset:0
	ds_write_b128 v202, v[132:135] offset:5120
	ds_write_b128 v202, v[136:139] offset:10240
	ds_write_b128 v202, v[140:143] offset:15360
	ds_write_b128 v202, v[144:147] offset:40960
	ds_write_b128 v202, v[148:151] offset:46080
	s_waitcnt lgkmcnt(13)
	v_mfma_f32_32x32x16_bf16 v[48:63], v[196:199], v[188:191], v[48:63]
	v_mfma_f32_32x32x16_bf16 v[32:47], v[228:231], v[188:191], v[32:47]
	s_waitcnt lgkmcnt(12)
	v_mfma_f32_32x32x16_bf16 v[16:31], v[196:199], v[192:195], v[16:31]
	v_mfma_f32_32x32x16_bf16 v[0:15], v[228:231], v[192:195], v[0:15]
	s_waitcnt lgkmcnt(0)
	s_barrier
	ds_read_b128 v[196:199], v207 offset:40960
	ds_read_b128 v[228:231], v207 offset:43520
	ds_read_b128 v[180:183], v206 offset:0
	ds_read_b128 v[184:187], v206 offset:2560
	ds_read_b128 v[188:191], v206 offset:5120
	ds_read_b128 v[192:195], v206 offset:7680
	v_mfma_f32_32x32x16_bf16 v[112:127], v[232:235], v[220:223], v[112:127]
	v_mfma_f32_32x32x16_bf16 v[96:111], v[236:239], v[220:223], v[96:111]
	v_mfma_f32_32x32x16_bf16 v[80:95], v[232:235], v[240:243], v[80:95]
	v_mfma_f32_32x32x16_bf16 v[64:79], v[236:239], v[240:243], v[64:79]
	v_mfma_f32_32x32x16_bf16 v[48:63], v[232:235], v[244:247], v[48:63]
	v_mfma_f32_32x32x16_bf16 v[32:47], v[236:239], v[244:247], v[32:47]
	v_mfma_f32_32x32x16_bf16 v[16:31], v[232:235], v[248:251], v[16:31]
	v_mfma_f32_32x32x16_bf16 v[0:15], v[236:239], v[248:251], v[0:15]
	s_add_i32 s65, s65, -1
	s_cmp_lg_u32 s65, 0
	s_cbranch_scc1 .Lgemm_q_loop
; DI u32 pack2(float a, float b) { return (u32)f2bf(a) | ((u32)f2bf(b) << 16); }
; template <bool SWAP, int MI, class AF, class BF, class EF>
; DI void gemm_tile(const AF& af, const BF& bfn, const EF& ef, int m0, int n0, int K, char* smem) {
;     ...
; #pragma unroll
;   for (int i = 0; i < MI; ++i)
; #pragma unroll
;     for (int j = 0; j < 2; ++j)
; #pragma unroll
;       for (int rg = 0; rg < 4; ++rg) {
;         const int m = SWAP ? (m0 + wm * (MI * 32) + i * 32 + l32) : (m0 + wm * (MI * 32) + i * 32 + rg * 8 + h * 4);
;         const int n = SWAP ? (n0 + wn * 64 + j * 32 + rg * 8 + h * 4) : (n0 + wn * 64 + j * 32 + l32);
;         ef(m, n, acc[i][j][rg * 4 + 0], acc[i][j][rg * 4 + 1], acc[i][j][rg * 4 + 2], acc[i][j][rg * 4 + 3]);
;       }
; DI void phase_q(const Params& p, int l, int bid, int nblk, char* smem) {
;     ...
;   auto ef = [=](int m, int n, float v0, float v1, float v2, float v3) {
;     const uint2 o = {pack2(v0, v1), pack2(v2, v3)};
;     *(uint2*)&Q[(size_t)m * 2048 + n] = o;
;   };
	s_waitcnt lgkmcnt(0)
	s_waitcnt vmcnt(0)
	v_and_b32_e32 v128, 31, v218
	v_lshrrev_b32_e32 v129, 7, v218
	v_bfe_u32 v130, v218, 5, 1
	v_bfe_u32 v131, v218, 6, 1
	v_lshl_add_u32 v128, v129, 7, v128
	v_mul_u32_u24_e32 v128, 272, v128
	v_lshlrev_b32_e32 v131, 7, v131
	v_lshl_add_u32 v131, v130, 3, v131
	v_add_u32_e32 v128, v128, v131
	s_nop 7
	v_cvt_pk_bf16_f32 v112, v112, v113
	v_cvt_pk_bf16_f32 v113, v114, v115
	v_cvt_pk_bf16_f32 v116, v116, v117
	v_cvt_pk_bf16_f32 v117, v118, v119
	v_cvt_pk_bf16_f32 v120, v120, v121
	v_cvt_pk_bf16_f32 v121, v122, v123
	v_cvt_pk_bf16_f32 v124, v124, v125
	v_cvt_pk_bf16_f32 v125, v126, v127
	ds_write_b64 v128, v[112:113] offset:0
	ds_write_b64 v128, v[116:117] offset:16
	ds_write_b64 v128, v[120:121] offset:32
	ds_write_b64 v128, v[124:125] offset:48
	v_cvt_pk_bf16_f32 v96, v96, v97
	v_cvt_pk_bf16_f32 v97, v98, v99
	v_cvt_pk_bf16_f32 v100, v100, v101
	v_cvt_pk_bf16_f32 v101, v102, v103
	v_cvt_pk_bf16_f32 v104, v104, v105
	v_cvt_pk_bf16_f32 v105, v106, v107
	v_cvt_pk_bf16_f32 v108, v108, v109
	v_cvt_pk_bf16_f32 v109, v110, v111
	ds_write_b64 v128, v[96:97] offset:64
	ds_write_b64 v128, v[100:101] offset:80
	ds_write_b64 v128, v[104:105] offset:96
	ds_write_b64 v128, v[108:109] offset:112
	v_cvt_pk_bf16_f32 v80, v80, v81
	v_cvt_pk_bf16_f32 v81, v82, v83
	v_cvt_pk_bf16_f32 v84, v84, v85
	v_cvt_pk_bf16_f32 v85, v86, v87
	v_cvt_pk_bf16_f32 v88, v88, v89
	v_cvt_pk_bf16_f32 v89, v90, v91
	v_cvt_pk_bf16_f32 v92, v92, v93
	v_cvt_pk_bf16_f32 v93, v94, v95
	ds_write_b64 v128, v[80:81] offset:8704
	ds_write_b64 v128, v[84:85] offset:8720
	ds_write_b64 v128, v[88:89] offset:8736
	ds_write_b64 v128, v[92:93] offset:8752
	v_cvt_pk_bf16_f32 v64, v64, v65
	v_cvt_pk_bf16_f32 v65, v66, v67
	v_cvt_pk_bf16_f32 v68, v68, v69
	v_cvt_pk_bf16_f32 v69, v70, v71
	v_cvt_pk_bf16_f32 v72, v72, v73
	v_cvt_pk_bf16_f32 v73, v74, v75
	v_cvt_pk_bf16_f32 v76, v76, v77
	v_cvt_pk_bf16_f32 v77, v78, v79
	ds_write_b64 v128, v[64:65] offset:8768
	ds_write_b64 v128, v[68:69] offset:8784
	ds_write_b64 v128, v[72:73] offset:8800
	ds_write_b64 v128, v[76:77] offset:8816
	v_cvt_pk_bf16_f32 v48, v48, v49
	v_cvt_pk_bf16_f32 v49, v50, v51
	v_cvt_pk_bf16_f32 v52, v52, v53
	v_cvt_pk_bf16_f32 v53, v54, v55
	v_cvt_pk_bf16_f32 v56, v56, v57
	v_cvt_pk_bf16_f32 v57, v58, v59
	v_cvt_pk_bf16_f32 v60, v60, v61
	v_cvt_pk_bf16_f32 v61, v62, v63
	ds_write_b64 v128, v[48:49] offset:17408
	ds_write_b64 v128, v[52:53] offset:17424
	ds_write_b64 v128, v[56:57] offset:17440
	ds_write_b64 v128, v[60:61] offset:17456
	v_cvt_pk_bf16_f32 v32, v32, v33
	v_cvt_pk_bf16_f32 v33, v34, v35
	v_cvt_pk_bf16_f32 v36, v36, v37
	v_cvt_pk_bf16_f32 v37, v38, v39
	v_cvt_pk_bf16_f32 v40, v40, v41
	v_cvt_pk_bf16_f32 v41, v42, v43
	v_cvt_pk_bf16_f32 v44, v44, v45
	v_cvt_pk_bf16_f32 v45, v46, v47
	ds_write_b64 v128, v[32:33] offset:17472
	ds_write_b64 v128, v[36:37] offset:17488
	ds_write_b64 v128, v[40:41] offset:17504
	ds_write_b64 v128, v[44:45] offset:17520
	v_cvt_pk_bf16_f32 v16, v16, v17
	v_cvt_pk_bf16_f32 v17, v18, v19
	v_cvt_pk_bf16_f32 v20, v20, v21
	v_cvt_pk_bf16_f32 v21, v22, v23
	v_cvt_pk_bf16_f32 v24, v24, v25
	v_cvt_pk_bf16_f32 v25, v26, v27
	v_cvt_pk_bf16_f32 v28, v28, v29
	v_cvt_pk_bf16_f32 v29, v30, v31
	ds_write_b64 v128, v[16:17] offset:26112
	ds_write_b64 v128, v[20:21] offset:26128
	ds_write_b64 v128, v[24:25] offset:26144
	ds_write_b64 v128, v[28:29] offset:26160
	v_cvt_pk_bf16_f32 v0, v0, v1
	v_cvt_pk_bf16_f32 v1, v2, v3
	v_cvt_pk_bf16_f32 v4, v4, v5
	v_cvt_pk_bf16_f32 v5, v6, v7
	v_cvt_pk_bf16_f32 v8, v8, v9
	v_cvt_pk_bf16_f32 v9, v10, v11
	v_cvt_pk_bf16_f32 v12, v12, v13
	v_cvt_pk_bf16_f32 v13, v14, v15
	ds_write_b64 v128, v[0:1] offset:26176
	ds_write_b64 v128, v[4:5] offset:26192
	ds_write_b64 v128, v[8:9] offset:26208
	ds_write_b64 v128, v[12:13] offset:26224
	s_lshl_b32 s16, s78, 12
	s_lshl_b32 s17, s79, 1
	s_add_u32 s16, s16, s17
	s_add_u32 s16, s96, s16
	s_addc_u32 s17, s97, 0
	s_movk_i32 s38, 0x1000
	s_mov_b32 s39, 0x10000
	v_lshrrev_b32_e32 v129, 4, v218
	v_and_b32_e32 v130, 15, v218
	v_mul_u32_u24_e32 v131, 272, v129
	v_mul_lo_u32 v132, v129, s38
	v_lshl_add_u32 v131, v130, 4, v131
	v_lshl_add_u32 v132, v130, 4, v132
	s_waitcnt lgkmcnt(0)
	s_barrier
	ds_read_b128 v[0:3], v131 offset:0
	ds_read_b128 v[4:7], v131 offset:4352
	ds_read_b128 v[8:11], v131 offset:8704
	ds_read_b128 v[12:15], v131 offset:13056
	ds_read_b128 v[16:19], v131 offset:17408
	ds_read_b128 v[20:23], v131 offset:21760
	ds_read_b128 v[24:27], v131 offset:26112
	ds_read_b128 v[28:31], v131 offset:30464
	ds_read_b128 v[32:35], v131 offset:34816
	ds_read_b128 v[36:39], v131 offset:39168
	ds_read_b128 v[40:43], v131 offset:43520
	ds_read_b128 v[44:47], v131 offset:47872
	ds_read_b128 v[48:51], v131 offset:52224
	ds_read_b128 v[52:55], v131 offset:56576
	ds_read_b128 v[56:59], v131 offset:60928
	ds_read_b128 v[60:63], v131 offset:65280
	s_waitcnt lgkmcnt(15)
	global_store_dwordx4 v132, v[0:3], s[16:17] sc1
	s_add_u32 s16, s16, s39
	s_addc_u32 s17, s17, 0
	s_waitcnt lgkmcnt(14)
	global_store_dwordx4 v132, v[4:7], s[16:17] sc1
	s_add_u32 s16, s16, s39
	s_addc_u32 s17, s17, 0
	s_waitcnt lgkmcnt(13)
	global_store_dwordx4 v132, v[8:11], s[16:17] sc1
	s_add_u32 s16, s16, s39
	s_addc_u32 s17, s17, 0
	s_waitcnt lgkmcnt(12)
	global_store_dwordx4 v132, v[12:15], s[16:17] sc1
	s_add_u32 s16, s16, s39
	s_addc_u32 s17, s17, 0
	s_waitcnt lgkmcnt(11)
	global_store_dwordx4 v132, v[16:19], s[16:17] sc1
	s_add_u32 s16, s16, s39
	s_addc_u32 s17, s17, 0
	s_waitcnt lgkmcnt(10)
	global_store_dwordx4 v132, v[20:23], s[16:17] sc1
	s_add_u32 s16, s16, s39
	s_addc_u32 s17, s17, 0
	s_waitcnt lgkmcnt(9)
	global_store_dwordx4 v132, v[24:27], s[16:17] sc1
	s_add_u32 s16, s16, s39
	s_addc_u32 s17, s17, 0
	s_waitcnt lgkmcnt(8)
	global_store_dwordx4 v132, v[28:31], s[16:17] sc1
	s_add_u32 s16, s16, s39
	s_addc_u32 s17, s17, 0
	s_waitcnt lgkmcnt(7)
	global_store_dwordx4 v132, v[32:35], s[16:17] sc1
	s_add_u32 s16, s16, s39
	s_addc_u32 s17, s17, 0
	s_waitcnt lgkmcnt(6)
	global_store_dwordx4 v132, v[36:39], s[16:17] sc1
	s_add_u32 s16, s16, s39
	s_addc_u32 s17, s17, 0
	s_waitcnt lgkmcnt(5)
	global_store_dwordx4 v132, v[40:43], s[16:17] sc1
	s_add_u32 s16, s16, s39
	s_addc_u32 s17, s17, 0
	s_waitcnt lgkmcnt(4)
	global_store_dwordx4 v132, v[44:47], s[16:17] sc1
	s_add_u32 s16, s16, s39
	s_addc_u32 s17, s17, 0
	s_waitcnt lgkmcnt(3)
	global_store_dwordx4 v132, v[48:51], s[16:17] sc1
	s_add_u32 s16, s16, s39
	s_addc_u32 s17, s17, 0
	s_waitcnt lgkmcnt(2)
	global_store_dwordx4 v132, v[52:55], s[16:17] sc1
	s_add_u32 s16, s16, s39
	s_addc_u32 s17, s17, 0
	s_waitcnt lgkmcnt(1)
	global_store_dwordx4 v132, v[56:59], s[16:17] sc1
	s_add_u32 s16, s16, s39
	s_addc_u32 s17, s17, 0
	s_waitcnt lgkmcnt(0)
	global_store_dwordx4 v132, v[60:63], s[16:17] sc1
	s_barrier
	s_add_i32 s34, s34, s54
	s_cmp_lt_i32 s34, s13
	s_cbranch_scc1 .LBB0_1387

; template <int CTRL> DI int dpp_i(int v) { return __builtin_amdgcn_mov_dpp(v, CTRL, 0xF, 0xF, true); }
; DI void phase_peer(const Params& p, int l, int bid, int nblk) {
;     ...
;     u32 ck[7];
; #pragma unroll
;     for (int s = 0; s < 7; ++s) {
;       const int c = sub + 8 * s;
;       if (c < 50) {
;         const u32 u = __float_as_uint(tv1[cand_a(c)] + tv2[cand_b(c)]);
;         const u32 ord = (u & 0x80000000u) ? ~u : (u | 0x80000000u);
;         ck[s] = (ord & ~63u) | (u32)(63 - c);
;       } else ck[s] = 0u;
;     }
;     float w0v = 0.f, w1v = 0.f, mx = 0.f;
;     int w0c = 0, w1c = 0;
;     u32 prevk = 0xFFFFFFFFu;
; #pragma unroll
;     for (int r = 0; r < 16; ++r) {
;       u32 m = 0u;
; #pragma unroll
;       for (int s = 0; s < 7; ++s) { const u32 d = ck[s] - prevk; m = d > m ? d : m; }
;       { const u32 ov = (u32)dpp_i<DPP_XOR1>((int)m); m = ov > m ? ov : m; }
;       { const u32 ov = (u32)dpp_i<DPP_XOR2>((int)m); m = ov > m ? ov : m; }
;       { const u32 ov = (u32)dpp_i<DPP_MIRROR8>((int)m); m = ov > m ? ov : m; }
;       const u32 best = prevk + m;
;       prevk = best;
;       const u32 ordv = best & ~63u;
;       const float bv = __uint_as_float((ordv & 0x80000000u) ? (ordv & 0x7FFFFFFFu) : ~ordv);
;       const int bc = 63 - (int)(best & 63u);
;       if (r == 0) mx = bv;
;       if (sub == (r & 7)) {
;         if (r < 8) { w0v = bv; w0c = bc; } else { w1v = bv; w1c = bc; }
;       }
;     }
.LBB0_1512:
	s_or_b64 exec, exec, s[34:35]
	s_waitcnt vmcnt(6)
	v_pk_add_f32 v[4:5], v[0:1], v[2:3] op_sel_hi:[0,1]
	v_not_b32_e32 v0, v5
	v_or_b32_e32 v2, 0x80000000, v5
	v_cmp_gt_i32_e64 s[0:1], 0, v5
	v_or_b32_e32 v5, 0x80000000, v4
	v_or_b32_e32 v9, 8, v20
	v_cndmask_b32_e64 v0, v2, v0, s[0:1]
	v_and_b32_e32 v0, 0xffffffc0, v0
	v_sub_u32_e32 v21, v0, v20
	v_not_b32_e32 v0, v4
	v_cmp_gt_i32_e64 s[0:1], 0, v4
	v_mov_b32_e32 v13, v1
	v_or_b32_e32 v23, 24, v20
	v_cndmask_b32_e64 v0, v5, v0, s[0:1]
	v_and_b32_e32 v0, 0xffffffc0, v0
	v_sub_u32_e32 v22, v0, v9
	v_mov_b32_e32 v9, v3
	s_waitcnt vmcnt(4)
	v_pk_add_f32 v[0:1], v[8:9], v[12:13]
	v_or_b32_e32 v5, 16, v20
	v_not_b32_e32 v3, v1
	v_or_b32_e32 v8, 0x80000000, v1
	v_cmp_gt_i32_e64 s[0:1], 0, v1
	v_or_b32_e32 v12, 32, v20
	v_or_b32_e32 v13, 40, v20
	v_cndmask_b32_e64 v1, v8, v3, s[0:1]
	v_and_b32_e32 v1, 0xffffffc0, v1
	v_sub_u32_e32 v8, v1, v5
	v_not_b32_e32 v1, v0
	v_or_b32_e32 v5, 0x80000000, v0
	v_cmp_gt_i32_e64 s[0:1], 0, v0
	v_add_u32_e32 v3, 63, v8
	v_add_u32_e32 v8, 64, v8
	v_cndmask_b32_e64 v0, v5, v1, s[0:1]
	v_and_b32_e32 v0, 0xffffffc0, v0
	v_sub_u32_e32 v9, v0, v23
	s_waitcnt vmcnt(0)
	v_pk_add_f32 v[0:1], v[6:7], v[10:11]
	v_add_u32_e32 v11, 64, v22
	v_not_b32_e32 v6, v1
	v_or_b32_e32 v7, 0x80000000, v1
	v_cmp_gt_i32_e64 s[0:1], 0, v1
	v_or_b32_e32 v10, 0x80000000, v0
	v_add_u32_e32 v5, 63, v9
	v_cndmask_b32_e64 v1, v7, v6, s[0:1]
	v_not_b32_e32 v7, v0
	v_cmp_gt_i32_e64 s[0:1], 0, v0
	v_and_b32_e32 v1, 0xffffffc0, v1
	v_sub_u32_e32 v1, v1, v12
	v_cndmask_b32_e64 v0, v10, v7, s[0:1]
	v_and_b32_e32 v0, 0xffffffc0, v0
	v_add_u32_e32 v10, 64, v21
	v_add_u32_e32 v6, 63, v1
	v_sub_u32_e32 v0, v0, v13
	v_max3_u32 v8, v8, v11, v10
	v_add_u32_e32 v9, 64, v9
	v_add_u32_e32 v1, 64, v1
	v_add_u32_e32 v7, 63, v0
	v_max3_u32 v1, v1, v9, v8
	v_add_u32_e32 v0, 64, v0
	v_add_u32_e32 v8, 1, v19
	v_max3_u32 v0, v8, v0, v1
	v_add_u32_e32 v2, 63, v21
	v_add_u32_e32 v4, 63, v22
	v_max_u32_dpp v0, v0, v0 quad_perm:[1,0,3,2] row_mask:0xf bank_mask:0xf bound_ctrl:1
	v_cmp_eq_u32_e64 s[46:47], 0, v20
	s_nop 0
	v_max_u32_dpp v0, v0, v0 quad_perm:[2,3,0,1] row_mask:0xf bank_mask:0xf bound_ctrl:1
	s_nop 1
	v_max_u32_dpp v0, v0, v0 row_half_mirror row_mask:0xf bank_mask:0xf bound_ctrl:1
	v_add_u32_e32 v9, -1, v0
	v_sub_u32_e32 v10, v2, v9
	v_sub_u32_e32 v11, v4, v9
	v_sub_u32_e32 v12, v3, v9
	v_max3_u32 v10, v12, v11, v10
	v_sub_u32_e32 v11, v5, v9
	v_sub_u32_e32 v12, v6, v9
	v_max3_u32 v10, v12, v11, v10
	v_sub_u32_e32 v11, v7, v9
	v_sub_u32_e32 v12, v19, v9
	v_max3_u32 v10, v12, v11, v10
	v_and_b32_e32 v0, 0x7fffffc0, v9
	v_bitop3_b32 v1, v9, 63, v9 bitop3:0xcf
	v_max_u32_dpp v10, v10, v10 quad_perm:[1,0,3,2] row_mask:0xf bank_mask:0xf bound_ctrl:1
	v_cmp_gt_i32_e64 s[0:1], 0, v9
	s_nop 0
	v_max_u32_dpp v10, v10, v10 quad_perm:[2,3,0,1] row_mask:0xf bank_mask:0xf bound_ctrl:1
	v_cndmask_b32_e64 v1, v1, v0, s[0:1]
	v_bitop3_b32 v0, v9, 63, v9 bitop3:0xc
	v_max_u32_dpp v10, v10, v10 row_half_mirror row_mask:0xf bank_mask:0xf bound_ctrl:1
	v_cndmask_b32_e64 v0, 0, v0, s[46:47]
	v_cndmask_b32_e64 v8, 0, v1, s[46:47]
	v_add_u32_e32 v9, v10, v9
	s_and_saveexec_b64 s[34:35], vcc
	v_and_b32_e32 v0, 0x7fffffc0, v9
	v_bitop3_b32 v8, v9, 63, v9 bitop3:0xcf
	v_cmp_gt_i32_e64 s[0:1], 0, v9
	s_nop 1
	v_cndmask_b32_e64 v8, v8, v0, s[0:1]
	v_bitop3_b32 v0, v9, 63, v9 bitop3:0xc
	s_or_b64 exec, exec, s[34:35]
	v_sub_u32_e32 v10, v2, v9
	v_sub_u32_e32 v11, v4, v9
	v_sub_u32_e32 v12, v3, v9
	v_max3_u32 v10, v12, v11, v10
	v_sub_u32_e32 v11, v5, v9
	v_sub_u32_e32 v12, v6, v9
	v_max3_u32 v10, v12, v11, v10
	v_sub_u32_e32 v11, v7, v9
	v_sub_u32_e32 v12, v19, v9
	v_max3_u32 v10, v12, v11, v10
	v_cmp_eq_u32_e64 s[0:1], 2, v20
	s_nop 0
	v_max_u32_dpp v10, v10, v10 quad_perm:[1,0,3,2] row_mask:0xf bank_mask:0xf bound_ctrl:1
	s_nop 1
	v_max_u32_dpp v10, v10, v10 quad_perm:[2,3,0,1] row_mask:0xf bank_mask:0xf bound_ctrl:1
	s_nop 1
	v_max_u32_dpp v10, v10, v10 row_half_mirror row_mask:0xf bank_mask:0xf bound_ctrl:1
	v_add_u32_e32 v9, v10, v9
	s_and_saveexec_b64 s[34:35], s[0:1]
	v_and_b32_e32 v0, 0x7fffffc0, v9
	v_bitop3_b32 v8, v9, 63, v9 bitop3:0xcf
	v_cmp_gt_i32_e64 s[36:37], 0, v9
	s_nop 1
	v_cndmask_b32_e64 v8, v8, v0, s[36:37]
	v_bitop3_b32 v0, v9, 63, v9 bitop3:0xc
	s_or_b64 exec, exec, s[34:35]
	v_sub_u32_e32 v10, v2, v9
	v_sub_u32_e32 v11, v4, v9
	v_sub_u32_e32 v12, v3, v9
	v_max3_u32 v10, v12, v11, v10
	v_sub_u32_e32 v11, v5, v9
	v_sub_u32_e32 v12, v6, v9
	v_max3_u32 v10, v12, v11, v10
	v_sub_u32_e32 v11, v7, v9
	v_sub_u32_e32 v12, v19, v9
	v_max3_u32 v10, v12, v11, v10
	v_cmp_eq_u32_e64 s[36:37], 3, v20
	s_nop 0
	v_max_u32_dpp v10, v10, v10 quad_perm:[1,0,3,2] row_mask:0xf bank_mask:0xf bound_ctrl:1
	s_nop 1
	v_max_u32_dpp v10, v10, v10 quad_perm:[2,3,0,1] row_mask:0xf bank_mask:0xf bound_ctrl:1
	s_nop 1
	v_max_u32_dpp v10, v10, v10 row_half_mirror row_mask:0xf bank_mask:0xf bound_ctrl:1
	v_add_u32_e32 v9, v10, v9
	s_and_saveexec_b64 s[34:35], s[36:37]
	v_and_b32_e32 v0, 0x7fffffc0, v9
	v_bitop3_b32 v8, v9, 63, v9 bitop3:0xcf
	v_cmp_gt_i32_e64 s[38:39], 0, v9
	s_nop 1
	v_cndmask_b32_e64 v8, v8, v0, s[38:39]
	v_bitop3_b32 v0, v9, 63, v9 bitop3:0xc
	s_or_b64 exec, exec, s[34:35]
	v_sub_u32_e32 v10, v2, v9
	v_sub_u32_e32 v11, v4, v9
	v_sub_u32_e32 v12, v3, v9
	v_max3_u32 v10, v12, v11, v10
	v_sub_u32_e32 v11, v5, v9
	v_sub_u32_e32 v12, v6, v9
	v_max3_u32 v10, v12, v11, v10
	v_sub_u32_e32 v11, v7, v9
	v_sub_u32_e32 v12, v19, v9
	v_max3_u32 v10, v12, v11, v10
	v_cmp_eq_u32_e64 s[38:39], 4, v20
	s_nop 0
	v_max_u32_dpp v10, v10, v10 quad_perm:[1,0,3,2] row_mask:0xf bank_mask:0xf bound_ctrl:1
	s_nop 1
; template <int CTRL> DI int dpp_i(int v) { return __builtin_amdgcn_mov_dpp(v, CTRL, 0xF, 0xF, true); }
; DI void phase_peer(const Params& p, int l, int bid, int nblk) {
;     ...
; #pragma unroll
;     for (int r = 0; r < 16; ++r) {
;       u32 m = 0u;
; #pragma unroll
;       for (int s = 0; s < 7; ++s) { const u32 d = ck[s] - prevk; m = d > m ? d : m; }
;       { const u32 ov = (u32)dpp_i<DPP_XOR1>((int)m); m = ov > m ? ov : m; }
;       { const u32 ov = (u32)dpp_i<DPP_XOR2>((int)m); m = ov > m ? ov : m; }
;       { const u32 ov = (u32)dpp_i<DPP_MIRROR8>((int)m); m = ov > m ? ov : m; }
;       const u32 best = prevk + m;
;       prevk = best;
;       const u32 ordv = best & ~63u;
;       const float bv = __uint_as_float((ordv & 0x80000000u) ? (ordv & 0x7FFFFFFFu) : ~ordv);
;       const int bc = 63 - (int)(best & 63u);
;       if (r == 0) mx = bv;
;       if (sub == (r & 7)) {
;         if (r < 8) { w0v = bv; w0c = bc; } else { w1v = bv; w1c = bc; }
;       }
;     }
	v_max_u32_dpp v10, v10, v10 quad_perm:[2,3,0,1] row_mask:0xf bank_mask:0xf bound_ctrl:1
	s_nop 1
	v_max_u32_dpp v10, v10, v10 row_half_mirror row_mask:0xf bank_mask:0xf bound_ctrl:1
	v_add_u32_e32 v9, v10, v9
	s_and_saveexec_b64 s[34:35], s[38:39]
	v_and_b32_e32 v0, 0x7fffffc0, v9
	v_bitop3_b32 v8, v9, 63, v9 bitop3:0xcf
	v_cmp_gt_i32_e64 s[40:41], 0, v9
	s_nop 1
	v_cndmask_b32_e64 v8, v8, v0, s[40:41]
	v_bitop3_b32 v0, v9, 63, v9 bitop3:0xc
	s_or_b64 exec, exec, s[34:35]
	v_sub_u32_e32 v10, v2, v9
	v_sub_u32_e32 v11, v4, v9
	v_sub_u32_e32 v12, v3, v9
	v_max3_u32 v10, v12, v11, v10
	v_sub_u32_e32 v11, v5, v9
	v_sub_u32_e32 v12, v6, v9
	v_max3_u32 v10, v12, v11, v10
	v_sub_u32_e32 v11, v7, v9
	v_sub_u32_e32 v12, v19, v9
	v_max3_u32 v10, v12, v11, v10
	v_cmp_eq_u32_e64 s[40:41], 5, v20
	s_nop 0
	v_max_u32_dpp v10, v10, v10 quad_perm:[1,0,3,2] row_mask:0xf bank_mask:0xf bound_ctrl:1
	s_nop 1
	v_max_u32_dpp v10, v10, v10 quad_perm:[2,3,0,1] row_mask:0xf bank_mask:0xf bound_ctrl:1
	s_nop 1
	v_max_u32_dpp v10, v10, v10 row_half_mirror row_mask:0xf bank_mask:0xf bound_ctrl:1
	v_add_u32_e32 v9, v10, v9
	s_and_saveexec_b64 s[34:35], s[40:41]
	v_and_b32_e32 v0, 0x7fffffc0, v9
	v_bitop3_b32 v8, v9, 63, v9 bitop3:0xcf
	v_cmp_gt_i32_e64 s[42:43], 0, v9
	s_nop 1
	v_cndmask_b32_e64 v8, v8, v0, s[42:43]
	v_bitop3_b32 v0, v9, 63, v9 bitop3:0xc
	s_or_b64 exec, exec, s[34:35]
	v_sub_u32_e32 v10, v2, v9
	v_sub_u32_e32 v11, v4, v9
	v_sub_u32_e32 v12, v3, v9
	v_max3_u32 v10, v12, v11, v10
	v_sub_u32_e32 v11, v5, v9
	v_sub_u32_e32 v12, v6, v9
	v_max3_u32 v10, v12, v11, v10
	v_sub_u32_e32 v11, v7, v9
	v_sub_u32_e32 v12, v19, v9
	v_max3_u32 v10, v12, v11, v10
	v_cmp_eq_u32_e64 s[42:43], 6, v20
	s_nop 0
	v_max_u32_dpp v10, v10, v10 quad_perm:[1,0,3,2] row_mask:0xf bank_mask:0xf bound_ctrl:1
	s_nop 1
	v_max_u32_dpp v10, v10, v10 quad_perm:[2,3,0,1] row_mask:0xf bank_mask:0xf bound_ctrl:1
	s_nop 1
	v_max_u32_dpp v10, v10, v10 row_half_mirror row_mask:0xf bank_mask:0xf bound_ctrl:1
	v_add_u32_e32 v9, v10, v9
	s_and_saveexec_b64 s[34:35], s[42:43]
	v_and_b32_e32 v0, 0x7fffffc0, v9
	v_bitop3_b32 v8, v9, 63, v9 bitop3:0xcf
	v_cmp_gt_i32_e64 s[44:45], 0, v9
	s_nop 1
	v_cndmask_b32_e64 v8, v8, v0, s[44:45]
	v_bitop3_b32 v0, v9, 63, v9 bitop3:0xc
	s_or_b64 exec, exec, s[34:35]
	v_sub_u32_e32 v10, v2, v9
	v_sub_u32_e32 v11, v4, v9
	v_sub_u32_e32 v12, v3, v9
	v_max3_u32 v10, v12, v11, v10
	v_sub_u32_e32 v11, v5, v9
	v_sub_u32_e32 v12, v6, v9
	v_max3_u32 v10, v12, v11, v10
	v_sub_u32_e32 v11, v7, v9
	v_sub_u32_e32 v12, v19, v9
	v_max3_u32 v10, v12, v11, v10
	v_cmp_eq_u32_e64 s[44:45], 7, v20
	s_nop 0
	v_max_u32_dpp v10, v10, v10 quad_perm:[1,0,3,2] row_mask:0xf bank_mask:0xf bound_ctrl:1
	s_nop 1
	v_max_u32_dpp v10, v10, v10 quad_perm:[2,3,0,1] row_mask:0xf bank_mask:0xf bound_ctrl:1
	s_nop 1
	v_max_u32_dpp v10, v10, v10 row_half_mirror row_mask:0xf bank_mask:0xf bound_ctrl:1
	v_add_u32_e32 v9, v10, v9
	s_and_saveexec_b64 s[34:35], s[44:45]
	v_and_b32_e32 v0, 0x7fffffc0, v9
	v_bitop3_b32 v8, v9, 63, v9 bitop3:0xcf
	v_cmp_gt_i32_e64 s[48:49], 0, v9
	s_nop 1
	v_cndmask_b32_e64 v8, v8, v0, s[48:49]
	v_bitop3_b32 v0, v9, 63, v9 bitop3:0xc
	s_or_b64 exec, exec, s[34:35]
	v_sub_u32_e32 v10, v2, v9
	v_sub_u32_e32 v11, v4, v9
	v_sub_u32_e32 v12, v3, v9
	v_max3_u32 v10, v12, v11, v10
	v_sub_u32_e32 v11, v5, v9
	v_sub_u32_e32 v12, v6, v9
	v_max3_u32 v10, v12, v11, v10
	v_sub_u32_e32 v11, v7, v9
	v_sub_u32_e32 v12, v19, v9
	v_max3_u32 v10, v12, v11, v10
	s_nop 1
	v_max_u32_dpp v10, v10, v10 quad_perm:[1,0,3,2] row_mask:0xf bank_mask:0xf bound_ctrl:1
	s_nop 1
	v_max_u32_dpp v10, v10, v10 quad_perm:[2,3,0,1] row_mask:0xf bank_mask:0xf bound_ctrl:1
	s_nop 1
	v_max_u32_dpp v10, v10, v10 row_half_mirror row_mask:0xf bank_mask:0xf bound_ctrl:1
	v_add_u32_e32 v11, v10, v9
	v_mov_b32_e32 v10, 0
	v_mov_b32_e32 v9, 0
	s_and_saveexec_b64 s[34:35], s[46:47]
	v_and_b32_e32 v9, 0x7fffffc0, v11
	v_bitop3_b32 v10, v11, 63, v11 bitop3:0xcf
	v_cmp_gt_i32_e64 s[46:47], 0, v11
	s_nop 1
	v_cndmask_b32_e64 v10, v10, v9, s[46:47]
	v_bitop3_b32 v9, v11, 63, v11 bitop3:0xc
	s_or_b64 exec, exec, s[34:35]
	v_sub_u32_e32 v12, v2, v11
	v_sub_u32_e32 v13, v4, v11
	v_sub_u32_e32 v20, v3, v11
	v_max3_u32 v12, v20, v13, v12
	v_sub_u32_e32 v13, v5, v11
	v_sub_u32_e32 v20, v6, v11
	v_max3_u32 v12, v20, v13, v12
	v_sub_u32_e32 v13, v7, v11
	v_sub_u32_e32 v20, v19, v11
	v_max3_u32 v12, v20, v13, v12
	s_nop 1
	v_max_u32_dpp v12, v12, v12 quad_perm:[1,0,3,2] row_mask:0xf bank_mask:0xf bound_ctrl:1
	s_nop 1
	v_max_u32_dpp v12, v12, v12 quad_perm:[2,3,0,1] row_mask:0xf bank_mask:0xf bound_ctrl:1
	s_nop 1
	v_max_u32_dpp v12, v12, v12 row_half_mirror row_mask:0xf bank_mask:0xf bound_ctrl:1
	v_add_u32_e32 v11, v12, v11
	s_and_saveexec_b64 s[34:35], vcc
	v_and_b32_e32 v9, 0x7fffffc0, v11
	v_bitop3_b32 v10, v11, 63, v11 bitop3:0xcf
	v_cmp_gt_i32_e32 vcc, 0, v11
	s_nop 1
	v_cndmask_b32_e32 v10, v10, v9, vcc
	v_bitop3_b32 v9, v11, 63, v11 bitop3:0xc
	s_or_b64 exec, exec, s[34:35]
	v_sub_u32_e32 v12, v2, v11
	v_sub_u32_e32 v13, v4, v11
	v_sub_u32_e32 v20, v3, v11
	v_max3_u32 v12, v20, v13, v12
	v_sub_u32_e32 v13, v5, v11
	v_sub_u32_e32 v20, v6, v11
	v_max3_u32 v12, v20, v13, v12
	v_sub_u32_e32 v13, v7, v11
	v_sub_u32_e32 v20, v19, v11
	v_max3_u32 v12, v20, v13, v12
	s_nop 1
	v_max_u32_dpp v12, v12, v12 quad_perm:[1,0,3,2] row_mask:0xf bank_mask:0xf bound_ctrl:1
	s_nop 1
	v_max_u32_dpp v12, v12, v12 quad_perm:[2,3,0,1] row_mask:0xf bank_mask:0xf bound_ctrl:1
	s_nop 1
	v_max_u32_dpp v12, v12, v12 row_half_mirror row_mask:0xf bank_mask:0xf bound_ctrl:1
	v_add_u32_e32 v11, v12, v11
	s_and_saveexec_b64 s[34:35], s[0:1]
; template <int CTRL> DI int dpp_i(int v) { return __builtin_amdgcn_mov_dpp(v, CTRL, 0xF, 0xF, true); }
; template <int CTRL> DI float dpp_f(float v) { return __builtin_bit_cast(float, __builtin_amdgcn_mov_dpp(__builtin_bit_cast(int, v), CTRL, 0xF, 0xF, true)); }
; DI void phase_peer(const Params& p, int l, int bid, int nblk) {
;     ...
; #pragma unroll
;     for (int r = 0; r < 16; ++r) {
;       u32 m = 0u;
; #pragma unroll
;       for (int s = 0; s < 7; ++s) { const u32 d = ck[s] - prevk; m = d > m ? d : m; }
;       { const u32 ov = (u32)dpp_i<DPP_XOR1>((int)m); m = ov > m ? ov : m; }
;       { const u32 ov = (u32)dpp_i<DPP_XOR2>((int)m); m = ov > m ? ov : m; }
;       { const u32 ov = (u32)dpp_i<DPP_MIRROR8>((int)m); m = ov > m ? ov : m; }
;       const u32 best = prevk + m;
;       prevk = best;
;       const u32 ordv = best & ~63u;
;       const float bv = __uint_as_float((ordv & 0x80000000u) ? (ordv & 0x7FFFFFFFu) : ~ordv);
;       const int bc = 63 - (int)(best & 63u);
;       if (r == 0) mx = bv;
;       if (sub == (r & 7)) {
;         if (r < 8) { w0v = bv; w0c = bc; } else { w1v = bv; w1c = bc; }
;       }
;     }
;     const float e0 = expf(w0v - mx), e1 = expf(w1v - mx);
;     float es = e0 + e1;
;     es += dpp_f<DPP_XOR1>(es);
;     es += dpp_f<DPP_XOR2>(es);
;     es += dpp_f<DPP_MIRROR8>(es);
;     const float g0 = e0 / es, g1 = e1 / es;
	v_and_b32_e32 v9, 0x7fffffc0, v11
	v_bitop3_b32 v10, v11, 63, v11 bitop3:0xcf
	v_cmp_gt_i32_e32 vcc, 0, v11
	s_nop 1
	v_cndmask_b32_e32 v10, v10, v9, vcc
	v_bitop3_b32 v9, v11, 63, v11 bitop3:0xc
	s_or_b64 exec, exec, s[34:35]
	v_sub_u32_e32 v12, v2, v11
	v_sub_u32_e32 v13, v4, v11
	v_sub_u32_e32 v20, v3, v11
	v_max3_u32 v12, v20, v13, v12
	v_sub_u32_e32 v13, v5, v11
	v_sub_u32_e32 v20, v6, v11
	v_max3_u32 v12, v20, v13, v12
	v_sub_u32_e32 v13, v7, v11
	v_sub_u32_e32 v20, v19, v11
	v_max3_u32 v12, v20, v13, v12
	s_nop 1
	v_max_u32_dpp v12, v12, v12 quad_perm:[1,0,3,2] row_mask:0xf bank_mask:0xf bound_ctrl:1
	s_nop 1
	v_max_u32_dpp v12, v12, v12 quad_perm:[2,3,0,1] row_mask:0xf bank_mask:0xf bound_ctrl:1
	s_nop 1
	v_max_u32_dpp v12, v12, v12 row_half_mirror row_mask:0xf bank_mask:0xf bound_ctrl:1
	v_add_u32_e32 v11, v12, v11
	s_and_saveexec_b64 s[0:1], s[36:37]
	v_and_b32_e32 v9, 0x7fffffc0, v11
	v_bitop3_b32 v10, v11, 63, v11 bitop3:0xcf
	v_cmp_gt_i32_e32 vcc, 0, v11
	s_nop 1
	v_cndmask_b32_e32 v10, v10, v9, vcc
	v_bitop3_b32 v9, v11, 63, v11 bitop3:0xc
	s_or_b64 exec, exec, s[0:1]
	v_sub_u32_e32 v12, v2, v11
	v_sub_u32_e32 v13, v4, v11
	v_sub_u32_e32 v20, v3, v11
	v_max3_u32 v12, v20, v13, v12
	v_sub_u32_e32 v13, v5, v11
	v_sub_u32_e32 v20, v6, v11
	v_max3_u32 v12, v20, v13, v12
	v_sub_u32_e32 v13, v7, v11
	v_sub_u32_e32 v20, v19, v11
	v_max3_u32 v12, v20, v13, v12
	s_nop 1
	v_max_u32_dpp v12, v12, v12 quad_perm:[1,0,3,2] row_mask:0xf bank_mask:0xf bound_ctrl:1
	s_nop 1
	v_max_u32_dpp v12, v12, v12 quad_perm:[2,3,0,1] row_mask:0xf bank_mask:0xf bound_ctrl:1
	s_nop 1
	v_max_u32_dpp v12, v12, v12 row_half_mirror row_mask:0xf bank_mask:0xf bound_ctrl:1
	v_add_u32_e32 v11, v12, v11
	s_and_saveexec_b64 s[0:1], s[38:39]
	v_and_b32_e32 v9, 0x7fffffc0, v11
	v_bitop3_b32 v10, v11, 63, v11 bitop3:0xcf
	v_cmp_gt_i32_e32 vcc, 0, v11
	s_nop 1
	v_cndmask_b32_e32 v10, v10, v9, vcc
	v_bitop3_b32 v9, v11, 63, v11 bitop3:0xc
	s_or_b64 exec, exec, s[0:1]
	v_sub_u32_e32 v12, v2, v11
	v_sub_u32_e32 v13, v4, v11
	v_sub_u32_e32 v20, v3, v11
	v_max3_u32 v12, v20, v13, v12
	v_sub_u32_e32 v13, v5, v11
	v_sub_u32_e32 v20, v6, v11
	v_max3_u32 v12, v20, v13, v12
	v_sub_u32_e32 v13, v7, v11
	v_sub_u32_e32 v20, v19, v11
	v_max3_u32 v12, v20, v13, v12
	s_nop 1
	v_max_u32_dpp v12, v12, v12 quad_perm:[1,0,3,2] row_mask:0xf bank_mask:0xf bound_ctrl:1
	s_nop 1
	v_max_u32_dpp v12, v12, v12 quad_perm:[2,3,0,1] row_mask:0xf bank_mask:0xf bound_ctrl:1
	s_nop 1
	v_max_u32_dpp v12, v12, v12 row_half_mirror row_mask:0xf bank_mask:0xf bound_ctrl:1
	v_add_u32_e32 v11, v12, v11
	s_and_saveexec_b64 s[0:1], s[40:41]
	v_and_b32_e32 v9, 0x7fffffc0, v11
	v_bitop3_b32 v10, v11, 63, v11 bitop3:0xcf
	v_cmp_gt_i32_e32 vcc, 0, v11
	s_nop 1
	v_cndmask_b32_e32 v10, v10, v9, vcc
	v_bitop3_b32 v9, v11, 63, v11 bitop3:0xc
	s_or_b64 exec, exec, s[0:1]
	v_sub_u32_e32 v12, v2, v11
	v_sub_u32_e32 v13, v4, v11
	v_sub_u32_e32 v20, v3, v11
	v_max3_u32 v12, v20, v13, v12
	v_sub_u32_e32 v13, v5, v11
	v_sub_u32_e32 v20, v6, v11
	v_max3_u32 v12, v20, v13, v12
	v_sub_u32_e32 v13, v7, v11
	v_sub_u32_e32 v20, v19, v11
	v_max3_u32 v12, v20, v13, v12
	s_nop 1
	v_max_u32_dpp v12, v12, v12 quad_perm:[1,0,3,2] row_mask:0xf bank_mask:0xf bound_ctrl:1
	s_nop 1
	v_max_u32_dpp v12, v12, v12 quad_perm:[2,3,0,1] row_mask:0xf bank_mask:0xf bound_ctrl:1
	s_nop 1
	v_max_u32_dpp v12, v12, v12 row_half_mirror row_mask:0xf bank_mask:0xf bound_ctrl:1
	v_add_u32_e32 v11, v12, v11
	s_and_saveexec_b64 s[0:1], s[42:43]
	v_and_b32_e32 v9, 0x7fffffc0, v11
	v_bitop3_b32 v10, v11, 63, v11 bitop3:0xcf
	v_cmp_gt_i32_e32 vcc, 0, v11
	s_nop 1
	v_cndmask_b32_e32 v10, v10, v9, vcc
	v_bitop3_b32 v9, v11, 63, v11 bitop3:0xc
	s_or_b64 exec, exec, s[0:1]
	v_sub_u32_e32 v2, v2, v11
	v_sub_u32_e32 v4, v4, v11
	v_sub_u32_e32 v3, v3, v11
	v_max3_u32 v2, v3, v4, v2
	v_sub_u32_e32 v3, v5, v11
	v_sub_u32_e32 v4, v6, v11
	v_max3_u32 v2, v4, v3, v2
	v_sub_u32_e32 v3, v7, v11
	v_sub_u32_e32 v4, v19, v11
	v_max3_u32 v2, v4, v3, v2
	s_nop 1
	v_max_u32_dpp v2, v2, v2 quad_perm:[1,0,3,2] row_mask:0xf bank_mask:0xf bound_ctrl:1
	s_nop 1
	v_max_u32_dpp v2, v2, v2 quad_perm:[2,3,0,1] row_mask:0xf bank_mask:0xf bound_ctrl:1
	s_nop 1
	v_mov_b32_dpp v3, v2 row_half_mirror row_mask:0xf bank_mask:0xf bound_ctrl:1
	s_and_saveexec_b64 s[0:1], s[44:45]
	v_max_u32_e32 v2, v3, v2
	v_add_u32_e32 v2, v2, v11
	v_and_b32_e32 v3, 0x7fffffc0, v2
	v_bitop3_b32 v4, v2, 63, v2 bitop3:0xcf
	v_cmp_gt_i32_e32 vcc, 0, v2
	v_bitop3_b32 v9, v2, 63, v2 bitop3:0xc
	s_nop 0
	v_cndmask_b32_e32 v10, v4, v3, vcc
	s_or_b64 exec, exec, s[0:1]
	v_sub_f32_e32 v3, v8, v1
	v_mul_f32_e32 v4, 0x3fb8aa3b, v3
	v_fma_f32 v5, v3, s2, -v4
	v_rndne_f32_e32 v6, v4
; template <int CTRL> DI float dpp_f(float v) { return __builtin_bit_cast(float, __builtin_amdgcn_mov_dpp(__builtin_bit_cast(int, v), CTRL, 0xF, 0xF, true)); }
; DI void phase_peer(const Params& p, int l, int bid, int nblk) {
;     ...
;     const float e0 = expf(w0v - mx), e1 = expf(w1v - mx);
;     float es = e0 + e1;
;     es += dpp_f<DPP_XOR1>(es);
;     es += dpp_f<DPP_XOR2>(es);
;     es += dpp_f<DPP_MIRROR8>(es);
;     const float g0 = e0 / es, g1 = e1 / es;
;     int idx0, idx1;
;     {
;       const int gb = lane & ~7;
;       const int a0 = cand_a(w0c), c0 = cand_b(w0c), a1 = cand_a(w1c), c1 = cand_b(w1c);
;       const int p0l = __shfl(t1lo, gb + (a0 & 7)), p0h = __shfl(t1hi, gb + (a0 & 7));
;       const int q0l = __shfl(t2lo, gb + (c0 & 7)), q0h = __shfl(t2hi, gb + (c0 & 7));
;       const int p1l = __shfl(t1lo, gb + (a1 & 7)), p1h = __shfl(t1hi, gb + (a1 & 7));
;       const int q1l = __shfl(t2lo, gb + (c1 & 7)), q1h = __shfl(t2hi, gb + (c1 & 7));
;       idx0 = ((a0 & 8) ? p0h : p0l) * 128 + ((c0 & 8) ? q0h : q0l);
;       idx1 = ((a1 & 8) ? p1h : p1l) * 128 + ((c1 & 8) ? q1h : q1l);
;     }
	v_fmac_f32_e32 v5, 0x32a5705f, v3
	v_sub_f32_e32 v4, v4, v6
	v_add_f32_e32 v4, v4, v5
	v_exp_f32_e32 v4, v4
	v_cvt_i32_f32_e32 v5, v6
	v_cmp_ngt_f32_e32 vcc, s3, v3
	v_sub_f32_e32 v1, v10, v1
	v_mov_b32_e32 v8, 0x11111111
	v_ldexp_f32 v4, v4, v5
	v_cndmask_b32_e32 v4, 0, v4, vcc
	v_cmp_nlt_f32_e32 vcc, s58, v3
	v_mul_f32_e32 v3, 0x3fb8aa3b, v1
	v_rndne_f32_e32 v5, v3
	v_cndmask_b32_e32 v85, v217, v4, vcc
	v_fma_f32 v4, v1, s2, -v3
	v_fmac_f32_e32 v4, 0x32a5705f, v1
	v_sub_f32_e32 v3, v3, v5
	v_add_f32_e32 v3, v3, v4
	v_exp_f32_e32 v3, v3
	v_cvt_i32_f32_e32 v4, v5
	v_cmp_ngt_f32_e32 vcc, s3, v1
	v_mov_b32_e32 v19, 0x76543210
	v_mov_b32_e32 v20, 0xfedcba98
	v_ldexp_f32 v3, v3, v4
	v_cndmask_b32_e32 v3, 0, v3, vcc
	v_cmp_nlt_f32_e32 vcc, s58, v1
	v_mov_b32_e32 v10, 0x33322222
	v_mov_b32_e32 v21, 0x21043210
	v_cndmask_b32_e32 v86, v217, v3, vcc
	v_lshrrev_b32_e32 v3, 3, v0
	v_cmp_eq_u32_e32 vcc, 2, v3
	v_cmp_eq_u32_e64 s[40:41], 1, v3
	v_cmp_eq_u32_e64 s[0:1], 4, v3
	v_cndmask_b32_e32 v4, 0, v8, vcc
	v_cmp_eq_u32_e32 vcc, 3, v3
	v_cmp_eq_u32_e64 s[36:37], 5, v3
	v_cmp_eq_u32_e64 s[38:39], 6, v3
	v_cndmask_b32_e64 v3, v19, v20, s[40:41]
	v_cndmask_b32_e32 v4, v4, v10, vcc
	v_mov_b32_e32 v11, 0x66554443
	v_cndmask_b32_e32 v3, v3, v21, vcc
	v_mov_b32_e32 v22, 0x10102103
	v_lshrrev_b32_e32 v7, 3, v9
	v_cndmask_b32_e64 v4, v4, v11, s[0:1]
	v_mov_b32_e32 v12, 0xdcba9877
	v_cndmask_b32_e64 v3, v3, v22, s[0:1]
	v_cmp_eq_u32_e32 vcc, 2, v7
	v_cndmask_b32_e64 v4, v4, v12, s[36:37]
	v_mov_b32_e32 v13, 0xfe
	v_cndmask_b32_e64 v3, v3, 16, s[36:37]
	v_cndmask_b32_e32 v8, 0, v8, vcc
	v_cmp_eq_u32_e32 vcc, 3, v7
	v_cmp_eq_u32_e64 s[40:41], 1, v7
	v_add_f32_e32 v1, v85, v86
	v_cndmask_b32_e64 v4, v4, v13, s[38:39]
	v_lshlrev_b32_e32 v0, 2, v0
	v_cndmask_b32_e64 v3, v3, 0, s[38:39]
	v_cndmask_b32_e32 v8, v8, v10, vcc
	v_cmp_eq_u32_e64 s[0:1], 4, v7
	v_cmp_eq_u32_e64 s[36:37], 5, v7
	v_cmp_eq_u32_e64 s[38:39], 6, v7
	v_cndmask_b32_e64 v7, v19, v20, s[40:41]
	v_add_f32_dpp v1, v1, v1 quad_perm:[1,0,3,2] row_mask:0xf bank_mask:0xf bound_ctrl:1
	v_and_b32_e32 v5, 28, v0
	v_cndmask_b32_e64 v8, v8, v11, s[0:1]
	v_cndmask_b32_e32 v7, v7, v21, vcc
	v_add_f32_dpp v87, v1, v1 quad_perm:[2,3,0,1] row_mask:0xf bank_mask:0xf bound_ctrl:1
	v_and_b32_e32 v1, 56, v14
	v_lshrrev_b32_e32 v6, v0, v4
	v_cndmask_b32_e64 v8, v8, v12, s[36:37]
	v_lshlrev_b32_e32 v9, 2, v9
	v_cndmask_b32_e64 v7, v7, v22, s[0:1]
	v_bfe_u32 v4, v4, v5, 3
	v_lshrrev_b32_e32 v0, v0, v3
	v_cndmask_b32_e64 v8, v8, v13, s[38:39]
	v_and_b32_e32 v10, 28, v9
	v_cndmask_b32_e64 v7, v7, 16, s[36:37]
	v_or3_b32 v4, v1, v4, v216
	v_bfe_u32 v3, v3, v5, 3
	v_lshrrev_b32_e32 v11, v9, v8
	v_cndmask_b32_e64 v7, v7, 0, s[38:39]
	v_lshlrev_b32_e32 v4, 2, v4
	v_or3_b32 v3, v1, v3, v216
	v_bfe_u32 v8, v8, v10, 3
	v_lshrrev_b32_e32 v9, v9, v7
	ds_bpermute_b32 v12, v4, v17
	ds_bpermute_b32 v4, v4, v18
	v_lshlrev_b32_e32 v3, 2, v3
	v_or3_b32 v8, v1, v8, v216
	v_bfe_u32 v7, v7, v10, 3
	ds_bpermute_b32 v5, v3, v15
	ds_bpermute_b32 v3, v3, v16
	v_lshlrev_b32_e32 v8, 2, v8
	v_or3_b32 v1, v1, v7, v216
	ds_bpermute_b32 v13, v8, v17
	ds_bpermute_b32 v8, v8, v18
	v_lshlrev_b32_e32 v1, 2, v1
	v_and_b32_e32 v6, 8, v6
	ds_bpermute_b32 v7, v1, v15
	ds_bpermute_b32 v1, v1, v16
	v_and_b32_e32 v0, 8, v0
	v_cmp_eq_u32_e32 vcc, 0, v6
	v_and_b32_e32 v11, 8, v11
	v_and_b32_e32 v9, 8, v9
	s_waitcnt lgkmcnt(6)
	v_cndmask_b32_e32 v10, v4, v12, vcc
	v_cmp_eq_u32_e32 vcc, 0, v0
	v_and_b32_e32 v2, 63, v14
	v_lshlrev_b32_e32 v172, 4, v2
	s_waitcnt lgkmcnt(4)
	v_cndmask_b32_e32 v12, v3, v5, vcc
	v_cmp_eq_u32_e32 vcc, 0, v11
	v_lshlrev_b32_e32 v2, 5, v2
	v_mov_b32_e32 v3, v173
	s_waitcnt lgkmcnt(2)
	v_cndmask_b32_e32 v8, v8, v13, vcc
	v_cmp_eq_u32_e32 vcc, 0, v9
	v_lshl_add_u32 v150, v10, 7, v12
	v_readlane_b32 s0, v255, 40
	s_waitcnt lgkmcnt(0)
	v_cndmask_b32_e32 v9, v1, v7, vcc
	v_lshl_add_u32 v151, v8, 7, v9
	v_mov_b32_dpp v88, v87 row_half_mirror row_mask:0xf bank_mask:0xf bound_ctrl:1
	v_lshrrev_b32_e32 v6, 6, v218
	v_and_b32_e32 v7, 63, v218
	v_add_f32_e32 v0, v87, v88
	v_mul_u32_u24_e32 v6, 0x4800, v6
	v_rcp_f32_e32 v1, v0
	v_lshl_add_u32 v6, v7, 2, v6
	v_fma_f32 v2, -v0, v1, 2.0
	v_mul_f32_e32 v1, v1, v2
	v_mul_f32_e32 v1, 0x3e800000, v1
	v_add_u32_e32 v6, s66, v6
	v_mul_f32_e32 v2, v85, v1
	v_mul_f32_e32 v3, v86, v1
	v_lshlrev_b32_e32 v4, 7, v150
	v_lshlrev_b32_e32 v5, 7, v151
	v_lshlrev_b32_e32 v9, 9, v64
	ds_write_b32 v6, v4
	ds_write_b32 v6, v5 offset:256
	v_lshl_add_u32 v9, v7, 2, v9
	s_add_u32 s16, s96, 0x0
	s_addc_u32 s17, s97, 0
	global_store_dword v9, v2, s[16:17] sc1
	global_store_dword v9, v3, s[16:17] offset:256 sc1
	s_add_i32 s55, s55, 1
	s_addk_i32 s66, 0x200
	s_branch .LBB0_1508

; DI void phase_peer(const Params& p, int l, int bid, int nblk) {
;     ...
;     PEER_LOAD(0, 0, VB)
; #pragma unroll 1
;     for (int k = 0; k < 16; k += 2) {
;       PEER_LOAD(1, k + 1, VB)
;       __builtin_amdgcn_sched_barrier(0);
;       PEER_ACC(0, k)
;       { const int kn = (k + 2 < 16) ? k + 2 : 15; PEER_LOAD(0, kn, VB) }
;       __builtin_amdgcn_sched_barrier(0);
;       PEER_ACC(1, k + 1)
;     }
.Lpeer_v_ptr:
	s_cmp_lg_u64 s[70:71], 0
	s_cselect_b32 s86, 17, 0
	s_add_i32 s84, s84, s86
	s_mul_i32 s84, s84, 0x6000
	s_add_u32 s82, s96, 0x1be09000
	s_addc_u32 s83, s97, 0
	s_add_u32 s82, s82, s84
	s_addc_u32 s83, s83, 0
	s_lshl_b32 s86, s46, 9
	s_add_u32 s80, s80, s86
	s_addc_u32 s81, s81, 0
	s_add_u32 s82, s82, s86
	s_addc_u32 s83, s83, 0
	v_add_u32_e32 v144, s65, v162
	ds_read_b128 v[64:67], v144
	ds_read_b128 v[68:71], v144 offset:16
	ds_read_b128 v[72:75], v144 offset:32
	ds_read_b128 v[76:79], v144 offset:48
	v_add_u32_e32 v145, s50, v164
	ds_read_b128 v[80:83], v145
	ds_read_b128 v[84:87], v145 offset:16
	ds_read_b128 v[88:91], v145 offset:32
	ds_read_b128 v[92:95], v145 offset:48
	v_mov_b64_e32 v[96:97], 0
	v_mov_b64_e32 v[98:99], 0
	v_mov_b64_e32 v[100:101], 0
	v_mov_b64_e32 v[102:103], 0
	v_mov_b64_e32 v[104:105], 0
	v_mov_b64_e32 v[106:107], 0
	v_mov_b64_e32 v[108:109], 0
	v_mov_b64_e32 v[110:111], 0
	global_load_dwordx2 v[140:141], v166, s[80:81]
	global_load_dwordx2 v[142:143], v166, s[82:83]
	s_waitcnt lgkmcnt(0)
	s_waitcnt vmcnt(16)
	v_cvt_pk_f32_fp8_e32 v[120:121], v0
	v_cvt_pk_f32_fp8_sdwa v[122:123], v0 src0_sel:WORD_1
	v_cvt_pk_f32_fp8_e32 v[124:125], v1
	v_cvt_pk_f32_fp8_sdwa v[126:127], v1 src0_sel:WORD_1
	v_pk_fma_f32 v[96:97], v[120:121], v[80:81], v[96:97] op_sel_hi:[1,0,1]
	v_pk_fma_f32 v[98:99], v[122:123], v[80:81], v[98:99] op_sel_hi:[1,0,1]
	v_pk_fma_f32 v[100:101], v[124:125], v[80:81], v[100:101] op_sel_hi:[1,0,1]
	v_pk_fma_f32 v[102:103], v[126:127], v[80:81], v[102:103] op_sel_hi:[1,0,1]
	v_cvt_pk_f32_fp8_e32 v[120:121], v2
	v_cvt_pk_f32_fp8_sdwa v[122:123], v2 src0_sel:WORD_1
	v_cvt_pk_f32_fp8_e32 v[124:125], v3
	v_cvt_pk_f32_fp8_sdwa v[126:127], v3 src0_sel:WORD_1
	v_pk_fma_f32 v[104:105], v[120:121], v[80:81], v[104:105] op_sel_hi:[1,0,1]
	v_pk_fma_f32 v[106:107], v[122:123], v[80:81], v[106:107] op_sel_hi:[1,0,1]
	v_pk_fma_f32 v[108:109], v[124:125], v[80:81], v[108:109] op_sel_hi:[1,0,1]
	v_pk_fma_f32 v[110:111], v[126:127], v[80:81], v[110:111] op_sel_hi:[1,0,1]
	v_cvt_pk_f32_fp8_e32 v[128:129], v4
	v_cvt_pk_f32_fp8_sdwa v[130:131], v4 src0_sel:WORD_1
	v_cvt_pk_f32_fp8_e32 v[132:133], v5
	v_cvt_pk_f32_fp8_sdwa v[134:135], v5 src0_sel:WORD_1
	v_pk_fma_f32 v[96:97], v[128:129], v[80:81], v[96:97] op_sel:[0,1,0]
	v_pk_fma_f32 v[98:99], v[130:131], v[80:81], v[98:99] op_sel:[0,1,0]
	v_pk_fma_f32 v[100:101], v[132:133], v[80:81], v[100:101] op_sel:[0,1,0]
	v_pk_fma_f32 v[102:103], v[134:135], v[80:81], v[102:103] op_sel:[0,1,0]
	v_cvt_pk_f32_fp8_e32 v[128:129], v6
	v_cvt_pk_f32_fp8_sdwa v[130:131], v6 src0_sel:WORD_1
	v_cvt_pk_f32_fp8_e32 v[132:133], v7
	v_cvt_pk_f32_fp8_sdwa v[134:135], v7 src0_sel:WORD_1
	v_pk_fma_f32 v[104:105], v[128:129], v[80:81], v[104:105] op_sel:[0,1,0]
	v_pk_fma_f32 v[106:107], v[130:131], v[80:81], v[106:107] op_sel:[0,1,0]
	v_pk_fma_f32 v[108:109], v[132:133], v[80:81], v[108:109] op_sel:[0,1,0]
	v_pk_fma_f32 v[110:111], v[134:135], v[80:81], v[110:111] op_sel:[0,1,0]
	v_add_u32_e32 v0, v64, v160
	v_add_u32_e32 v4, v65, v160
	global_load_dwordx4 v[0:3], v0, s[42:43]
	global_load_dwordx4 v[4:7], v4, s[42:43]
	s_waitcnt vmcnt(16)
	v_cvt_pk_f32_fp8_e32 v[120:121], v8
	v_cvt_pk_f32_fp8_sdwa v[122:123], v8 src0_sel:WORD_1
	v_cvt_pk_f32_fp8_e32 v[124:125], v9
	v_cvt_pk_f32_fp8_sdwa v[126:127], v9 src0_sel:WORD_1
	v_pk_fma_f32 v[96:97], v[120:121], v[82:83], v[96:97] op_sel_hi:[1,0,1]
	v_pk_fma_f32 v[98:99], v[122:123], v[82:83], v[98:99] op_sel_hi:[1,0,1]
	v_pk_fma_f32 v[100:101], v[124:125], v[82:83], v[100:101] op_sel_hi:[1,0,1]
	v_pk_fma_f32 v[102:103], v[126:127], v[82:83], v[102:103] op_sel_hi:[1,0,1]
	v_cvt_pk_f32_fp8_e32 v[120:121], v10
	v_cvt_pk_f32_fp8_sdwa v[122:123], v10 src0_sel:WORD_1
	v_cvt_pk_f32_fp8_e32 v[124:125], v11
	v_cvt_pk_f32_fp8_sdwa v[126:127], v11 src0_sel:WORD_1
	v_pk_fma_f32 v[104:105], v[120:121], v[82:83], v[104:105] op_sel_hi:[1,0,1]
	v_pk_fma_f32 v[106:107], v[122:123], v[82:83], v[106:107] op_sel_hi:[1,0,1]
	v_pk_fma_f32 v[108:109], v[124:125], v[82:83], v[108:109] op_sel_hi:[1,0,1]
	v_pk_fma_f32 v[110:111], v[126:127], v[82:83], v[110:111] op_sel_hi:[1,0,1]
	v_cvt_pk_f32_fp8_e32 v[128:129], v12
	v_cvt_pk_f32_fp8_sdwa v[130:131], v12 src0_sel:WORD_1
	v_cvt_pk_f32_fp8_e32 v[132:133], v13
	v_cvt_pk_f32_fp8_sdwa v[134:135], v13 src0_sel:WORD_1
	v_pk_fma_f32 v[96:97], v[128:129], v[82:83], v[96:97] op_sel:[0,1,0]
	v_pk_fma_f32 v[98:99], v[130:131], v[82:83], v[98:99] op_sel:[0,1,0]
	v_pk_fma_f32 v[100:101], v[132:133], v[82:83], v[100:101] op_sel:[0,1,0]
	v_pk_fma_f32 v[102:103], v[134:135], v[82:83], v[102:103] op_sel:[0,1,0]
	v_cvt_pk_f32_fp8_e32 v[128:129], v14
	v_cvt_pk_f32_fp8_sdwa v[130:131], v14 src0_sel:WORD_1
	v_cvt_pk_f32_fp8_e32 v[132:133], v15
	v_cvt_pk_f32_fp8_sdwa v[134:135], v15 src0_sel:WORD_1
	v_pk_fma_f32 v[104:105], v[128:129], v[82:83], v[104:105] op_sel:[0,1,0]
	v_pk_fma_f32 v[106:107], v[130:131], v[82:83], v[106:107] op_sel:[0,1,0]
	v_pk_fma_f32 v[108:109], v[132:133], v[82:83], v[108:109] op_sel:[0,1,0]
	v_pk_fma_f32 v[110:111], v[134:135], v[82:83], v[110:111] op_sel:[0,1,0]
	v_add_u32_e32 v8, v66, v160
	v_add_u32_e32 v12, v67, v160
	global_load_dwordx4 v[8:11], v8, s[42:43]
	global_load_dwordx4 v[12:15], v12, s[42:43]
	s_waitcnt vmcnt(16)
	v_cvt_pk_f32_fp8_e32 v[120:121], v16
	v_cvt_pk_f32_fp8_sdwa v[122:123], v16 src0_sel:WORD_1
	v_cvt_pk_f32_fp8_e32 v[124:125], v17
	v_cvt_pk_f32_fp8_sdwa v[126:127], v17 src0_sel:WORD_1
	v_pk_fma_f32 v[96:97], v[120:121], v[84:85], v[96:97] op_sel_hi:[1,0,1]
	v_pk_fma_f32 v[98:99], v[122:123], v[84:85], v[98:99] op_sel_hi:[1,0,1]
	v_pk_fma_f32 v[100:101], v[124:125], v[84:85], v[100:101] op_sel_hi:[1,0,1]
	v_pk_fma_f32 v[102:103], v[126:127], v[84:85], v[102:103] op_sel_hi:[1,0,1]
	v_cvt_pk_f32_fp8_e32 v[120:121], v18
	v_cvt_pk_f32_fp8_sdwa v[122:123], v18 src0_sel:WORD_1
	v_cvt_pk_f32_fp8_e32 v[124:125], v19
	v_cvt_pk_f32_fp8_sdwa v[126:127], v19 src0_sel:WORD_1
	v_pk_fma_f32 v[104:105], v[120:121], v[84:85], v[104:105] op_sel_hi:[1,0,1]
	v_pk_fma_f32 v[106:107], v[122:123], v[84:85], v[106:107] op_sel_hi:[1,0,1]
	v_pk_fma_f32 v[108:109], v[124:125], v[84:85], v[108:109] op_sel_hi:[1,0,1]
	v_pk_fma_f32 v[110:111], v[126:127], v[84:85], v[110:111] op_sel_hi:[1,0,1]
	v_cvt_pk_f32_fp8_e32 v[128:129], v20
	v_cvt_pk_f32_fp8_sdwa v[130:131], v20 src0_sel:WORD_1
	v_cvt_pk_f32_fp8_e32 v[132:133], v21
	v_cvt_pk_f32_fp8_sdwa v[134:135], v21 src0_sel:WORD_1
	v_pk_fma_f32 v[96:97], v[128:129], v[84:85], v[96:97] op_sel:[0,1,0]
	v_pk_fma_f32 v[98:99], v[130:131], v[84:85], v[98:99] op_sel:[0,1,0]
	v_pk_fma_f32 v[100:101], v[132:133], v[84:85], v[100:101] op_sel:[0,1,0]
	v_pk_fma_f32 v[102:103], v[134:135], v[84:85], v[102:103] op_sel:[0,1,0]
	v_cvt_pk_f32_fp8_e32 v[128:129], v22
	v_cvt_pk_f32_fp8_sdwa v[130:131], v22 src0_sel:WORD_1
	v_cvt_pk_f32_fp8_e32 v[132:133], v23
	v_cvt_pk_f32_fp8_sdwa v[134:135], v23 src0_sel:WORD_1
	v_pk_fma_f32 v[104:105], v[128:129], v[84:85], v[104:105] op_sel:[0,1,0]
	v_pk_fma_f32 v[106:107], v[130:131], v[84:85], v[106:107] op_sel:[0,1,0]
	v_pk_fma_f32 v[108:109], v[132:133], v[84:85], v[108:109] op_sel:[0,1,0]
	v_pk_fma_f32 v[110:111], v[134:135], v[84:85], v[110:111] op_sel:[0,1,0]
	v_add_u32_e32 v16, v68, v160
	v_add_u32_e32 v20, v69, v160
	global_load_dwordx4 v[16:19], v16, s[42:43]
	global_load_dwordx4 v[20:23], v20, s[42:43]
	s_waitcnt vmcnt(16)
	v_cvt_pk_f32_fp8_e32 v[120:121], v24
	v_cvt_pk_f32_fp8_sdwa v[122:123], v24 src0_sel:WORD_1
	v_cvt_pk_f32_fp8_e32 v[124:125], v25
	v_cvt_pk_f32_fp8_sdwa v[126:127], v25 src0_sel:WORD_1
	v_pk_fma_f32 v[96:97], v[120:121], v[86:87], v[96:97] op_sel_hi:[1,0,1]
	v_pk_fma_f32 v[98:99], v[122:123], v[86:87], v[98:99] op_sel_hi:[1,0,1]
	v_pk_fma_f32 v[100:101], v[124:125], v[86:87], v[100:101] op_sel_hi:[1,0,1]
	v_pk_fma_f32 v[102:103], v[126:127], v[86:87], v[102:103] op_sel_hi:[1,0,1]
	v_cvt_pk_f32_fp8_e32 v[120:121], v26
	v_cvt_pk_f32_fp8_sdwa v[122:123], v26 src0_sel:WORD_1
	v_cvt_pk_f32_fp8_e32 v[124:125], v27
	v_cvt_pk_f32_fp8_sdwa v[126:127], v27 src0_sel:WORD_1
	v_pk_fma_f32 v[104:105], v[120:121], v[86:87], v[104:105] op_sel_hi:[1,0,1]
	v_pk_fma_f32 v[106:107], v[122:123], v[86:87], v[106:107] op_sel_hi:[1,0,1]
	v_pk_fma_f32 v[108:109], v[124:125], v[86:87], v[108:109] op_sel_hi:[1,0,1]
	v_pk_fma_f32 v[110:111], v[126:127], v[86:87], v[110:111] op_sel_hi:[1,0,1]
	v_cvt_pk_f32_fp8_e32 v[128:129], v28
	v_cvt_pk_f32_fp8_sdwa v[130:131], v28 src0_sel:WORD_1
	v_cvt_pk_f32_fp8_e32 v[132:133], v29
	v_cvt_pk_f32_fp8_sdwa v[134:135], v29 src0_sel:WORD_1
	v_pk_fma_f32 v[96:97], v[128:129], v[86:87], v[96:97] op_sel:[0,1,0]
	v_pk_fma_f32 v[98:99], v[130:131], v[86:87], v[98:99] op_sel:[0,1,0]
	v_pk_fma_f32 v[100:101], v[132:133], v[86:87], v[100:101] op_sel:[0,1,0]
	v_pk_fma_f32 v[102:103], v[134:135], v[86:87], v[102:103] op_sel:[0,1,0]
	v_cvt_pk_f32_fp8_e32 v[128:129], v30
	v_cvt_pk_f32_fp8_sdwa v[130:131], v30 src0_sel:WORD_1
	v_cvt_pk_f32_fp8_e32 v[132:133], v31
	v_cvt_pk_f32_fp8_sdwa v[134:135], v31 src0_sel:WORD_1
	v_pk_fma_f32 v[104:105], v[128:129], v[86:87], v[104:105] op_sel:[0,1,0]
	v_pk_fma_f32 v[106:107], v[130:131], v[86:87], v[106:107] op_sel:[0,1,0]
	v_pk_fma_f32 v[108:109], v[132:133], v[86:87], v[108:109] op_sel:[0,1,0]
	v_pk_fma_f32 v[110:111], v[134:135], v[86:87], v[110:111] op_sel:[0,1,0]
	v_add_u32_e32 v24, v70, v160
	v_add_u32_e32 v28, v71, v160
	global_load_dwordx4 v[24:27], v24, s[42:43]
	global_load_dwordx4 v[28:31], v28, s[42:43]
	s_waitcnt vmcnt(16)
	v_cvt_pk_f32_fp8_e32 v[120:121], v32
	v_cvt_pk_f32_fp8_sdwa v[122:123], v32 src0_sel:WORD_1
	v_cvt_pk_f32_fp8_e32 v[124:125], v33
	v_cvt_pk_f32_fp8_sdwa v[126:127], v33 src0_sel:WORD_1
	v_pk_fma_f32 v[96:97], v[120:121], v[88:89], v[96:97] op_sel_hi:[1,0,1]
	v_pk_fma_f32 v[98:99], v[122:123], v[88:89], v[98:99] op_sel_hi:[1,0,1]
	v_pk_fma_f32 v[100:101], v[124:125], v[88:89], v[100:101] op_sel_hi:[1,0,1]
	v_pk_fma_f32 v[102:103], v[126:127], v[88:89], v[102:103] op_sel_hi:[1,0,1]
	v_cvt_pk_f32_fp8_e32 v[120:121], v34
	v_cvt_pk_f32_fp8_sdwa v[122:123], v34 src0_sel:WORD_1
	v_cvt_pk_f32_fp8_e32 v[124:125], v35
	v_cvt_pk_f32_fp8_sdwa v[126:127], v35 src0_sel:WORD_1
	v_pk_fma_f32 v[104:105], v[120:121], v[88:89], v[104:105] op_sel_hi:[1,0,1]
	v_pk_fma_f32 v[106:107], v[122:123], v[88:89], v[106:107] op_sel_hi:[1,0,1]
	v_pk_fma_f32 v[108:109], v[124:125], v[88:89], v[108:109] op_sel_hi:[1,0,1]
	v_pk_fma_f32 v[110:111], v[126:127], v[88:89], v[110:111] op_sel_hi:[1,0,1]
	v_cvt_pk_f32_fp8_e32 v[128:129], v36
	v_cvt_pk_f32_fp8_sdwa v[130:131], v36 src0_sel:WORD_1
	v_cvt_pk_f32_fp8_e32 v[132:133], v37
	v_cvt_pk_f32_fp8_sdwa v[134:135], v37 src0_sel:WORD_1
	v_pk_fma_f32 v[96:97], v[128:129], v[88:89], v[96:97] op_sel:[0,1,0]
	v_pk_fma_f32 v[98:99], v[130:131], v[88:89], v[98:99] op_sel:[0,1,0]
	v_pk_fma_f32 v[100:101], v[132:133], v[88:89], v[100:101] op_sel:[0,1,0]
	v_pk_fma_f32 v[102:103], v[134:135], v[88:89], v[102:103] op_sel:[0,1,0]
	v_cvt_pk_f32_fp8_e32 v[128:129], v38
	v_cvt_pk_f32_fp8_sdwa v[130:131], v38 src0_sel:WORD_1
	v_cvt_pk_f32_fp8_e32 v[132:133], v39
	v_cvt_pk_f32_fp8_sdwa v[134:135], v39 src0_sel:WORD_1
	v_pk_fma_f32 v[104:105], v[128:129], v[88:89], v[104:105] op_sel:[0,1,0]
	v_pk_fma_f32 v[106:107], v[130:131], v[88:89], v[106:107] op_sel:[0,1,0]
	v_pk_fma_f32 v[108:109], v[132:133], v[88:89], v[108:109] op_sel:[0,1,0]
	v_pk_fma_f32 v[110:111], v[134:135], v[88:89], v[110:111] op_sel:[0,1,0]
	v_add_u32_e32 v32, v72, v160
	v_add_u32_e32 v36, v73, v160
	global_load_dwordx4 v[32:35], v32, s[42:43]
	global_load_dwordx4 v[36:39], v36, s[42:43]
	s_waitcnt vmcnt(16)
	v_cvt_pk_f32_fp8_e32 v[120:121], v40
	v_cvt_pk_f32_fp8_sdwa v[122:123], v40 src0_sel:WORD_1
	v_cvt_pk_f32_fp8_e32 v[124:125], v41
	v_cvt_pk_f32_fp8_sdwa v[126:127], v41 src0_sel:WORD_1
	v_pk_fma_f32 v[96:97], v[120:121], v[90:91], v[96:97] op_sel_hi:[1,0,1]
	v_pk_fma_f32 v[98:99], v[122:123], v[90:91], v[98:99] op_sel_hi:[1,0,1]
	v_pk_fma_f32 v[100:101], v[124:125], v[90:91], v[100:101] op_sel_hi:[1,0,1]
	v_pk_fma_f32 v[102:103], v[126:127], v[90:91], v[102:103] op_sel_hi:[1,0,1]
	v_cvt_pk_f32_fp8_e32 v[120:121], v42
	v_cvt_pk_f32_fp8_sdwa v[122:123], v42 src0_sel:WORD_1
	v_cvt_pk_f32_fp8_e32 v[124:125], v43
	v_cvt_pk_f32_fp8_sdwa v[126:127], v43 src0_sel:WORD_1
	v_pk_fma_f32 v[104:105], v[120:121], v[90:91], v[104:105] op_sel_hi:[1,0,1]
	v_pk_fma_f32 v[106:107], v[122:123], v[90:91], v[106:107] op_sel_hi:[1,0,1]
	v_pk_fma_f32 v[108:109], v[124:125], v[90:91], v[108:109] op_sel_hi:[1,0,1]
	v_pk_fma_f32 v[110:111], v[126:127], v[90:91], v[110:111] op_sel_hi:[1,0,1]
	v_cvt_pk_f32_fp8_e32 v[128:129], v44
	v_cvt_pk_f32_fp8_sdwa v[130:131], v44 src0_sel:WORD_1
	v_cvt_pk_f32_fp8_e32 v[132:133], v45
	v_cvt_pk_f32_fp8_sdwa v[134:135], v45 src0_sel:WORD_1
	v_pk_fma_f32 v[96:97], v[128:129], v[90:91], v[96:97] op_sel:[0,1,0]
	v_pk_fma_f32 v[98:99], v[130:131], v[90:91], v[98:99] op_sel:[0,1,0]
	v_pk_fma_f32 v[100:101], v[132:133], v[90:91], v[100:101] op_sel:[0,1,0]
	v_pk_fma_f32 v[102:103], v[134:135], v[90:91], v[102:103] op_sel:[0,1,0]
	v_cvt_pk_f32_fp8_e32 v[128:129], v46
	v_cvt_pk_f32_fp8_sdwa v[130:131], v46 src0_sel:WORD_1
	v_cvt_pk_f32_fp8_e32 v[132:133], v47
	v_cvt_pk_f32_fp8_sdwa v[134:135], v47 src0_sel:WORD_1
	v_pk_fma_f32 v[104:105], v[128:129], v[90:91], v[104:105] op_sel:[0,1,0]
	v_pk_fma_f32 v[106:107], v[130:131], v[90:91], v[106:107] op_sel:[0,1,0]
	v_pk_fma_f32 v[108:109], v[132:133], v[90:91], v[108:109] op_sel:[0,1,0]
	v_pk_fma_f32 v[110:111], v[134:135], v[90:91], v[110:111] op_sel:[0,1,0]
	v_add_u32_e32 v40, v74, v160
	v_add_u32_e32 v44, v75, v160
	global_load_dwordx4 v[40:43], v40, s[42:43]
	global_load_dwordx4 v[44:47], v44, s[42:43]
	s_waitcnt vmcnt(16)
	v_cvt_pk_f32_fp8_e32 v[120:121], v48
	v_cvt_pk_f32_fp8_sdwa v[122:123], v48 src0_sel:WORD_1
	v_cvt_pk_f32_fp8_e32 v[124:125], v49
	v_cvt_pk_f32_fp8_sdwa v[126:127], v49 src0_sel:WORD_1
	v_pk_fma_f32 v[96:97], v[120:121], v[92:93], v[96:97] op_sel_hi:[1,0,1]
	v_pk_fma_f32 v[98:99], v[122:123], v[92:93], v[98:99] op_sel_hi:[1,0,1]
	v_pk_fma_f32 v[100:101], v[124:125], v[92:93], v[100:101] op_sel_hi:[1,0,1]
	v_pk_fma_f32 v[102:103], v[126:127], v[92:93], v[102:103] op_sel_hi:[1,0,1]
	v_cvt_pk_f32_fp8_e32 v[120:121], v50
	v_cvt_pk_f32_fp8_sdwa v[122:123], v50 src0_sel:WORD_1
	v_cvt_pk_f32_fp8_e32 v[124:125], v51
	v_cvt_pk_f32_fp8_sdwa v[126:127], v51 src0_sel:WORD_1
	v_pk_fma_f32 v[104:105], v[120:121], v[92:93], v[104:105] op_sel_hi:[1,0,1]
	v_pk_fma_f32 v[106:107], v[122:123], v[92:93], v[106:107] op_sel_hi:[1,0,1]
	v_pk_fma_f32 v[108:109], v[124:125], v[92:93], v[108:109] op_sel_hi:[1,0,1]
	v_pk_fma_f32 v[110:111], v[126:127], v[92:93], v[110:111] op_sel_hi:[1,0,1]
	v_cvt_pk_f32_fp8_e32 v[128:129], v52
	v_cvt_pk_f32_fp8_sdwa v[130:131], v52 src0_sel:WORD_1
	v_cvt_pk_f32_fp8_e32 v[132:133], v53
	v_cvt_pk_f32_fp8_sdwa v[134:135], v53 src0_sel:WORD_1
	v_pk_fma_f32 v[96:97], v[128:129], v[92:93], v[96:97] op_sel:[0,1,0]
	v_pk_fma_f32 v[98:99], v[130:131], v[92:93], v[98:99] op_sel:[0,1,0]
	v_pk_fma_f32 v[100:101], v[132:133], v[92:93], v[100:101] op_sel:[0,1,0]
	v_pk_fma_f32 v[102:103], v[134:135], v[92:93], v[102:103] op_sel:[0,1,0]
	v_cvt_pk_f32_fp8_e32 v[128:129], v54
	v_cvt_pk_f32_fp8_sdwa v[130:131], v54 src0_sel:WORD_1
	v_cvt_pk_f32_fp8_e32 v[132:133], v55
	v_cvt_pk_f32_fp8_sdwa v[134:135], v55 src0_sel:WORD_1
	v_pk_fma_f32 v[104:105], v[128:129], v[92:93], v[104:105] op_sel:[0,1,0]
	v_pk_fma_f32 v[106:107], v[130:131], v[92:93], v[106:107] op_sel:[0,1,0]
	v_pk_fma_f32 v[108:109], v[132:133], v[92:93], v[108:109] op_sel:[0,1,0]
	v_pk_fma_f32 v[110:111], v[134:135], v[92:93], v[110:111] op_sel:[0,1,0]
	v_add_u32_e32 v48, v76, v160
	v_add_u32_e32 v52, v77, v160
	global_load_dwordx4 v[48:51], v48, s[42:43]
	global_load_dwordx4 v[52:55], v52, s[42:43]
	s_waitcnt vmcnt(16)
; DI int TID() { int t = threadIdx.x; asm volatile("" : "+v"(t)); return t; }
; DI void phase_peer(const Params& p, int l, int bid, int nblk) {
;     ...
;     PEER_LOAD(0, 0, VB)
; #pragma unroll 1
;     for (int k = 0; k < 16; k += 2) {
;       PEER_LOAD(1, k + 1, VB)
;       __builtin_amdgcn_sched_barrier(0);
;       PEER_ACC(0, k)
;       { const int kn = (k + 2 < 16) ? k + 2 : 15; PEER_LOAD(0, kn, VB) }
;       __builtin_amdgcn_sched_barrier(0);
;       PEER_ACC(1, k + 1)
;     }
;     ...
;       if (prep_ + 1 < PEER_REPS) { _Pragma("unroll") for (int i = 0; i < 16; ++i) asm volatile("" :: "v"(acc[i])); }
;     }
;     int row2 = row;
;     asm volatile("" : "+v"(row2));
;     const int lane2 = TID() & 63;
;     const int b2 = row2 / TPB, pos2 = row2 % TPB;
;     const float* xr = xrow_ptr(p, false, b2, pos2);
;     float* xw = xrow_wptr(p, b2, pos2);
;     const float* ga = WSP(const float, OFF_MOD) + (size_t)(l * 17 + (pos2 < CTXL ? 16 : b2)) * 6144 + 5120;
;     float xn[16];
;     float ss = 0.f;
; #pragma unroll
;     for (int q = 0; q < 4; ++q) {
;       const float4 xv = *(const float4*)(xr + lane2 * 16 + q * 4);
;       const float4 gv = *(const float4*)(ga + lane2 * 16 + q * 4);
;       xn[q * 4 + 0] = xv.x + gv.x * acc[q * 4 + 0];
;       xn[q * 4 + 1] = xv.y + gv.y * acc[q * 4 + 1];
;       xn[q * 4 + 2] = xv.z + gv.z * acc[q * 4 + 2];
;       xn[q * 4 + 3] = xv.w + gv.w * acc[q * 4 + 3];
	v_cvt_pk_f32_fp8_e32 v[120:121], v56
	v_cvt_pk_f32_fp8_sdwa v[122:123], v56 src0_sel:WORD_1
	v_cvt_pk_f32_fp8_e32 v[124:125], v57
	v_cvt_pk_f32_fp8_sdwa v[126:127], v57 src0_sel:WORD_1
	v_pk_fma_f32 v[96:97], v[120:121], v[94:95], v[96:97] op_sel_hi:[1,0,1]
	v_pk_fma_f32 v[98:99], v[122:123], v[94:95], v[98:99] op_sel_hi:[1,0,1]
	v_pk_fma_f32 v[100:101], v[124:125], v[94:95], v[100:101] op_sel_hi:[1,0,1]
	v_pk_fma_f32 v[102:103], v[126:127], v[94:95], v[102:103] op_sel_hi:[1,0,1]
	v_cvt_pk_f32_fp8_e32 v[120:121], v58
	v_cvt_pk_f32_fp8_sdwa v[122:123], v58 src0_sel:WORD_1
	v_cvt_pk_f32_fp8_e32 v[124:125], v59
	v_cvt_pk_f32_fp8_sdwa v[126:127], v59 src0_sel:WORD_1
	v_pk_fma_f32 v[104:105], v[120:121], v[94:95], v[104:105] op_sel_hi:[1,0,1]
	v_pk_fma_f32 v[106:107], v[122:123], v[94:95], v[106:107] op_sel_hi:[1,0,1]
	v_pk_fma_f32 v[108:109], v[124:125], v[94:95], v[108:109] op_sel_hi:[1,0,1]
	v_pk_fma_f32 v[110:111], v[126:127], v[94:95], v[110:111] op_sel_hi:[1,0,1]
	v_cvt_pk_f32_fp8_e32 v[128:129], v60
	v_cvt_pk_f32_fp8_sdwa v[130:131], v60 src0_sel:WORD_1
	v_cvt_pk_f32_fp8_e32 v[132:133], v61
	v_cvt_pk_f32_fp8_sdwa v[134:135], v61 src0_sel:WORD_1
	v_pk_fma_f32 v[96:97], v[128:129], v[94:95], v[96:97] op_sel:[0,1,0]
	v_pk_fma_f32 v[98:99], v[130:131], v[94:95], v[98:99] op_sel:[0,1,0]
	v_pk_fma_f32 v[100:101], v[132:133], v[94:95], v[100:101] op_sel:[0,1,0]
	v_pk_fma_f32 v[102:103], v[134:135], v[94:95], v[102:103] op_sel:[0,1,0]
	v_cvt_pk_f32_fp8_e32 v[128:129], v62
	v_cvt_pk_f32_fp8_sdwa v[130:131], v62 src0_sel:WORD_1
	v_cvt_pk_f32_fp8_e32 v[132:133], v63
	v_cvt_pk_f32_fp8_sdwa v[134:135], v63 src0_sel:WORD_1
	v_pk_fma_f32 v[104:105], v[128:129], v[94:95], v[104:105] op_sel:[0,1,0]
	v_pk_fma_f32 v[106:107], v[130:131], v[94:95], v[106:107] op_sel:[0,1,0]
	v_pk_fma_f32 v[108:109], v[132:133], v[94:95], v[108:109] op_sel:[0,1,0]
	v_pk_fma_f32 v[110:111], v[134:135], v[94:95], v[110:111] op_sel:[0,1,0]
	v_add_u32_e32 v56, v78, v160
	v_add_u32_e32 v60, v79, v160
	global_load_dwordx4 v[56:59], v56, s[42:43]
	global_load_dwordx4 v[60:63], v60, s[42:43]
	s_nop 1
	v_permlane32_swap_b32 v96, v104
	v_permlane32_swap_b32 v97, v105
	v_permlane32_swap_b32 v98, v106
	v_permlane32_swap_b32 v99, v107
	v_permlane32_swap_b32 v100, v108
	v_permlane32_swap_b32 v101, v109
	v_permlane32_swap_b32 v102, v110
	v_permlane32_swap_b32 v103, v111
	v_pk_add_f32 v[96:97], v[96:97], v[104:105]
	v_pk_add_f32 v[98:99], v[98:99], v[106:107]
	v_pk_add_f32 v[100:101], v[100:101], v[108:109]
	v_pk_add_f32 v[102:103], v[102:103], v[110:111]
	s_nop 0
	v_permlane16_swap_b32 v96, v100
	v_permlane16_swap_b32 v97, v101
	v_permlane16_swap_b32 v98, v102
	v_permlane16_swap_b32 v99, v103
	v_pk_add_f32 v[96:97], v[96:97], v[100:101]
	v_pk_add_f32 v[98:99], v[98:99], v[102:103]
	v_cndmask_b32_e64 v120, v96, v98, s[40:41]
	v_cndmask_b32_e64 v121, v97, v99, s[40:41]
	v_cndmask_b32_e64 v122, v98, v96, s[40:41]
	v_cndmask_b32_e64 v123, v99, v97, s[40:41]
	s_nop 1
	v_add_f32_dpp v124, v122, v120 row_ror:8 row_mask:0xf bank_mask:0xf
	v_add_f32_dpp v125, v123, v121 row_ror:8 row_mask:0xf bank_mask:0xf
	s_waitcnt vmcnt(16)
	v_pk_fma_f32 v[140:141], v[142:143], v[124:125], v[140:141]
	s_nop 0
	global_store_dwordx2 v166, v[140:141], s[80:81] sc1
	s_mov_b32 s46, s62
	s_mov_b32 s47, s63
	s_mov_b32 s48, s64
	s_mov_b32 s50, s65
	s_add_i32 s49, s49, -1
	s_cmp_lg_u32 s49, 0
	s_cbranch_scc1 .Lpeer_v_top
	s_waitcnt vmcnt(0) lgkmcnt(0)
	s_cmp_lg_u64 s[70:71], 0
	s_cbranch_scc1 .Lpeer_n1_done
	v_lshlrev_b32_e32 v144, 4, v161
	v_lshlrev_b32_e32 v149, 3, v161
	v_readlane_b32 s84, v253, 15
	v_readlane_b32 s85, v253, 16
	s_add_u32 s84, s84, 0x1000
	s_addc_u32 s85, s85, 0
	global_load_dwordx4 v[16:19], v144, s[84:85]
	global_load_dwordx4 v[20:23], v144, s[84:85] offset:1024
	global_load_dwordx4 v[24:27], v144, s[84:85] offset:2048
	global_load_dwordx4 v[28:31], v144, s[84:85] offset:3072
	v_xor_b32_e32 v145, 16, v161
	v_xor_b32_e32 v146, 32, v161
	v_lshlrev_b32_e32 v145, 2, v145
	v_lshlrev_b32_e32 v146, 2, v146
	s_mov_b32 s47, 0

; DI u32 pack2(float a, float b) { return (u32)f2bf(a) | ((u32)f2bf(b) << 16); }
; DI void phase_norm(const Params& p, int l, int which, int bid, int nblk) {
;     ...
;     float ss = 0.f;
; #pragma unroll
;     for (int i = 0; i < 16; ++i) ss += x[i] * x[i];
;     ss = wave_sum(ss);
;     const float rs = rsqrtf(ss * (1.f / 1024.f) + EPSF);
; #pragma unroll
;     for (int hh = 0; hh < 2; ++hh) {
;       const int c0 = hh * 512 + lane * 8;
;       float y[8];
; #pragma unroll
;       for (int i = 0; i < 8; ++i) {
;         const float yn = x[hh * 8 + i] * rs * g[c0 + i];
;         y[i] = yn * (1.f + mod[1024 + c0 + i]) + mod[c0 + i];
;       }
;       uint4 o = {pack2(y[0], y[1]), pack2(y[2], y[3]), pack2(y[4], y[5]), pack2(y[6], y[7])};
;       *(uint4*)&WSP(u16, OFF_ACT)[(size_t)row * 1024 + c0] = o;
;     }
.Lpeer_n1_ptr:
	s_mul_i32 s13, s13, 0x6000
	s_add_u32 s82, s96, 0x1be04000
	s_addc_u32 s83, s97, 0
	s_add_u32 s82, s82, s13
	s_addc_u32 s83, s83, 0
	s_add_u32 s78, s82, 0x1000
	s_addc_u32 s79, s83, 0
	s_lshl_b32 s17, s48, 11
	s_add_u32 s84, s6, s17
	s_addc_u32 s85, s7, 0
	global_load_dwordx4 v[32:35], v144, s[80:81] sc1
	global_load_dwordx4 v[36:39], v144, s[80:81] offset:1024 sc1
	global_load_dwordx4 v[40:43], v144, s[80:81] offset:2048 sc1
	global_load_dwordx4 v[44:47], v144, s[80:81] offset:3072 sc1
	global_load_dwordx4 v[48:51], v144, s[82:83]
	global_load_dwordx4 v[52:55], v144, s[82:83] offset:1024
	global_load_dwordx4 v[56:59], v144, s[82:83] offset:2048
	global_load_dwordx4 v[60:63], v144, s[82:83] offset:3072
	global_load_dwordx4 v[64:67], v144, s[78:79]
	global_load_dwordx4 v[68:71], v144, s[78:79] offset:1024
	global_load_dwordx4 v[72:75], v144, s[78:79] offset:2048
	global_load_dwordx4 v[76:79], v144, s[78:79] offset:3072
	s_waitcnt vmcnt(8)
	v_mul_f32_e32 v147, v32, v32
	v_fmac_f32_e32 v147, v33, v33
	v_fmac_f32_e32 v147, v34, v34
	v_fmac_f32_e32 v147, v35, v35
	v_fmac_f32_e32 v147, v36, v36
	v_fmac_f32_e32 v147, v37, v37
	v_fmac_f32_e32 v147, v38, v38
	v_fmac_f32_e32 v147, v39, v39
	v_fmac_f32_e32 v147, v40, v40
	v_fmac_f32_e32 v147, v41, v41
	v_fmac_f32_e32 v147, v42, v42
	v_fmac_f32_e32 v147, v43, v43
	v_fmac_f32_e32 v147, v44, v44
	v_fmac_f32_e32 v147, v45, v45
	v_fmac_f32_e32 v147, v46, v46
	v_fmac_f32_e32 v147, v47, v47
	s_nop 1
	v_add_f32_dpp v147, v147, v147 quad_perm:[1,0,3,2] row_mask:0xf bank_mask:0xf
	s_nop 1
	v_add_f32_dpp v147, v147, v147 quad_perm:[2,3,0,1] row_mask:0xf bank_mask:0xf
	s_nop 1
	v_add_f32_dpp v147, v147, v147 row_half_mirror row_mask:0xf bank_mask:0xf
	s_nop 1
	v_add_f32_dpp v147, v147, v147 row_mirror row_mask:0xf bank_mask:0xf
	s_nop 1
	ds_bpermute_b32 v148, v145, v147
	s_waitcnt lgkmcnt(0)
	v_add_f32_e32 v147, v147, v148
	ds_bpermute_b32 v148, v146, v147
	s_waitcnt lgkmcnt(0)
	v_add_f32_e32 v147, v147, v148
	v_mov_b32_e32 v148, 0x358637bd
	v_fmac_f32_e32 v148, 0x3a800000, v147
	v_rsq_f32_e32 v148, v148
	s_waitcnt vmcnt(0)
	v_mul_f32_e32 v32, v32, v148
	v_mul_f32_e32 v33, v33, v148
	v_mul_f32_e32 v34, v34, v148
	v_mul_f32_e32 v35, v35, v148
	v_mul_f32_e32 v36, v36, v148
	v_mul_f32_e32 v37, v37, v148
	v_mul_f32_e32 v38, v38, v148
	v_mul_f32_e32 v39, v39, v148
	v_mul_f32_e32 v40, v40, v148
	v_mul_f32_e32 v41, v41, v148
	v_mul_f32_e32 v42, v42, v148
	v_mul_f32_e32 v43, v43, v148
	v_mul_f32_e32 v44, v44, v148
	v_mul_f32_e32 v45, v45, v148
	v_mul_f32_e32 v46, v46, v148
	v_mul_f32_e32 v47, v47, v148
	v_mul_f32_e32 v32, v32, v16
	v_mul_f32_e32 v33, v33, v17
	v_mul_f32_e32 v34, v34, v18
	v_mul_f32_e32 v35, v35, v19
	v_mul_f32_e32 v36, v36, v20
	v_mul_f32_e32 v37, v37, v21
	v_mul_f32_e32 v38, v38, v22
	v_mul_f32_e32 v39, v39, v23
	v_mul_f32_e32 v40, v40, v24
	v_mul_f32_e32 v41, v41, v25
	v_mul_f32_e32 v42, v42, v26
	v_mul_f32_e32 v43, v43, v27
	v_mul_f32_e32 v44, v44, v28
	v_mul_f32_e32 v45, v45, v29
	v_mul_f32_e32 v46, v46, v30
	v_mul_f32_e32 v47, v47, v31
	v_add_f32_e32 v64, 1.0, v64
	v_add_f32_e32 v65, 1.0, v65
	v_add_f32_e32 v66, 1.0, v66
	v_add_f32_e32 v67, 1.0, v67
	v_add_f32_e32 v68, 1.0, v68
	v_add_f32_e32 v69, 1.0, v69
	v_add_f32_e32 v70, 1.0, v70
	v_add_f32_e32 v71, 1.0, v71
	v_add_f32_e32 v72, 1.0, v72
	v_add_f32_e32 v73, 1.0, v73
	v_add_f32_e32 v74, 1.0, v74
	v_add_f32_e32 v75, 1.0, v75
	v_add_f32_e32 v76, 1.0, v76
	v_add_f32_e32 v77, 1.0, v77
	v_add_f32_e32 v78, 1.0, v78
	v_add_f32_e32 v79, 1.0, v79
	v_fma_f32 v32, v32, v64, v48
	v_fma_f32 v33, v33, v65, v49
	v_fma_f32 v34, v34, v66, v50
	v_fma_f32 v35, v35, v67, v51
	v_fma_f32 v36, v36, v68, v52
	v_fma_f32 v37, v37, v69, v53
	v_fma_f32 v38, v38, v70, v54
	v_fma_f32 v39, v39, v71, v55
	v_fma_f32 v40, v40, v72, v56
	v_fma_f32 v41, v41, v73, v57
	v_fma_f32 v42, v42, v74, v58
	v_fma_f32 v43, v43, v75, v59
	v_fma_f32 v44, v44, v76, v60
	v_fma_f32 v45, v45, v77, v61
	v_fma_f32 v46, v46, v78, v62
	v_fma_f32 v47, v47, v79, v63
	v_cvt_pk_bf16_f32 v32, v32, v33
	v_cvt_pk_bf16_f32 v33, v34, v35
	v_cvt_pk_bf16_f32 v34, v36, v37
	v_cvt_pk_bf16_f32 v35, v38, v39
	v_cvt_pk_bf16_f32 v36, v40, v41
	v_cvt_pk_bf16_f32 v37, v42, v43
	v_cvt_pk_bf16_f32 v38, v44, v45
	v_cvt_pk_bf16_f32 v39, v46, v47
	s_nop 0
	global_store_dwordx2 v149, v[32:33], s[84:85] sc1
	global_store_dwordx2 v149, v[34:35], s[84:85] offset:512 sc1
	global_store_dwordx2 v149, v[36:37], s[84:85] offset:1024 sc1
	global_store_dwordx2 v149, v[38:39], s[84:85] offset:1536 sc1
	s_add_i32 s47, s47, 1
	s_cmp_lt_u32 s47, s75
	s_cbranch_scc1 .Lpeer_n1_top

; DI void phase_peer(const Params& p, int l, int bid, int nblk) {
;     ...
;     if (l == 1) {
; #pragma unroll
;       for (int i = 0; i < 16; ++i) ss += xn[i] * xn[i];
;       ss = wave_sum(ss);
;       const float rs = rsqrtf(ss * (1.f / 1024.f) + EPSF);
; #pragma unroll
;       for (int i = 0; i < 16; ++i) xn[i] = xn[i] * rs * gfin[lane2 * 16 + i];
;     }
; #pragma unroll
;     for (int q = 0; q < 4; ++q) {
;       float4 o = {xn[q * 4 + 0], xn[q * 4 + 1], xn[q * 4 + 2], xn[q * 4 + 3]};
;       *(float4*)(xw + lane2 * 16 + q * 4) = o;
;     }
.Lpeer_e_top:
	s_cmp_ge_u32 s47, s55
	s_addc_u32 s48, s47, 0
	s_cmp_ge_u32 s48, s66
	s_addc_u32 s48, s48, 0
	s_lshl_b32 s48, s48, 11
	s_add_i32 s48, s48, s67
	s_mul_hi_u32 s84, s48, 0x38e38e39
	s_lshr_b32 s84, s84, 9
	s_mul_i32 s85, s84, 0x900
	s_sub_u32 s85, s48, s85
	s_lshl_b32 s86, s84, 11
	s_add_i32 s86, s86, s85
	s_add_i32 s86, s86, 0xffffff00
	s_lshl_b32 s86, s86, 12
	s_add_u32 s80, s94, s86
	s_addc_u32 s81, s95, 0
	global_load_dwordx4 v[32:35], v144, s[80:81] sc1
	global_load_dwordx4 v[36:39], v144, s[80:81] offset:1024 sc1
	global_load_dwordx4 v[40:43], v144, s[80:81] offset:2048 sc1
	global_load_dwordx4 v[44:47], v144, s[80:81] offset:3072 sc1
	s_waitcnt vmcnt(0)
	v_mul_f32_e32 v147, v32, v32
	v_fmac_f32_e32 v147, v33, v33
	v_fmac_f32_e32 v147, v34, v34
	v_fmac_f32_e32 v147, v35, v35
	v_fmac_f32_e32 v147, v36, v36
	v_fmac_f32_e32 v147, v37, v37
	v_fmac_f32_e32 v147, v38, v38
	v_fmac_f32_e32 v147, v39, v39
	v_fmac_f32_e32 v147, v40, v40
	v_fmac_f32_e32 v147, v41, v41
	v_fmac_f32_e32 v147, v42, v42
	v_fmac_f32_e32 v147, v43, v43
	v_fmac_f32_e32 v147, v44, v44
	v_fmac_f32_e32 v147, v45, v45
	v_fmac_f32_e32 v147, v46, v46
	v_fmac_f32_e32 v147, v47, v47
	s_nop 1
	v_add_f32_dpp v147, v147, v147 quad_perm:[1,0,3,2] row_mask:0xf bank_mask:0xf
	s_nop 1
	v_add_f32_dpp v147, v147, v147 quad_perm:[2,3,0,1] row_mask:0xf bank_mask:0xf
	s_nop 1
	v_add_f32_dpp v147, v147, v147 row_half_mirror row_mask:0xf bank_mask:0xf
	s_nop 1
	v_add_f32_dpp v147, v147, v147 row_mirror row_mask:0xf bank_mask:0xf
	s_nop 1
	ds_bpermute_b32 v148, v145, v147
	s_waitcnt lgkmcnt(0)
	v_add_f32_e32 v147, v147, v148
	ds_bpermute_b32 v148, v146, v147
	s_waitcnt lgkmcnt(0)
	v_add_f32_e32 v147, v147, v148
	v_mov_b32_e32 v148, 0x358637bd
	v_fmac_f32_e32 v148, 0x3a800000, v147
	v_rsq_f32_e32 v148, v148
	s_nop 0
	v_mul_f32_e32 v32, v32, v148
	v_mul_f32_e32 v33, v33, v148
	v_mul_f32_e32 v34, v34, v148
	v_mul_f32_e32 v35, v35, v148
	v_mul_f32_e32 v36, v36, v148
	v_mul_f32_e32 v37, v37, v148
	v_mul_f32_e32 v38, v38, v148
	v_mul_f32_e32 v39, v39, v148
	v_mul_f32_e32 v40, v40, v148
	v_mul_f32_e32 v41, v41, v148
	v_mul_f32_e32 v42, v42, v148
	v_mul_f32_e32 v43, v43, v148
	v_mul_f32_e32 v44, v44, v148
	v_mul_f32_e32 v45, v45, v148
	v_mul_f32_e32 v46, v46, v148
	v_mul_f32_e32 v47, v47, v148
	v_mul_f32_e32 v32, v32, v16
	v_mul_f32_e32 v33, v33, v17
	v_mul_f32_e32 v34, v34, v18
	v_mul_f32_e32 v35, v35, v19
	v_mul_f32_e32 v36, v36, v20
	v_mul_f32_e32 v37, v37, v21
	v_mul_f32_e32 v38, v38, v22
	v_mul_f32_e32 v39, v39, v23
	v_mul_f32_e32 v40, v40, v24
	v_mul_f32_e32 v41, v41, v25
	v_mul_f32_e32 v42, v42, v26
	v_mul_f32_e32 v43, v43, v27
	v_mul_f32_e32 v44, v44, v28
	v_mul_f32_e32 v45, v45, v29
	v_mul_f32_e32 v46, v46, v30
	v_mul_f32_e32 v47, v47, v31
	global_store_dwordx4 v144, v[32:35], s[80:81] sc1
	global_store_dwordx4 v144, v[36:39], s[80:81] offset:1024 sc1
	global_store_dwordx4 v144, v[40:43], s[80:81] offset:2048 sc1
	global_store_dwordx4 v144, v[44:47], s[80:81] offset:3072 sc1
	s_add_i32 s47, s47, 1
	s_cmp_lt_u32 s47, s75
	s_cbranch_scc1 .Lpeer_e_top
